# P1c column-scale prefetch before K-loop (no vmcnt(0) left in P1c epilogue) + loop-control SALU moved into MFMA shadow of phase 8 in all six K-loops
# speedup vs baseline: 1.0190x; 1.0097x over previous
; #define G_STAGE(bufoff, gbase, voff) do { _Pragma("unroll") for (int _i = 0; _i < 2; ++_i) \
;         __builtin_amdgcn_global_load_lds((const unsigned*)((const char*)(gbase) + (voff)[_i]), (LAS unsigned*)(lds + (bufoff) + ldsw + _i * 8192), 16, 0, 0); } while (0)
; #define G_WAIT_L(n) asm volatile("s_waitcnt lgkmcnt(" #n ")" ::: "memory")
; #define G_BAR __builtin_amdgcn_s_barrier()
; #define G_SCHED __builtin_amdgcn_sched_barrier(0)
; template <int MODE  , class Epi, class Sched>
; __device__ __forceinline__ void gemm_phase(LAS unsigned char* lds, const GemmDesc g, const Sched& S, const Epi& E) {
;     ...
;             G_LDB(B0, 0, 0); G_SCHED; G_LDA(At, 0, 0); G_STAGE(G_SA(1, 1), a1 + hstepA, voffA);
;             G_WAIT_L(8); G_BAR; G_WAIT_L(0); G_MMA(0, 0, At, B0); G_BAR; G_SCHED;
;             G_LDB(B1, 0, 1); G_STAGE(G_SB(0, 0), b2, voffB);
;             G_BAR; G_WAIT_L(0); G_MMA(0, 1, At, B1); G_BAR;
;     __device__ __forceinline__ bool operator()(f32x4 (&acc)[2][2][4][2], const Unit& u, int wr, int wc, int fr, int fq) const {
;     ...
;         const float* cq = csv + (pn - 4) * 256 + cl;
;         const f32x4 c00 = *(const f32x4*)(cq), c01 = *(const f32x4*)(cq + 4), c10 = *(const f32x4*)(cq + HALF), c11 = *(const f32x4*)(cq + HALF + 4);
.LBB0_526:
	s_add_u32 s72, s40, 0x100
	v_mov_b32_e32 v10, 0
	s_addc_u32 s76, s41, 0
	s_mov_b32 s77, -2
	v_lshl_add_u32 v198, s73, 8, v1
	v_ashrrev_i32_e32 v199, 31, v198
	v_lshl_add_u64 v[198:199], v[198:199], 2, s[4:5]
	global_load_dword v248, v[198:199], off
	global_load_dword v249, v[198:199], off offset:64
	global_load_dword v250, v[198:199], off offset:128
	global_load_dword v251, v[198:199], off offset:192
	global_load_dword v252, v[198:199], off offset:512
	global_load_dword v253, v[198:199], off offset:576
	global_load_dword v254, v[198:199], off offset:640
	global_load_dword v255, v[198:199], off offset:704
	s_lshl_b32 s0, s75, 8
	s_add_i32 s10, s0, 0xfffffc00
	s_ashr_i32 s11, s10, 31
	v_lshl_add_u64 v[198:199], s[10:11], 2, v[156:157]
	global_load_dwordx4 v[218:221], v[198:199], off
	global_load_dwordx4 v[222:225], v[198:199], off offset:16
	global_load_dwordx4 v[226:229], v[198:199], off offset:512
	global_load_dwordx4 v[158:161], v[198:199], off offset:528
	v_mov_b32_e32 v11, v10
	v_mov_b64_e32 v[12:13], v[10:11]
	v_mov_b64_e32 v[14:15], v[10:11]
	v_mov_b64_e32 v[16:17], v[10:11]
	v_mov_b64_e32 v[26:27], v[10:11]
	v_mov_b64_e32 v[28:29], v[10:11]
	v_mov_b64_e32 v[30:31], v[10:11]
	v_mov_b64_e32 v[32:33], v[10:11]
	v_mov_b64_e32 v[58:59], v[10:11]
	v_mov_b64_e32 v[60:61], v[10:11]
	v_mov_b64_e32 v[62:63], v[10:11]
	v_mov_b64_e32 v[64:65], v[10:11]
	v_mov_b64_e32 v[74:75], v[10:11]
	v_mov_b64_e32 v[76:77], v[10:11]
	v_mov_b64_e32 v[78:79], v[10:11]
	v_mov_b64_e32 v[80:81], v[10:11]
	v_mov_b64_e32 v[2:3], v[10:11]
	v_mov_b64_e32 v[4:5], v[10:11]
	v_mov_b64_e32 v[6:7], v[10:11]
	v_mov_b64_e32 v[8:9], v[10:11]
	v_mov_b64_e32 v[18:19], v[10:11]
	v_mov_b64_e32 v[20:21], v[10:11]
	v_mov_b64_e32 v[22:23], v[10:11]
	v_mov_b64_e32 v[24:25], v[10:11]
	v_mov_b64_e32 v[50:51], v[10:11]
	v_mov_b64_e32 v[52:53], v[10:11]
	v_mov_b64_e32 v[54:55], v[10:11]
	v_mov_b64_e32 v[56:57], v[10:11]
	v_mov_b64_e32 v[66:67], v[10:11]
	v_mov_b64_e32 v[68:69], v[10:11]
	v_mov_b64_e32 v[70:71], v[10:11]
	v_mov_b64_e32 v[72:73], v[10:11]
	v_mov_b64_e32 v[90:91], v[10:11]
	v_mov_b64_e32 v[92:93], v[10:11]
	v_mov_b64_e32 v[94:95], v[10:11]
	v_mov_b64_e32 v[96:97], v[10:11]
	v_mov_b64_e32 v[106:107], v[10:11]
	v_mov_b64_e32 v[108:109], v[10:11]
	v_mov_b64_e32 v[110:111], v[10:11]
	v_mov_b64_e32 v[112:113], v[10:11]
	v_mov_b64_e32 v[122:123], v[10:11]
	v_mov_b64_e32 v[124:125], v[10:11]
	v_mov_b64_e32 v[126:127], v[10:11]
	v_mov_b64_e32 v[128:129], v[10:11]
	v_mov_b64_e32 v[138:139], v[10:11]
	v_mov_b64_e32 v[140:141], v[10:11]
	v_mov_b64_e32 v[142:143], v[10:11]
	v_mov_b64_e32 v[144:145], v[10:11]
	v_mov_b64_e32 v[82:83], v[10:11]
	v_mov_b64_e32 v[84:85], v[10:11]
	v_mov_b64_e32 v[86:87], v[10:11]
	v_mov_b64_e32 v[88:89], v[10:11]
	v_mov_b64_e32 v[98:99], v[10:11]
	v_mov_b64_e32 v[100:101], v[10:11]
	v_mov_b64_e32 v[102:103], v[10:11]
	v_mov_b64_e32 v[104:105], v[10:11]
	v_mov_b64_e32 v[114:115], v[10:11]
	v_mov_b64_e32 v[116:117], v[10:11]
	v_mov_b64_e32 v[118:119], v[10:11]
	v_mov_b64_e32 v[120:121], v[10:11]
	v_mov_b64_e32 v[130:131], v[10:11]
	v_mov_b64_e32 v[132:133], v[10:11]
	v_mov_b64_e32 v[134:135], v[10:11]
	v_mov_b64_e32 v[136:137], v[10:11]
	s_cmp_eq_u32 s101, 1
	s_cbranch_scc0 .Lnodb_p1c
	s_barrier
	s_mov_b32 s101, 0
.Lnodb_p1c:
.LBB0_527:
	s_add_u32 s40, s34, 0x100
	s_addc_u32 s41, s35, 0
	s_cmp_eq_u32 s77, 12
	s_cselect_b32 s47, s21, s41
	s_cselect_b32 s46, s20, s40
	s_cselect_b32 s45, s3, s76
	s_cselect_b32 s44, s2, s72
	s_mov_b32 m0, s64
	s_add_u32 s98, s34, 0x44080
	s_addc_u32 s99, s35, 0
	ds_read_b128 v[162:165], v194
	ds_read_b128 v[166:169], v194 offset:1024
	ds_read_b128 v[170:173], v194 offset:2048
	ds_read_b128 v[174:177], v194 offset:3072
	ds_read_b128 v[178:181], v194 offset:4096
	ds_read_b128 v[182:185], v194 offset:5120
	ds_read_b128 v[186:189], v194 offset:6144
	ds_read_b128 v[198:201], v194 offset:7168
	global_load_lds_dwordx4 v146, s[98:99]
	s_mov_b32 m0, s65
	s_nop 0
	global_load_lds_dwordx4 v150, s[98:99]
	s_waitcnt lgkmcnt(8)
	s_barrier
	s_waitcnt lgkmcnt(0)
	s_setprio 1
	s_waitcnt lgkmcnt(0)
	v_mfma_i32_16x16x64_i8 v[134:137], v[232:235], v[162:165], v[134:137]
	v_mfma_i32_16x16x64_i8 v[130:133], v[240:243], v[162:165], v[130:133]
	v_mfma_i32_16x16x64_i8 v[118:121], v[232:235], v[170:173], v[118:121]
	v_mfma_i32_16x16x64_i8 v[114:117], v[240:243], v[170:173], v[114:117]
	v_mfma_i32_16x16x64_i8 v[102:105], v[232:235], v[178:181], v[102:105]
	v_mfma_i32_16x16x64_i8 v[98:101], v[240:243], v[178:181], v[98:101]
	v_mfma_i32_16x16x64_i8 v[86:89], v[232:235], v[186:189], v[86:89]
	v_mfma_i32_16x16x64_i8 v[82:85], v[240:243], v[186:189], v[82:85]
	v_mfma_i32_16x16x64_i8 v[134:137], v[236:239], v[166:169], v[134:137]
	v_mfma_i32_16x16x64_i8 v[130:133], v[244:247], v[166:169], v[130:133]
	v_mfma_i32_16x16x64_i8 v[118:121], v[236:239], v[174:177], v[118:121]
	v_mfma_i32_16x16x64_i8 v[114:117], v[244:247], v[174:177], v[114:117]
	v_mfma_i32_16x16x64_i8 v[102:105], v[236:239], v[182:185], v[102:105]
	v_mfma_i32_16x16x64_i8 v[98:101], v[244:247], v[182:185], v[98:101]
	v_mfma_i32_16x16x64_i8 v[86:89], v[236:239], v[198:201], v[86:89]
	v_mfma_i32_16x16x64_i8 v[82:85], v[244:247], v[198:201], v[82:85]
	s_setprio 0
	s_barrier
	s_mov_b32 m0, s66
	ds_read_b128 v[202:205], v195
	ds_read_b128 v[206:209], v195 offset:1024
	ds_read_b128 v[210:213], v195 offset:2048
	ds_read_b128 v[214:217], v195 offset:3072
	global_load_lds_dwordx4 v148, s[44:45]
	s_mov_b32 m0, s67
	s_nop 0
	global_load_lds_dwordx4 v152, s[44:45]
	s_barrier
; #define G_STAGE(bufoff, gbase, voff) do { _Pragma("unroll") for (int _i = 0; _i < 2; ++_i) \
;         __builtin_amdgcn_global_load_lds((const unsigned*)((const char*)(gbase) + (voff)[_i]), (LAS unsigned*)(lds + (bufoff) + ldsw + _i * 8192), 16, 0, 0); } while (0)
; #define G_WAIT_V(n) asm volatile("s_waitcnt vmcnt(" #n ")" ::: "memory")
; #define G_WAIT_L(n) asm volatile("s_waitcnt lgkmcnt(" #n ")" ::: "memory")
; #define G_BAR __builtin_amdgcn_s_barrier()
; #define G_SCHED __builtin_amdgcn_sched_barrier(0)
; template <int MODE  , class Epi, class Sched>
; __device__ __forceinline__ void gemm_phase(LAS unsigned char* lds, const GemmDesc g, const Sched& S, const Epi& E) {
;     ...
;             G_BAR; G_WAIT_L(0); G_MMA(0, 1, At, B1); G_BAR;
;             G_LDA(At, 0, 1); G_STAGE(G_SA(0, 0), a2, voffA);
;             G_BAR; G_WAIT_L(0); G_MMA(1, 0, At, B0); G_BAR; G_SCHED;
;             G_STAGE(G_SB(0, 1), b2 + hstepB, voffB);
;             G_WAIT_V(6); G_BAR; G_MMA(1, 1, At, B1); G_BAR;
;             G_LDB(B0, 1, 0); G_SCHED; G_LDA(At, 1, 0); G_STAGE(G_SA(0, 1), a2 + hstepA, voffA);
;             G_WAIT_L(8); G_BAR; G_WAIT_L(0); G_MMA(0, 0, At, B0); G_BAR; G_SCHED;
	s_waitcnt lgkmcnt(0)
	s_setprio 1
	s_waitcnt lgkmcnt(0)
	v_mfma_i32_16x16x64_i8 v[142:145], v[202:205], v[162:165], v[142:145]
	v_mfma_i32_16x16x64_i8 v[138:141], v[210:213], v[162:165], v[138:141]
	v_mfma_i32_16x16x64_i8 v[126:129], v[202:205], v[170:173], v[126:129]
	v_mfma_i32_16x16x64_i8 v[122:125], v[210:213], v[170:173], v[122:125]
	v_mfma_i32_16x16x64_i8 v[110:113], v[202:205], v[178:181], v[110:113]
	v_mfma_i32_16x16x64_i8 v[106:109], v[210:213], v[178:181], v[106:109]
	v_mfma_i32_16x16x64_i8 v[94:97], v[202:205], v[186:189], v[94:97]
	v_mfma_i32_16x16x64_i8 v[90:93], v[210:213], v[186:189], v[90:93]
	v_mfma_i32_16x16x64_i8 v[142:145], v[206:209], v[166:169], v[142:145]
	v_mfma_i32_16x16x64_i8 v[138:141], v[214:217], v[166:169], v[138:141]
	v_mfma_i32_16x16x64_i8 v[126:129], v[206:209], v[174:177], v[126:129]
	v_mfma_i32_16x16x64_i8 v[122:125], v[214:217], v[174:177], v[122:125]
	v_mfma_i32_16x16x64_i8 v[110:113], v[206:209], v[182:185], v[110:113]
	v_mfma_i32_16x16x64_i8 v[106:109], v[214:217], v[182:185], v[106:109]
	v_mfma_i32_16x16x64_i8 v[94:97], v[206:209], v[198:201], v[94:97]
	v_mfma_i32_16x16x64_i8 v[90:93], v[214:217], v[198:201], v[90:93]
	s_setprio 0
	s_mov_b32 m0, s55
	s_barrier
	ds_read_b128 v[162:165], v194 offset:16384
	ds_read_b128 v[166:169], v194 offset:17408
	ds_read_b128 v[170:173], v194 offset:18432
	ds_read_b128 v[174:177], v194 offset:19456
	ds_read_b128 v[178:181], v194 offset:20480
	ds_read_b128 v[182:185], v194 offset:21504
	ds_read_b128 v[186:189], v194 offset:22528
	ds_read_b128 v[198:201], v194 offset:23552
	global_load_lds_dwordx4 v146, s[46:47]
	s_mov_b32 m0, s56
	s_nop 0
	global_load_lds_dwordx4 v150, s[46:47]
	s_barrier
	s_waitcnt lgkmcnt(0)
	s_setprio 1
	s_waitcnt lgkmcnt(0)
	v_mfma_i32_16x16x64_i8 v[70:73], v[232:235], v[162:165], v[70:73]
	v_mfma_i32_16x16x64_i8 v[66:69], v[240:243], v[162:165], v[66:69]
	v_mfma_i32_16x16x64_i8 v[54:57], v[232:235], v[170:173], v[54:57]
	v_mfma_i32_16x16x64_i8 v[50:53], v[240:243], v[170:173], v[50:53]
	v_mfma_i32_16x16x64_i8 v[22:25], v[232:235], v[178:181], v[22:25]
	v_mfma_i32_16x16x64_i8 v[18:21], v[240:243], v[178:181], v[18:21]
	v_mfma_i32_16x16x64_i8 v[6:9], v[232:235], v[186:189], v[6:9]
	v_mfma_i32_16x16x64_i8 v[2:5], v[240:243], v[186:189], v[2:5]
	v_mfma_i32_16x16x64_i8 v[70:73], v[236:239], v[166:169], v[70:73]
	v_mfma_i32_16x16x64_i8 v[66:69], v[244:247], v[166:169], v[66:69]
	v_mfma_i32_16x16x64_i8 v[54:57], v[236:239], v[174:177], v[54:57]
	v_mfma_i32_16x16x64_i8 v[50:53], v[244:247], v[174:177], v[50:53]
	v_mfma_i32_16x16x64_i8 v[22:25], v[236:239], v[182:185], v[22:25]
	v_mfma_i32_16x16x64_i8 v[18:21], v[244:247], v[182:185], v[18:21]
	v_mfma_i32_16x16x64_i8 v[6:9], v[236:239], v[198:201], v[6:9]
	v_mfma_i32_16x16x64_i8 v[2:5], v[244:247], v[198:201], v[2:5]
	s_setprio 0
	s_barrier
	s_mov_b32 m0, s68
	s_add_u32 s0, s44, 0x44000
	s_addc_u32 s1, s45, 0
	global_load_lds_dwordx4 v148, s[0:1]
	s_mov_b32 m0, s69
	s_nop 0
	global_load_lds_dwordx4 v152, s[0:1]
	s_waitcnt vmcnt(6)
	s_barrier
	s_setprio 1
	v_mfma_i32_16x16x64_i8 v[30:33], v[202:205], v[178:181], v[30:33]
	v_mfma_i32_16x16x64_i8 v[26:29], v[210:213], v[178:181], v[26:29]
	v_mfma_i32_16x16x64_i8 v[14:17], v[202:205], v[186:189], v[14:17]
	v_mfma_i32_16x16x64_i8 v[10:13], v[210:213], v[186:189], v[10:13]
	v_mfma_i32_16x16x64_i8 v[34:37], v[202:205], v[162:165], v[78:81]
	v_mfma_i32_16x16x64_i8 v[38:41], v[210:213], v[162:165], v[74:77]
	v_mfma_i32_16x16x64_i8 v[42:45], v[202:205], v[170:173], v[62:65]
	v_mfma_i32_16x16x64_i8 v[46:49], v[210:213], v[170:173], v[58:61]
	v_mfma_i32_16x16x64_i8 v[30:33], v[206:209], v[182:185], v[30:33]
	v_mfma_i32_16x16x64_i8 v[26:29], v[214:217], v[182:185], v[26:29]
	v_mfma_i32_16x16x64_i8 v[14:17], v[206:209], v[198:201], v[14:17]
	v_mfma_i32_16x16x64_i8 v[10:13], v[214:217], v[198:201], v[10:13]
	v_mfma_i32_16x16x64_i8 v[34:37], v[206:209], v[166:169], v[34:37]
	v_mfma_i32_16x16x64_i8 v[38:41], v[214:217], v[166:169], v[38:41]
	v_mfma_i32_16x16x64_i8 v[42:45], v[206:209], v[174:177], v[42:45]
	v_mfma_i32_16x16x64_i8 v[46:49], v[214:217], v[174:177], v[46:49]
	s_setprio 0
	s_add_i32 s10, 0, 0x18000
	v_add_u32_e32 v78, s10, v191
	s_barrier
	ds_read_b128 v[58:61], v78
	ds_read_b128 v[62:65], v78 offset:1024
	ds_read_b128 v[74:77], v78 offset:2048
	ds_read_b128 v[78:81], v78 offset:3072
	s_add_u32 s0, s46, 0x44000
	s_addc_u32 s1, s47, 0
	s_mov_b32 m0, s57
	ds_read_b128 v[162:165], v194 offset:32768
	ds_read_b128 v[166:169], v194 offset:33792
	ds_read_b128 v[170:173], v194 offset:34816
	ds_read_b128 v[174:177], v194 offset:35840
	ds_read_b128 v[178:181], v194 offset:36864
	ds_read_b128 v[182:185], v194 offset:37888
	ds_read_b128 v[186:189], v194 offset:38912
	ds_read_b128 v[198:201], v194 offset:39936
	global_load_lds_dwordx4 v146, s[0:1]
	s_mov_b32 m0, s58
	s_nop 0
	global_load_lds_dwordx4 v150, s[0:1]
	s_waitcnt lgkmcnt(8)
	s_barrier
	s_waitcnt lgkmcnt(0)
	s_setprio 1
	s_waitcnt lgkmcnt(0)
	v_mfma_i32_16x16x64_i8 v[134:137], v[58:61], v[162:165], v[134:137]
	v_mfma_i32_16x16x64_i8 v[130:133], v[74:77], v[162:165], v[130:133]
	v_mfma_i32_16x16x64_i8 v[118:121], v[58:61], v[170:173], v[118:121]
	v_mfma_i32_16x16x64_i8 v[114:117], v[74:77], v[170:173], v[114:117]
	v_mfma_i32_16x16x64_i8 v[102:105], v[58:61], v[178:181], v[102:105]
	v_mfma_i32_16x16x64_i8 v[98:101], v[74:77], v[178:181], v[98:101]
	v_mfma_i32_16x16x64_i8 v[86:89], v[58:61], v[186:189], v[86:89]
	v_mfma_i32_16x16x64_i8 v[82:85], v[74:77], v[186:189], v[82:85]
	v_mfma_i32_16x16x64_i8 v[134:137], v[62:65], v[166:169], v[134:137]
	v_mfma_i32_16x16x64_i8 v[130:133], v[78:81], v[166:169], v[130:133]
	v_mfma_i32_16x16x64_i8 v[118:121], v[62:65], v[174:177], v[118:121]
	v_mfma_i32_16x16x64_i8 v[114:117], v[78:81], v[174:177], v[114:117]
	v_mfma_i32_16x16x64_i8 v[102:105], v[62:65], v[182:185], v[102:105]
	v_mfma_i32_16x16x64_i8 v[98:101], v[78:81], v[182:185], v[98:101]
	v_mfma_i32_16x16x64_i8 v[86:89], v[62:65], v[198:201], v[86:89]
	v_mfma_i32_16x16x64_i8 v[82:85], v[78:81], v[198:201], v[82:85]
	s_setprio 0
	s_barrier
; #define G_STAGE(bufoff, gbase, voff) do { _Pragma("unroll") for (int _i = 0; _i < 2; ++_i) \
;         __builtin_amdgcn_global_load_lds((const unsigned*)((const char*)(gbase) + (voff)[_i]), (LAS unsigned*)(lds + (bufoff) + ldsw + _i * 8192), 16, 0, 0); } while (0)
; #define G_WAIT_V(n) asm volatile("s_waitcnt vmcnt(" #n ")" ::: "memory")
; #define G_WAIT_L(n) asm volatile("s_waitcnt lgkmcnt(" #n ")" ::: "memory")
; #define G_BAR __builtin_amdgcn_s_barrier()
; #define G_SCHED __builtin_amdgcn_sched_barrier(0)
; template <int MODE  , class Epi, class Sched>
; __device__ __forceinline__ void gemm_phase(LAS unsigned char* lds, const GemmDesc g, const Sched& S, const Epi& E) {
;     ...
;             G_LDB(B1, 1, 1); G_STAGE(G_SB(1, 0), b3, voffB);
;             G_BAR; G_WAIT_L(0); G_MMA(0, 1, At, B1); G_BAR;
;             G_LDA(At, 1, 1); G_STAGE(G_SA(1, 0), a3, voffA);
;             G_BAR; G_WAIT_L(0); G_MMA(1, 0, At, B0); G_BAR; G_SCHED;
;             G_STAGE(G_SB(1, 1), b3 + hstepB, voffB);
;             G_WAIT_V(6); G_BAR; G_MMA(1, 1, At, B1); G_BAR;
	s_add_i32 s11, 0, 0x1c000
	s_add_i32 s0, s10, s54
	v_add_u32_e32 v154, s11, v191
	s_add_u32 s98, s44, 0x80
	s_addc_u32 s99, s45, 0
	s_mov_b32 m0, s0
	ds_read_b128 v[202:205], v154
	ds_read_b128 v[206:209], v154 offset:1024
	ds_read_b128 v[210:213], v154 offset:2048
	ds_read_b128 v[214:217], v154 offset:3072
	global_load_lds_dwordx4 v148, s[98:99]
	s_add_i32 m0, s0, 0x2000
	s_nop 0
	global_load_lds_dwordx4 v152, s[98:99]
	s_barrier
	s_waitcnt lgkmcnt(0)
	s_setprio 1
	s_waitcnt lgkmcnt(0)
	v_mfma_i32_16x16x64_i8 v[142:145], v[202:205], v[162:165], v[142:145]
	v_mfma_i32_16x16x64_i8 v[138:141], v[210:213], v[162:165], v[138:141]
	v_mfma_i32_16x16x64_i8 v[126:129], v[202:205], v[170:173], v[126:129]
	v_mfma_i32_16x16x64_i8 v[122:125], v[210:213], v[170:173], v[122:125]
	v_mfma_i32_16x16x64_i8 v[110:113], v[202:205], v[178:181], v[110:113]
	v_mfma_i32_16x16x64_i8 v[106:109], v[210:213], v[178:181], v[106:109]
	v_mfma_i32_16x16x64_i8 v[94:97], v[202:205], v[186:189], v[94:97]
	v_mfma_i32_16x16x64_i8 v[90:93], v[210:213], v[186:189], v[90:93]
	v_mfma_i32_16x16x64_i8 v[142:145], v[206:209], v[166:169], v[142:145]
	v_mfma_i32_16x16x64_i8 v[138:141], v[214:217], v[166:169], v[138:141]
	v_mfma_i32_16x16x64_i8 v[126:129], v[206:209], v[174:177], v[126:129]
	v_mfma_i32_16x16x64_i8 v[122:125], v[214:217], v[174:177], v[122:125]
	v_mfma_i32_16x16x64_i8 v[110:113], v[206:209], v[182:185], v[110:113]
	v_mfma_i32_16x16x64_i8 v[106:109], v[214:217], v[182:185], v[106:109]
	v_mfma_i32_16x16x64_i8 v[94:97], v[206:209], v[198:201], v[94:97]
	v_mfma_i32_16x16x64_i8 v[90:93], v[214:217], v[198:201], v[90:93]
	s_setprio 0
	s_mov_b32 m0, s60
	s_barrier
	ds_read_b128 v[162:165], v194 offset:49152
	ds_read_b128 v[166:169], v194 offset:50176
	ds_read_b128 v[170:173], v194 offset:51200
	ds_read_b128 v[174:177], v194 offset:52224
	ds_read_b128 v[178:181], v194 offset:53248
	ds_read_b128 v[182:185], v194 offset:54272
	ds_read_b128 v[186:189], v194 offset:55296
	ds_read_b128 v[198:201], v194 offset:56320
	s_add_u32 s98, s46, 0x80
	s_addc_u32 s99, s47, 0
	global_load_lds_dwordx4 v146, s[98:99]
	s_mov_b32 m0, s61
	s_nop 0
	global_load_lds_dwordx4 v150, s[98:99]
	s_barrier
	s_waitcnt lgkmcnt(0)
	s_setprio 1
	s_waitcnt lgkmcnt(0)
	v_mfma_i32_16x16x64_i8 v[70:73], v[58:61], v[162:165], v[70:73]
	v_mfma_i32_16x16x64_i8 v[66:69], v[74:77], v[162:165], v[66:69]
	v_mfma_i32_16x16x64_i8 v[54:57], v[58:61], v[170:173], v[54:57]
	v_mfma_i32_16x16x64_i8 v[50:53], v[74:77], v[170:173], v[50:53]
	v_mfma_i32_16x16x64_i8 v[22:25], v[58:61], v[178:181], v[22:25]
	v_mfma_i32_16x16x64_i8 v[18:21], v[74:77], v[178:181], v[18:21]
	v_mfma_i32_16x16x64_i8 v[6:9], v[58:61], v[186:189], v[6:9]
	v_mfma_i32_16x16x64_i8 v[2:5], v[74:77], v[186:189], v[2:5]
	v_mfma_i32_16x16x64_i8 v[70:73], v[62:65], v[166:169], v[70:73]
	v_mfma_i32_16x16x64_i8 v[66:69], v[78:81], v[166:169], v[66:69]
	v_mfma_i32_16x16x64_i8 v[54:57], v[62:65], v[174:177], v[54:57]
	v_mfma_i32_16x16x64_i8 v[50:53], v[78:81], v[174:177], v[50:53]
	v_mfma_i32_16x16x64_i8 v[22:25], v[62:65], v[182:185], v[22:25]
	v_mfma_i32_16x16x64_i8 v[18:21], v[78:81], v[182:185], v[18:21]
	v_mfma_i32_16x16x64_i8 v[6:9], v[62:65], v[198:201], v[6:9]
	v_mfma_i32_16x16x64_i8 v[2:5], v[78:81], v[198:201], v[2:5]
	s_setprio 0
	s_barrier
	ds_read_b128 v[232:235], v193
	ds_read_b128 v[236:239], v193 offset:1024
	ds_read_b128 v[240:243], v193 offset:2048
	ds_read_b128 v[244:247], v193 offset:3072
	s_add_u32 s0, s44, 0x44080
	s_addc_u32 s1, s45, 0
	s_add_i32 s10, s11, s54
	s_mov_b32 m0, s10
	s_nop 0
	global_load_lds_dwordx4 v148, s[0:1]
	s_add_i32 m0, s10, 0x2000
	s_nop 0
	global_load_lds_dwordx4 v152, s[0:1]
	s_waitcnt vmcnt(6)
	s_barrier
	s_setprio 1
	v_mfma_i32_16x16x64_i8 v[34:37], v[202:205], v[162:165], v[34:37]
	s_add_i32 s77, s77, 2
	s_add_u32 s72, s72, 0x100
	s_addc_u32 s76, s76, 0
	s_cmp_gt_u32 s77, 13
	s_mov_b64 s[34:35], s[40:41]
	v_mfma_i32_16x16x64_i8 v[78:81], v[206:209], v[166:169], v[34:37]
	v_mfma_i32_16x16x64_i8 v[34:37], v[210:213], v[162:165], v[38:41]
	v_mfma_i32_16x16x64_i8 v[74:77], v[214:217], v[166:169], v[34:37]
	v_mfma_i32_16x16x64_i8 v[34:37], v[202:205], v[170:173], v[42:45]
	v_mfma_i32_16x16x64_i8 v[62:65], v[206:209], v[174:177], v[34:37]
	v_mfma_i32_16x16x64_i8 v[34:37], v[210:213], v[170:173], v[46:49]
	v_mfma_i32_16x16x64_i8 v[30:33], v[202:205], v[178:181], v[30:33]
	v_mfma_i32_16x16x64_i8 v[26:29], v[210:213], v[178:181], v[26:29]
	v_mfma_i32_16x16x64_i8 v[14:17], v[202:205], v[186:189], v[14:17]
	v_mfma_i32_16x16x64_i8 v[10:13], v[210:213], v[186:189], v[10:13]
	v_mfma_i32_16x16x64_i8 v[58:61], v[214:217], v[174:177], v[34:37]
	v_mfma_i32_16x16x64_i8 v[30:33], v[206:209], v[182:185], v[30:33]
	v_mfma_i32_16x16x64_i8 v[26:29], v[214:217], v[182:185], v[26:29]
	v_mfma_i32_16x16x64_i8 v[14:17], v[206:209], v[198:201], v[14:17]
	v_mfma_i32_16x16x64_i8 v[10:13], v[214:217], v[198:201], v[10:13]
	s_setprio 0
	s_cbranch_scc1 .Lkdone_p1c
	s_barrier
	s_branch .LBB0_527

;     __device__ __forceinline__ bool operator()(f32x4 (&acc)[2][2][4][2], const Unit& u, int wr, int wc, int fr, int fq) const {
;     ...
;         const float* cq = csv + (pn - 4) * 256 + cl;
;         const f32x4 c00 = *(const f32x4*)(cq), c01 = *(const f32x4*)(cq + 4), c10 = *(const f32x4*)(cq + HALF), c11 = *(const f32x4*)(cq + HALF + 4);
;         const int kind = pn < 8 ? 0 : (pn < 16 ? 1 : (pn < 24 ? 2 : 3));
;         bf16_t* O = SA + (ptrdiff_t)(kind == 3 ? -1 : kind) * ((ptrdiff_t)T * 1024);
;         const int c0 = (kind == 0 || kind == 3) ? (pn & 3) * 256 + cl : ((pn - 8) & 7) * 128 + cl;
.Lkepi_p1c:
	s_lshl_b32 s0, s75, 8
	s_cmp_lt_u32 s75, 24
	s_cselect_b32 s1, 2, 3
	s_cmp_gt_u32 s75, 15
	s_cselect_b32 s1, s1, 1
	s_cmp_gt_i32 s75, 7
	s_cselect_b32 s72, s1, 0
	s_cmp_gt_i32 s72, 2
	s_mov_b64 s[34:35], -1
	s_cbranch_scc1 .LBB0_531
	s_cmp_eq_u32 s72, 0
	s_cselect_b64 s[34:35], -1, 0
	s_cmp_lg_u32 s72, 0
	s_cbranch_scc0 .LBB0_531
	s_lshl_b32 s1, s75, 7
	s_and_b32 s76, s1, 0x380

; __device__ __forceinline__ float silu_f(float x) { return x * sigmoid_f(x); }
;     __device__ __forceinline__ bool operator()(f32x4 (&acc)[2][2][4][2], const Unit& u, int wr, int wc, int fr, int fq) const {
;     ...
;             for (int m = 0; m < 4; ++m) { const int row = r0 + ai * HALF + m * 16; const float rq = rsc[row];
;                 const i32x4 i00 = __builtin_bit_cast(i32x4, acc[ai][0][m][0]), i01 = __builtin_bit_cast(i32x4, acc[ai][0][m][1]), i10 = __builtin_bit_cast(i32x4, acc[ai][1][m][0]), i11 = __builtin_bit_cast(i32x4, acc[ai][1][m][1]);
;                 f32x4 a0, a1, b0, b1;
; #pragma unroll
;                 for (int j = 0; j < 4; ++j) { a0[j] = (float)i00[j] * (rq * c00[j]); a1[j] = (float)i01[j] * (rq * c01[j]); b0[j] = (float)i10[j] * (rq * c10[j]); b1[j] = (float)i11[j] * (rq * c11[j]); }
;                 if (kind == 0 || kind == 3) {
;                     if (kind == 0) {
; #pragma unroll
;                         for (int j = 0; j < 4; ++j) { a0[j] = silu_f(a0[j]); a1[j] = silu_f(a1[j]); b0[j] = silu_f(b0[j]); b1[j] = silu_f(b1[j]); } }
.LBB0_533:
	v_lshl_add_u32 v162, s73, 8, v1
	v_ashrrev_i32_e32 v163, 31, v162
	v_lshl_add_u64 v[164:165], v[162:163], 2, s[4:5]
	v_mov_b32_e32 v154, v248
	s_mul_i32 s0, s72, 0x2200000
	s_cmp_lg_u32 s72, 3
	s_cselect_b32 s0, s0, 0xfde00000
	v_cvt_f32_i32_e32 v143, v143
	v_cvt_f32_i32_e32 v142, v142
	v_cvt_f32_i32_e32 v139, v139
	v_cvt_f32_i32_e32 v138, v138
	v_cvt_f32_i32_e32 v145, v145
	v_cvt_f32_i32_e32 v144, v144
	v_cvt_f32_i32_e32 v141, v141
	v_cvt_f32_i32_e32 v140, v140
	s_ashr_i32 s1, s0, 31
	s_lshl_b64 s[0:1], s[0:1], 1
	s_add_u32 s34, s6, s0
	s_addc_u32 s35, s7, s1
	s_cmp_lt_i32 s72, 2
	s_nop 0
	v_pk_mul_f32 v[166:167], v[226:227], v[154:155] op_sel_hi:[1,0]
	v_pk_mul_f32 v[168:169], v[158:159], v[154:155] op_sel_hi:[1,0]
	v_pk_mul_f32 v[170:171], v[228:229], v[154:155] op_sel_hi:[1,0]
	v_pk_mul_f32 v[172:173], v[160:161], v[154:155] op_sel_hi:[1,0]
	v_pk_mul_f32 v[142:143], v[166:167], v[142:143]
	v_pk_mul_f32 v[138:139], v[168:169], v[138:139]
	v_pk_mul_f32 v[144:145], v[170:171], v[144:145]
	v_pk_mul_f32 v[140:141], v[172:173], v[140:141]
	s_cbranch_scc1 .LBB0_536
	s_mov_b64 s[44:45], -1
	s_mov_b64 s[46:47], 0
	s_cmp_lt_i32 s72, 3
	s_mov_b64 s[40:41], 0
	s_cbranch_scc0 .LBB0_537
	v_med3_f32 v168, v143, s63, v196
	v_mul_f32_e32 v168, 0xbfb8aa3b, v168
	v_med3_f32 v167, v138, s63, v196
	v_exp_f32_e32 v169, v168
	v_mul_f32_e32 v167, 0xbfb8aa3b, v167
	v_med3_f32 v168, v139, s63, v196
	v_exp_f32_e32 v167, v167
	v_mul_f32_e32 v168, 0xbfb8aa3b, v168
	v_exp_f32_e32 v170, v168
	v_add_f32_e32 v167, 1.0, v167
	v_rcp_f32_e32 v168, v167
	v_add_f32_e32 v167, 1.0, v169
	v_add_f32_e32 v169, 1.0, v170
	v_med3_f32 v171, v140, s63, v196
	v_med3_f32 v166, v142, s63, v196
	v_med3_f32 v170, v144, s63, v196
	v_mul_f32_e32 v171, 0xbfb8aa3b, v171
	v_med3_f32 v172, v145, s63, v196
	v_med3_f32 v173, v141, s63, v196
	v_mul_f32_e32 v166, 0xbfb8aa3b, v166
	v_mul_f32_e32 v170, 0xbfb8aa3b, v170
	v_exp_f32_e32 v171, v171
	v_mul_f32_e32 v172, 0xbfb8aa3b, v172
	v_mul_f32_e32 v173, 0xbfb8aa3b, v173
	v_exp_f32_e32 v166, v166
	v_exp_f32_e32 v170, v170
	v_exp_f32_e32 v172, v172
	v_exp_f32_e32 v173, v173
	v_add_f32_e32 v171, 1.0, v171
	v_add_f32_e32 v166, 1.0, v166
	v_add_f32_e32 v170, 1.0, v170
	v_rcp_f32_e32 v176, v171
	v_add_f32_e32 v171, 1.0, v172
	v_add_f32_e32 v172, 1.0, v173
	v_rcp_f32_e32 v166, v166
	v_rcp_f32_e32 v167, v167
	v_rcp_f32_e32 v169, v169
	v_rcp_f32_e32 v170, v170
	v_rcp_f32_e32 v171, v171
	v_rcp_f32_e32 v177, v172
	v_pk_mul_f32 v[174:175], v[142:143], v[166:167]
	v_pk_mul_f32 v[172:173], v[138:139], v[168:169]
	v_pk_mul_f32 v[170:171], v[144:145], v[170:171]
	v_pk_mul_f32 v[168:169], v[140:141], v[176:177]
	s_mov_b64 s[44:45], 0
	s_mov_b64 s[40:41], -1
	s_branch .LBB0_537

; __device__ __forceinline__ unsigned pk_bf16(float lo, float hi) { const f32x2_t v = {lo, hi}; return __builtin_bit_cast(unsigned, __builtin_convertvector(v, bf16x2_t)); }
; __device__ __forceinline__ float silu_f(float x) { return x * sigmoid_f(x); }
;     __device__ __forceinline__ bool operator()(f32x4 (&acc)[2][2][4][2], const Unit& u, int wr, int wc, int fr, int fq) const {
;     ...
;                 for (int j = 0; j < 4; ++j) { a0[j] = (float)i00[j] * (rq * c00[j]); a1[j] = (float)i01[j] * (rq * c01[j]); b0[j] = (float)i10[j] * (rq * c10[j]); b1[j] = (float)i11[j] * (rq * c11[j]); }
;                 if (kind == 0 || kind == 3) {
;                     if (kind == 0) {
; #pragma unroll
;                         for (int j = 0; j < 4; ++j) { a0[j] = silu_f(a0[j]); a1[j] = silu_f(a1[j]); b0[j] = silu_f(b0[j]); b1[j] = silu_f(b1[j]); } }
;                     u32x4 w; w.x = pk_bf16(a0[0], a0[1]); w.y = pk_bf16(a0[2], a0[3]); w.z = pk_bf16(a1[0], a1[1]); w.w = pk_bf16(a1[2], a1[3]);
;                     *(u32x4*)(O + (size_t)row * 1024 + c0) = w;
;                     w.x = pk_bf16(b0[0], b0[1]); w.y = pk_bf16(b0[2], b0[3]); w.z = pk_bf16(b1[0], b1[1]); w.w = pk_bf16(b1[2], b1[3]);
;                     *(u32x4*)(O + (size_t)row * 1024 + c0 + HALF) = w;
;                 } else { f32x4 v0, v1;
;                     if (kind == 1) { v0 = a0 * b0; v1 = a1 * b1; }
;                     else {
; #pragma unroll
;                         for (int j = 0; j < 4; ++j) { v0[j] = a0[j] * silu_f(b0[j]); v1[j] = a1[j] * silu_f(b1[j]); } }
.LBB0_537:
	v_cvt_f32_i32_e32 v135, v135
	v_cvt_f32_i32_e32 v134, v134
	v_cvt_f32_i32_e32 v131, v131
	v_cvt_f32_i32_e32 v130, v130
	v_pk_mul_f32 v[166:167], v[218:219], v[154:155] op_sel_hi:[1,0]
	s_and_b64 vcc, exec, s[46:47]
	v_pk_mul_f32 v[134:135], v[166:167], v[134:135]
	v_pk_mul_f32 v[166:167], v[222:223], v[154:155] op_sel_hi:[1,0]
	s_nop 0
	v_pk_mul_f32 v[166:167], v[166:167], v[130:131]
	v_cvt_f32_i32_e32 v131, v137
	v_cvt_f32_i32_e32 v130, v136
	v_cvt_f32_i32_e32 v137, v133
	v_cvt_f32_i32_e32 v136, v132
	v_pk_mul_f32 v[132:133], v[220:221], v[154:155] op_sel_hi:[1,0]
	s_nop 0
	v_pk_mul_f32 v[132:133], v[132:133], v[130:131]
	v_pk_mul_f32 v[130:131], v[224:225], v[154:155] op_sel_hi:[1,0]
	s_nop 0
	v_pk_mul_f32 v[136:137], v[130:131], v[136:137]
	s_cbranch_vccz .LBB0_541
	s_cmp_lg_u32 s72, 1
	s_mov_b64 s[40:41], -1
	s_cbranch_scc0 .LBB0_540
	v_med3_f32 v131, v166, s63, v196
	v_mul_f32_e32 v131, 0xbfb8aa3b, v131
	v_med3_f32 v154, v142, s63, v196
	v_exp_f32_e32 v131, v131
	v_mul_f32_e32 v154, 0xbfb8aa3b, v154
	v_med3_f32 v168, v138, s63, v196
	v_exp_f32_e32 v154, v154
	v_mul_f32_e32 v168, 0xbfb8aa3b, v168
	v_exp_f32_e32 v169, v168
	v_add_f32_e32 v131, 1.0, v131
	v_rcp_f32_e32 v168, v131
	v_add_f32_e32 v131, 1.0, v154
	v_rcp_f32_e32 v170, v131
	v_add_f32_e32 v131, 1.0, v169
	v_med3_f32 v154, v135, s63, v196
	v_med3_f32 v169, v167, s63, v196
	v_mul_f32_e32 v154, 0xbfb8aa3b, v154
	v_mul_f32_e32 v169, 0xbfb8aa3b, v169
	v_exp_f32_e32 v154, v154
	v_exp_f32_e32 v169, v169
	v_rcp_f32_e32 v172, v131
	v_add_f32_e32 v131, 1.0, v154
	v_add_f32_e32 v154, 1.0, v169
	v_med3_f32 v169, v143, s63, v196
	v_mul_f32_e32 v169, 0xbfb8aa3b, v169
	v_exp_f32_e32 v171, v169
	v_med3_f32 v169, v139, s63, v196
	v_mul_f32_e32 v169, 0xbfb8aa3b, v169
	v_exp_f32_e32 v173, v169
	v_rcp_f32_e32 v169, v154
	v_add_f32_e32 v154, 1.0, v171
	v_rcp_f32_e32 v171, v154
	v_add_f32_e32 v154, 1.0, v173
	v_med3_f32 v173, v132, s63, v196
	v_mul_f32_e32 v173, 0xbfb8aa3b, v173
	v_exp_f32_e32 v174, v173
	v_med3_f32 v173, v136, s63, v196
	v_mul_f32_e32 v173, 0xbfb8aa3b, v173
	v_exp_f32_e32 v175, v173
	v_rcp_f32_e32 v173, v154
	v_add_f32_e32 v154, 1.0, v174
	v_rcp_f32_e32 v174, v154
	v_add_f32_e32 v154, 1.0, v175
	v_rcp_f32_e32 v182, v154
	v_med3_f32 v154, v144, s63, v196
	v_mul_f32_e32 v154, 0xbfb8aa3b, v154
	v_med3_f32 v175, v140, s63, v196
	v_med3_f32 v176, v133, s63, v196
	v_exp_f32_e32 v154, v154
	v_mul_f32_e32 v175, 0xbfb8aa3b, v175
	v_mul_f32_e32 v176, 0xbfb8aa3b, v176
	v_med3_f32 v130, v134, s63, v196
	v_exp_f32_e32 v175, v175
	v_exp_f32_e32 v176, v176
	v_mul_f32_e32 v130, 0xbfb8aa3b, v130
	v_exp_f32_e32 v130, v130
	v_add_f32_e32 v154, 1.0, v154
	v_rcp_f32_e32 v184, v154
	v_add_f32_e32 v154, 1.0, v175
	v_add_f32_e32 v175, 1.0, v176
	v_med3_f32 v176, v137, s63, v196
	v_add_f32_e32 v130, 1.0, v130
	v_mul_f32_e32 v176, 0xbfb8aa3b, v176
	v_rcp_f32_e32 v130, v130
	v_rcp_f32_e32 v131, v131
	v_exp_f32_e32 v178, v176
	v_rcp_f32_e32 v175, v175
	v_rcp_f32_e32 v188, v154
	v_pk_mul_f32 v[180:181], v[134:135], v[130:131]
	v_add_f32_e32 v130, 1.0, v178
	v_rcp_f32_e32 v183, v130
	v_med3_f32 v130, v145, s63, v196
	v_mul_f32_e32 v130, 0xbfb8aa3b, v130
	v_med3_f32 v131, v141, s63, v196
	v_exp_f32_e32 v130, v130
	v_mul_f32_e32 v131, 0xbfb8aa3b, v131
	v_exp_f32_e32 v131, v131
	v_pk_mul_f32 v[176:177], v[132:133], v[174:175]
	v_add_f32_e32 v130, 1.0, v130
	v_rcp_f32_e32 v185, v130
	v_add_f32_e32 v130, 1.0, v131
	v_rcp_f32_e32 v189, v130
	v_pk_mul_f32 v[178:179], v[166:167], v[168:169]
	v_pk_mul_f32 v[182:183], v[136:137], v[182:183]
	v_pk_mul_f32 v[130:131], v[142:143], v[170:171]
	v_pk_mul_f32 v[184:185], v[144:145], v[184:185]
	v_pk_mul_f32 v[186:187], v[138:139], v[172:173]
	v_pk_mul_f32 v[188:189], v[140:141], v[188:189]
	s_mov_b64 s[44:45], -1
	s_mov_b64 s[40:41], 0

; __device__ __forceinline__ float silu_f(float x) { return x * sigmoid_f(x); }
;     __device__ __forceinline__ bool operator()(f32x4 (&acc)[2][2][4][2], const Unit& u, int wr, int wc, int fr, int fq) const {
;     ...
;             for (int m = 0; m < 4; ++m) { const int row = r0 + ai * HALF + m * 16; const float rq = rsc[row];
;                 const i32x4 i00 = __builtin_bit_cast(i32x4, acc[ai][0][m][0]), i01 = __builtin_bit_cast(i32x4, acc[ai][0][m][1]), i10 = __builtin_bit_cast(i32x4, acc[ai][1][m][0]), i11 = __builtin_bit_cast(i32x4, acc[ai][1][m][1]);
;                 f32x4 a0, a1, b0, b1;
; #pragma unroll
;                 for (int j = 0; j < 4; ++j) { a0[j] = (float)i00[j] * (rq * c00[j]); a1[j] = (float)i01[j] * (rq * c01[j]); b0[j] = (float)i10[j] * (rq * c10[j]); b1[j] = (float)i11[j] * (rq * c11[j]); }
;                 if (kind == 0 || kind == 3) {
;                     if (kind == 0) {
; #pragma unroll
;                         for (int j = 0; j < 4; ++j) { a0[j] = silu_f(a0[j]); a1[j] = silu_f(a1[j]); b0[j] = silu_f(b0[j]); b1[j] = silu_f(b1[j]); } }
.LBB0_546:
	s_nop 1
	v_or_b32_e32 v132, 16, v162
	v_ashrrev_i32_e32 v133, 31, v132
	v_lshl_add_u64 v[134:135], v[132:133], 2, s[4:5]
	s_nop 1
	v_mov_b32_e32 v134, v249
	v_cvt_f32_i32_e32 v127, v127
	v_cvt_f32_i32_e32 v126, v126
	v_cvt_f32_i32_e32 v123, v123
	v_cvt_f32_i32_e32 v122, v122
	v_cvt_f32_i32_e32 v129, v129
	v_cvt_f32_i32_e32 v128, v128
	v_cvt_f32_i32_e32 v125, v125
	v_cvt_f32_i32_e32 v124, v124
	s_cmp_lt_i32 s72, 2
	s_nop 0
	v_pk_mul_f32 v[136:137], v[226:227], v[134:135] op_sel_hi:[1,0]
	v_pk_mul_f32 v[138:139], v[158:159], v[134:135] op_sel_hi:[1,0]
	v_pk_mul_f32 v[140:141], v[228:229], v[134:135] op_sel_hi:[1,0]
	v_pk_mul_f32 v[142:143], v[160:161], v[134:135] op_sel_hi:[1,0]
	v_pk_mul_f32 v[126:127], v[136:137], v[126:127]
	v_pk_mul_f32 v[122:123], v[138:139], v[122:123]
	v_pk_mul_f32 v[128:129], v[140:141], v[128:129]
	v_pk_mul_f32 v[124:125], v[142:143], v[124:125]
	s_cbranch_scc1 .LBB0_549
	s_mov_b64 s[40:41], -1
	s_mov_b64 s[44:45], 0
	s_cmp_lt_i32 s72, 3
	s_mov_b64 s[34:35], 0
	s_cbranch_scc0 .LBB0_550
	v_med3_f32 v135, v126, s63, v196
	v_mul_f32_e32 v135, 0xbfb8aa3b, v135
	v_med3_f32 v136, v122, s63, v196
	v_exp_f32_e32 v135, v135
	v_mul_f32_e32 v136, 0xbfb8aa3b, v136
	v_exp_f32_e32 v137, v136
	v_add_f32_e32 v135, 1.0, v135
	v_rcp_f32_e32 v136, v135
	v_add_f32_e32 v135, 1.0, v137
	v_med3_f32 v137, v127, s63, v196
	v_mul_f32_e32 v137, 0xbfb8aa3b, v137
	v_med3_f32 v138, v123, s63, v196
	v_exp_f32_e32 v137, v137
	v_mul_f32_e32 v138, 0xbfb8aa3b, v138
	v_exp_f32_e32 v138, v138
	v_rcp_f32_e32 v140, v135
	v_add_f32_e32 v135, 1.0, v137
	v_rcp_f32_e32 v137, v135
	v_add_f32_e32 v135, 1.0, v138
	v_med3_f32 v138, v128, s63, v196
	v_mul_f32_e32 v138, 0xbfb8aa3b, v138
	v_med3_f32 v139, v124, s63, v196
	v_exp_f32_e32 v138, v138
	v_mul_f32_e32 v139, 0xbfb8aa3b, v139
	v_exp_f32_e32 v139, v139
	v_rcp_f32_e32 v141, v135
	v_add_f32_e32 v135, 1.0, v138
	v_rcp_f32_e32 v138, v135
	v_add_f32_e32 v135, 1.0, v139
	v_med3_f32 v139, v129, s63, v196
	v_mul_f32_e32 v139, 0xbfb8aa3b, v139
	v_med3_f32 v142, v125, s63, v196
	v_exp_f32_e32 v139, v139
	v_mul_f32_e32 v142, 0xbfb8aa3b, v142
	v_exp_f32_e32 v142, v142
	v_rcp_f32_e32 v144, v135
	v_add_f32_e32 v135, 1.0, v139
	v_rcp_f32_e32 v139, v135
	v_add_f32_e32 v135, 1.0, v142
	v_rcp_f32_e32 v145, v135
	v_pk_mul_f32 v[142:143], v[126:127], v[136:137]
	v_pk_mul_f32 v[138:139], v[128:129], v[138:139]
	v_pk_mul_f32 v[140:141], v[122:123], v[140:141]
	v_pk_mul_f32 v[136:137], v[124:125], v[144:145]
	s_mov_b64 s[40:41], 0
	s_mov_b64 s[34:35], -1
	s_branch .LBB0_550

; __device__ __forceinline__ unsigned pk_bf16(float lo, float hi) { const f32x2_t v = {lo, hi}; return __builtin_bit_cast(unsigned, __builtin_convertvector(v, bf16x2_t)); }
; __device__ __forceinline__ float silu_f(float x) { return x * sigmoid_f(x); }
;     __device__ __forceinline__ bool operator()(f32x4 (&acc)[2][2][4][2], const Unit& u, int wr, int wc, int fr, int fq) const {
;     ...
;                 for (int j = 0; j < 4; ++j) { a0[j] = (float)i00[j] * (rq * c00[j]); a1[j] = (float)i01[j] * (rq * c01[j]); b0[j] = (float)i10[j] * (rq * c10[j]); b1[j] = (float)i11[j] * (rq * c11[j]); }
;                 if (kind == 0 || kind == 3) {
;                     if (kind == 0) {
; #pragma unroll
;                         for (int j = 0; j < 4; ++j) { a0[j] = silu_f(a0[j]); a1[j] = silu_f(a1[j]); b0[j] = silu_f(b0[j]); b1[j] = silu_f(b1[j]); } }
;                     u32x4 w; w.x = pk_bf16(a0[0], a0[1]); w.y = pk_bf16(a0[2], a0[3]); w.z = pk_bf16(a1[0], a1[1]); w.w = pk_bf16(a1[2], a1[3]);
;                     *(u32x4*)(O + (size_t)row * 1024 + c0) = w;
;                     w.x = pk_bf16(b0[0], b0[1]); w.y = pk_bf16(b0[2], b0[3]); w.z = pk_bf16(b1[0], b1[1]); w.w = pk_bf16(b1[2], b1[3]);
;                     *(u32x4*)(O + (size_t)row * 1024 + c0 + HALF) = w;
;                 } else { f32x4 v0, v1;
;                     if (kind == 1) { v0 = a0 * b0; v1 = a1 * b1; }
;                     else {
; #pragma unroll
;                         for (int j = 0; j < 4; ++j) { v0[j] = a0[j] * silu_f(b0[j]); v1[j] = a1[j] * silu_f(b1[j]); } }
.LBB0_550:
	v_cvt_f32_i32_e32 v119, v119
	v_cvt_f32_i32_e32 v118, v118
	v_cvt_f32_i32_e32 v145, v115
	v_cvt_f32_i32_e32 v144, v114
	v_pk_mul_f32 v[114:115], v[218:219], v[134:135] op_sel_hi:[1,0]
	v_cvt_f32_i32_e32 v121, v121
	v_pk_mul_f32 v[114:115], v[114:115], v[118:119]
	v_pk_mul_f32 v[118:119], v[222:223], v[134:135] op_sel_hi:[1,0]
	v_cvt_f32_i32_e32 v120, v120
	v_pk_mul_f32 v[118:119], v[118:119], v[144:145]
	v_cvt_f32_i32_e32 v145, v117
	v_cvt_f32_i32_e32 v144, v116
	v_pk_mul_f32 v[116:117], v[220:221], v[134:135] op_sel_hi:[1,0]
	s_and_b64 vcc, exec, s[44:45]
	v_pk_mul_f32 v[116:117], v[116:117], v[120:121]
	v_pk_mul_f32 v[120:121], v[224:225], v[134:135] op_sel_hi:[1,0]
	s_nop 0
	v_pk_mul_f32 v[120:121], v[120:121], v[144:145]
	s_cbranch_vccz .LBB0_554
	s_cmp_lg_u32 s72, 1
	s_mov_b64 s[34:35], -1
	s_cbranch_scc0 .LBB0_553
	v_med3_f32 v143, v120, s63, v196
	v_med3_f32 v136, v126, s63, v196
	v_mul_f32_e32 v143, 0xbfb8aa3b, v143
	v_med3_f32 v135, v118, s63, v196
	v_mul_f32_e32 v136, 0xbfb8aa3b, v136
	v_exp_f32_e32 v143, v143
	v_mul_f32_e32 v135, 0xbfb8aa3b, v135
	v_exp_f32_e32 v137, v136
	v_exp_f32_e32 v135, v135
	v_med3_f32 v136, v122, s63, v196
	v_mul_f32_e32 v136, 0xbfb8aa3b, v136
	v_exp_f32_e32 v139, v136
	v_add_f32_e32 v143, 1.0, v143
	v_rcp_f32_e32 v168, v143
	v_add_f32_e32 v135, 1.0, v135
	v_med3_f32 v143, v128, s63, v196
	v_rcp_f32_e32 v136, v135
	v_add_f32_e32 v135, 1.0, v137
	v_mul_f32_e32 v143, 0xbfb8aa3b, v143
	v_med3_f32 v145, v117, s63, v196
	v_rcp_f32_e32 v138, v135
	v_add_f32_e32 v135, 1.0, v139
	v_exp_f32_e32 v143, v143
	v_mul_f32_e32 v145, 0xbfb8aa3b, v145
	v_med3_f32 v134, v114, s63, v196
	v_med3_f32 v137, v115, s63, v196
	v_med3_f32 v139, v119, s63, v196
	v_med3_f32 v142, v116, s63, v196
	v_exp_f32_e32 v145, v145
	v_mul_f32_e32 v134, 0xbfb8aa3b, v134
	v_mul_f32_e32 v137, 0xbfb8aa3b, v137
	v_mul_f32_e32 v139, 0xbfb8aa3b, v139
	v_mul_f32_e32 v142, 0xbfb8aa3b, v142
	v_exp_f32_e32 v134, v134
	v_exp_f32_e32 v137, v137
	v_exp_f32_e32 v139, v139
	v_exp_f32_e32 v142, v142
	v_add_f32_e32 v143, 1.0, v143
	v_med3_f32 v144, v124, s63, v196
	v_rcp_f32_e32 v172, v143
	v_add_f32_e32 v143, 1.0, v145
	v_mul_f32_e32 v144, 0xbfb8aa3b, v144
	v_med3_f32 v145, v121, s63, v196
	v_add_f32_e32 v134, 1.0, v134
	v_rcp_f32_e32 v140, v135
	v_add_f32_e32 v135, 1.0, v137
	v_add_f32_e32 v137, 1.0, v139
	v_add_f32_e32 v142, 1.0, v142
	v_exp_f32_e32 v144, v144
	v_mul_f32_e32 v145, 0xbfb8aa3b, v145
	v_rcp_f32_e32 v134, v134
	v_rcp_f32_e32 v135, v135
	v_rcp_f32_e32 v137, v137
	v_rcp_f32_e32 v142, v142
	v_rcp_f32_e32 v143, v143
	v_exp_f32_e32 v145, v145
	v_add_f32_e32 v144, 1.0, v144
	v_rcp_f32_e32 v176, v144
	v_pk_mul_f32 v[166:167], v[114:115], v[134:135]
	v_pk_mul_f32 v[134:135], v[116:117], v[142:143]
	v_add_f32_e32 v142, 1.0, v145
	v_pk_mul_f32 v[144:145], v[118:119], v[136:137]
	v_med3_f32 v136, v129, s63, v196
	v_med3_f32 v139, v127, s63, v196
	v_med3_f32 v141, v123, s63, v196
	v_mul_f32_e32 v136, 0xbfb8aa3b, v136
	v_med3_f32 v137, v125, s63, v196
	v_mul_f32_e32 v139, 0xbfb8aa3b, v139
	v_mul_f32_e32 v141, 0xbfb8aa3b, v141
	v_exp_f32_e32 v136, v136
	v_mul_f32_e32 v137, 0xbfb8aa3b, v137
	v_exp_f32_e32 v139, v139
	v_exp_f32_e32 v141, v141
	v_exp_f32_e32 v137, v137
	v_add_f32_e32 v136, 1.0, v136
	v_add_f32_e32 v139, 1.0, v139
	v_add_f32_e32 v141, 1.0, v141
	v_rcp_f32_e32 v173, v136
	v_add_f32_e32 v136, 1.0, v137
	v_rcp_f32_e32 v139, v139
	v_rcp_f32_e32 v141, v141
	v_rcp_f32_e32 v169, v142
	v_rcp_f32_e32 v177, v136
	v_pk_mul_f32 v[170:171], v[126:127], v[138:139]
	v_pk_mul_f32 v[172:173], v[128:129], v[172:173]
	v_pk_mul_f32 v[168:169], v[120:121], v[168:169]
	v_pk_mul_f32 v[174:175], v[122:123], v[140:141]
	v_pk_mul_f32 v[176:177], v[124:125], v[176:177]
	s_mov_b64 s[40:41], -1
	s_mov_b64 s[34:35], 0

; __device__ __forceinline__ float silu_f(float x) { return x * sigmoid_f(x); }
;     __device__ __forceinline__ bool operator()(f32x4 (&acc)[2][2][4][2], const Unit& u, int wr, int wc, int fr, int fq) const {
;     ...
;             for (int m = 0; m < 4; ++m) { const int row = r0 + ai * HALF + m * 16; const float rq = rsc[row];
;                 const i32x4 i00 = __builtin_bit_cast(i32x4, acc[ai][0][m][0]), i01 = __builtin_bit_cast(i32x4, acc[ai][0][m][1]), i10 = __builtin_bit_cast(i32x4, acc[ai][1][m][0]), i11 = __builtin_bit_cast(i32x4, acc[ai][1][m][1]);
;                 f32x4 a0, a1, b0, b1;
; #pragma unroll
;                 for (int j = 0; j < 4; ++j) { a0[j] = (float)i00[j] * (rq * c00[j]); a1[j] = (float)i01[j] * (rq * c01[j]); b0[j] = (float)i10[j] * (rq * c10[j]); b1[j] = (float)i11[j] * (rq * c11[j]); }
;                 if (kind == 0 || kind == 3) {
;                     if (kind == 0) {
; #pragma unroll
;                         for (int j = 0; j < 4; ++j) { a0[j] = silu_f(a0[j]); a1[j] = silu_f(a1[j]); b0[j] = silu_f(b0[j]); b1[j] = silu_f(b1[j]); } }
.LBB0_558:
	s_nop 1
	v_or_b32_e32 v114, 32, v162
	v_ashrrev_i32_e32 v115, 31, v114
	v_lshl_add_u64 v[116:117], v[114:115], 2, s[4:5]
	s_nop 1
	v_mov_b32_e32 v116, v250
	v_cvt_f32_i32_e32 v111, v111
	v_cvt_f32_i32_e32 v110, v110
	v_cvt_f32_i32_e32 v107, v107
	v_cvt_f32_i32_e32 v106, v106
	v_cvt_f32_i32_e32 v113, v113
	v_cvt_f32_i32_e32 v112, v112
	v_cvt_f32_i32_e32 v109, v109
	v_cvt_f32_i32_e32 v108, v108
	s_cmp_lt_i32 s72, 2
	s_nop 0
	v_pk_mul_f32 v[118:119], v[226:227], v[116:117] op_sel_hi:[1,0]
	v_pk_mul_f32 v[120:121], v[158:159], v[116:117] op_sel_hi:[1,0]
	v_pk_mul_f32 v[122:123], v[228:229], v[116:117] op_sel_hi:[1,0]
	v_pk_mul_f32 v[124:125], v[160:161], v[116:117] op_sel_hi:[1,0]
	v_pk_mul_f32 v[110:111], v[118:119], v[110:111]
	v_pk_mul_f32 v[106:107], v[120:121], v[106:107]
	v_pk_mul_f32 v[112:113], v[122:123], v[112:113]
	v_pk_mul_f32 v[108:109], v[124:125], v[108:109]
	s_cbranch_scc1 .LBB0_561
	s_mov_b64 s[40:41], -1
	s_mov_b64 s[44:45], 0
	s_cmp_lt_i32 s72, 3
	s_mov_b64 s[34:35], 0
	s_cbranch_scc0 .LBB0_562
	v_med3_f32 v117, v110, s63, v196
	v_mul_f32_e32 v117, 0xbfb8aa3b, v117
	v_med3_f32 v118, v106, s63, v196
	v_exp_f32_e32 v117, v117
	v_mul_f32_e32 v118, 0xbfb8aa3b, v118
	v_exp_f32_e32 v119, v118
	v_add_f32_e32 v117, 1.0, v117
	v_rcp_f32_e32 v118, v117
	v_add_f32_e32 v117, 1.0, v119
	v_med3_f32 v119, v111, s63, v196
	v_mul_f32_e32 v119, 0xbfb8aa3b, v119
	v_med3_f32 v120, v107, s63, v196
	v_exp_f32_e32 v119, v119
	v_mul_f32_e32 v120, 0xbfb8aa3b, v120
	v_exp_f32_e32 v120, v120
	v_rcp_f32_e32 v122, v117
	v_add_f32_e32 v117, 1.0, v119
	v_rcp_f32_e32 v119, v117
	v_add_f32_e32 v117, 1.0, v120
	v_med3_f32 v120, v112, s63, v196
	v_mul_f32_e32 v120, 0xbfb8aa3b, v120
	v_med3_f32 v121, v108, s63, v196
	v_exp_f32_e32 v120, v120
	v_mul_f32_e32 v121, 0xbfb8aa3b, v121
	v_exp_f32_e32 v121, v121
	v_rcp_f32_e32 v123, v117
	v_add_f32_e32 v117, 1.0, v120
	v_rcp_f32_e32 v120, v117
	v_add_f32_e32 v117, 1.0, v121
	v_med3_f32 v121, v113, s63, v196
	v_mul_f32_e32 v121, 0xbfb8aa3b, v121
	v_med3_f32 v124, v109, s63, v196
	v_exp_f32_e32 v121, v121
	v_mul_f32_e32 v124, 0xbfb8aa3b, v124
	v_exp_f32_e32 v124, v124
	v_rcp_f32_e32 v126, v117
	v_add_f32_e32 v117, 1.0, v121
	v_rcp_f32_e32 v121, v117
	v_add_f32_e32 v117, 1.0, v124
	v_rcp_f32_e32 v127, v117
	v_pk_mul_f32 v[124:125], v[110:111], v[118:119]
	v_pk_mul_f32 v[120:121], v[112:113], v[120:121]
	v_pk_mul_f32 v[122:123], v[106:107], v[122:123]
	v_pk_mul_f32 v[118:119], v[108:109], v[126:127]
	s_mov_b64 s[40:41], 0
	s_mov_b64 s[34:35], -1
	s_branch .LBB0_562

; __device__ __forceinline__ unsigned pk_bf16(float lo, float hi) { const f32x2_t v = {lo, hi}; return __builtin_bit_cast(unsigned, __builtin_convertvector(v, bf16x2_t)); }
; __device__ __forceinline__ float silu_f(float x) { return x * sigmoid_f(x); }
;     __device__ __forceinline__ bool operator()(f32x4 (&acc)[2][2][4][2], const Unit& u, int wr, int wc, int fr, int fq) const {
;     ...
;                 for (int j = 0; j < 4; ++j) { a0[j] = (float)i00[j] * (rq * c00[j]); a1[j] = (float)i01[j] * (rq * c01[j]); b0[j] = (float)i10[j] * (rq * c10[j]); b1[j] = (float)i11[j] * (rq * c11[j]); }
;                 if (kind == 0 || kind == 3) {
;                     if (kind == 0) {
; #pragma unroll
;                         for (int j = 0; j < 4; ++j) { a0[j] = silu_f(a0[j]); a1[j] = silu_f(a1[j]); b0[j] = silu_f(b0[j]); b1[j] = silu_f(b1[j]); } }
;                     u32x4 w; w.x = pk_bf16(a0[0], a0[1]); w.y = pk_bf16(a0[2], a0[3]); w.z = pk_bf16(a1[0], a1[1]); w.w = pk_bf16(a1[2], a1[3]);
;                     *(u32x4*)(O + (size_t)row * 1024 + c0) = w;
;                     w.x = pk_bf16(b0[0], b0[1]); w.y = pk_bf16(b0[2], b0[3]); w.z = pk_bf16(b1[0], b1[1]); w.w = pk_bf16(b1[2], b1[3]);
;                     *(u32x4*)(O + (size_t)row * 1024 + c0 + HALF) = w;
;                 } else { f32x4 v0, v1;
;                     if (kind == 1) { v0 = a0 * b0; v1 = a1 * b1; }
;                     else {
; #pragma unroll
;                         for (int j = 0; j < 4; ++j) { v0[j] = a0[j] * silu_f(b0[j]); v1[j] = a1[j] * silu_f(b1[j]); } }
.LBB0_562:
	v_cvt_f32_i32_e32 v103, v103
	v_cvt_f32_i32_e32 v102, v102
	v_cvt_f32_i32_e32 v127, v99
	v_cvt_f32_i32_e32 v126, v98
	v_pk_mul_f32 v[98:99], v[218:219], v[116:117] op_sel_hi:[1,0]
	v_cvt_f32_i32_e32 v105, v105
	v_pk_mul_f32 v[98:99], v[98:99], v[102:103]
	v_pk_mul_f32 v[102:103], v[222:223], v[116:117] op_sel_hi:[1,0]
	v_cvt_f32_i32_e32 v104, v104
	v_pk_mul_f32 v[102:103], v[102:103], v[126:127]
	v_cvt_f32_i32_e32 v127, v101
	v_cvt_f32_i32_e32 v126, v100
	v_pk_mul_f32 v[100:101], v[220:221], v[116:117] op_sel_hi:[1,0]
	s_and_b64 vcc, exec, s[44:45]
	v_pk_mul_f32 v[100:101], v[100:101], v[104:105]
	v_pk_mul_f32 v[104:105], v[224:225], v[116:117] op_sel_hi:[1,0]
	s_nop 0
	v_pk_mul_f32 v[104:105], v[104:105], v[126:127]
	s_cbranch_vccz .LBB0_566
	s_cmp_lg_u32 s72, 1
	s_mov_b64 s[34:35], -1
	s_cbranch_scc0 .LBB0_565
	v_med3_f32 v125, v104, s63, v196
	v_med3_f32 v118, v110, s63, v196
	v_mul_f32_e32 v125, 0xbfb8aa3b, v125
	v_med3_f32 v117, v102, s63, v196
	v_mul_f32_e32 v118, 0xbfb8aa3b, v118
	v_exp_f32_e32 v125, v125
	v_mul_f32_e32 v117, 0xbfb8aa3b, v117
	v_exp_f32_e32 v119, v118
	v_exp_f32_e32 v117, v117
	v_med3_f32 v118, v106, s63, v196
	v_mul_f32_e32 v118, 0xbfb8aa3b, v118
	v_exp_f32_e32 v121, v118
	v_add_f32_e32 v125, 1.0, v125
	v_rcp_f32_e32 v132, v125
	v_add_f32_e32 v117, 1.0, v117
	v_med3_f32 v125, v112, s63, v196
	v_rcp_f32_e32 v118, v117
	v_add_f32_e32 v117, 1.0, v119
	v_mul_f32_e32 v125, 0xbfb8aa3b, v125
	v_med3_f32 v127, v101, s63, v196
	v_rcp_f32_e32 v120, v117
	v_add_f32_e32 v117, 1.0, v121
	v_exp_f32_e32 v125, v125
	v_mul_f32_e32 v127, 0xbfb8aa3b, v127
	v_med3_f32 v116, v98, s63, v196
	v_med3_f32 v119, v99, s63, v196
	v_med3_f32 v121, v103, s63, v196
	v_med3_f32 v124, v100, s63, v196
	v_exp_f32_e32 v127, v127
	v_mul_f32_e32 v116, 0xbfb8aa3b, v116
	v_mul_f32_e32 v119, 0xbfb8aa3b, v119
	v_mul_f32_e32 v121, 0xbfb8aa3b, v121
	v_mul_f32_e32 v124, 0xbfb8aa3b, v124
	v_exp_f32_e32 v116, v116
	v_exp_f32_e32 v119, v119
	v_exp_f32_e32 v121, v121
	v_exp_f32_e32 v124, v124
	v_add_f32_e32 v125, 1.0, v125
	v_med3_f32 v126, v108, s63, v196
	v_rcp_f32_e32 v136, v125
	v_add_f32_e32 v125, 1.0, v127
	v_mul_f32_e32 v126, 0xbfb8aa3b, v126
	v_med3_f32 v127, v105, s63, v196
	v_add_f32_e32 v116, 1.0, v116
	v_rcp_f32_e32 v122, v117
	v_add_f32_e32 v117, 1.0, v119
	v_add_f32_e32 v119, 1.0, v121
	v_add_f32_e32 v124, 1.0, v124
	v_exp_f32_e32 v126, v126
	v_mul_f32_e32 v127, 0xbfb8aa3b, v127
	v_rcp_f32_e32 v116, v116
	v_rcp_f32_e32 v117, v117
	v_rcp_f32_e32 v119, v119
	v_rcp_f32_e32 v124, v124
	v_rcp_f32_e32 v125, v125
	v_exp_f32_e32 v127, v127
	v_add_f32_e32 v126, 1.0, v126
	v_rcp_f32_e32 v140, v126
	v_pk_mul_f32 v[128:129], v[98:99], v[116:117]
	v_pk_mul_f32 v[116:117], v[100:101], v[124:125]
	v_add_f32_e32 v124, 1.0, v127
	v_pk_mul_f32 v[126:127], v[102:103], v[118:119]
	v_med3_f32 v118, v113, s63, v196
	v_med3_f32 v121, v111, s63, v196
	v_med3_f32 v123, v107, s63, v196
	v_mul_f32_e32 v118, 0xbfb8aa3b, v118
	v_med3_f32 v119, v109, s63, v196
	v_mul_f32_e32 v121, 0xbfb8aa3b, v121
	v_mul_f32_e32 v123, 0xbfb8aa3b, v123
	v_exp_f32_e32 v118, v118
	v_mul_f32_e32 v119, 0xbfb8aa3b, v119
	v_exp_f32_e32 v121, v121
	v_exp_f32_e32 v123, v123
	v_exp_f32_e32 v119, v119
	v_add_f32_e32 v118, 1.0, v118
	v_add_f32_e32 v121, 1.0, v121
	v_add_f32_e32 v123, 1.0, v123
	v_rcp_f32_e32 v137, v118
	v_add_f32_e32 v118, 1.0, v119
	v_rcp_f32_e32 v121, v121
	v_rcp_f32_e32 v123, v123
	v_rcp_f32_e32 v133, v124
	v_rcp_f32_e32 v141, v118
	v_pk_mul_f32 v[134:135], v[110:111], v[120:121]
	v_pk_mul_f32 v[136:137], v[112:113], v[136:137]
	v_pk_mul_f32 v[132:133], v[104:105], v[132:133]
	v_pk_mul_f32 v[138:139], v[106:107], v[122:123]
	v_pk_mul_f32 v[140:141], v[108:109], v[140:141]
	s_mov_b64 s[40:41], -1
	s_mov_b64 s[34:35], 0

; __device__ __forceinline__ float silu_f(float x) { return x * sigmoid_f(x); }
;     __device__ __forceinline__ bool operator()(f32x4 (&acc)[2][2][4][2], const Unit& u, int wr, int wc, int fr, int fq) const {
;     ...
;             for (int m = 0; m < 4; ++m) { const int row = r0 + ai * HALF + m * 16; const float rq = rsc[row];
;                 const i32x4 i00 = __builtin_bit_cast(i32x4, acc[ai][0][m][0]), i01 = __builtin_bit_cast(i32x4, acc[ai][0][m][1]), i10 = __builtin_bit_cast(i32x4, acc[ai][1][m][0]), i11 = __builtin_bit_cast(i32x4, acc[ai][1][m][1]);
;                 f32x4 a0, a1, b0, b1;
; #pragma unroll
;                 for (int j = 0; j < 4; ++j) { a0[j] = (float)i00[j] * (rq * c00[j]); a1[j] = (float)i01[j] * (rq * c01[j]); b0[j] = (float)i10[j] * (rq * c10[j]); b1[j] = (float)i11[j] * (rq * c11[j]); }
;                 if (kind == 0 || kind == 3) {
;                     if (kind == 0) {
; #pragma unroll
;                         for (int j = 0; j < 4; ++j) { a0[j] = silu_f(a0[j]); a1[j] = silu_f(a1[j]); b0[j] = silu_f(b0[j]); b1[j] = silu_f(b1[j]); } }
.LBB0_570:
	s_nop 1
	v_or_b32_e32 v98, 48, v162
	v_ashrrev_i32_e32 v99, 31, v98
	v_lshl_add_u64 v[100:101], v[98:99], 2, s[4:5]
	s_nop 1
	v_mov_b32_e32 v100, v251
	v_cvt_f32_i32_e32 v95, v95
	v_cvt_f32_i32_e32 v94, v94
	v_cvt_f32_i32_e32 v91, v91
	v_cvt_f32_i32_e32 v90, v90
	v_cvt_f32_i32_e32 v97, v97
	v_cvt_f32_i32_e32 v96, v96
	v_cvt_f32_i32_e32 v93, v93
	v_cvt_f32_i32_e32 v92, v92
	s_cmp_lt_i32 s72, 2
	s_nop 0
	v_pk_mul_f32 v[102:103], v[226:227], v[100:101] op_sel_hi:[1,0]
	v_pk_mul_f32 v[104:105], v[158:159], v[100:101] op_sel_hi:[1,0]
	v_pk_mul_f32 v[106:107], v[228:229], v[100:101] op_sel_hi:[1,0]
	v_pk_mul_f32 v[108:109], v[160:161], v[100:101] op_sel_hi:[1,0]
	v_pk_mul_f32 v[94:95], v[102:103], v[94:95]
	v_pk_mul_f32 v[90:91], v[104:105], v[90:91]
	v_pk_mul_f32 v[96:97], v[106:107], v[96:97]
	v_pk_mul_f32 v[92:93], v[108:109], v[92:93]
	s_cbranch_scc1 .LBB0_573
	s_mov_b64 s[40:41], -1
	s_mov_b64 s[44:45], 0
	s_cmp_lt_i32 s72, 3
	s_mov_b64 s[34:35], 0
	s_cbranch_scc0 .LBB0_574
	v_med3_f32 v101, v94, s63, v196
	v_mul_f32_e32 v101, 0xbfb8aa3b, v101
	v_med3_f32 v102, v90, s63, v196
	v_exp_f32_e32 v101, v101
	v_mul_f32_e32 v102, 0xbfb8aa3b, v102
	v_exp_f32_e32 v103, v102
	v_add_f32_e32 v101, 1.0, v101
	v_rcp_f32_e32 v102, v101
	v_add_f32_e32 v101, 1.0, v103
	v_med3_f32 v103, v95, s63, v196
	v_mul_f32_e32 v103, 0xbfb8aa3b, v103
	v_med3_f32 v104, v91, s63, v196
	v_exp_f32_e32 v103, v103
	v_mul_f32_e32 v104, 0xbfb8aa3b, v104
	v_exp_f32_e32 v104, v104
	v_rcp_f32_e32 v106, v101
	v_add_f32_e32 v101, 1.0, v103
	v_rcp_f32_e32 v103, v101
	v_add_f32_e32 v101, 1.0, v104
	v_med3_f32 v104, v96, s63, v196
	v_mul_f32_e32 v104, 0xbfb8aa3b, v104
	v_med3_f32 v105, v92, s63, v196
	v_exp_f32_e32 v104, v104
	v_mul_f32_e32 v105, 0xbfb8aa3b, v105
	v_exp_f32_e32 v105, v105
	v_rcp_f32_e32 v107, v101
	v_add_f32_e32 v101, 1.0, v104
	v_rcp_f32_e32 v104, v101
	v_add_f32_e32 v101, 1.0, v105
	v_med3_f32 v105, v97, s63, v196
	v_mul_f32_e32 v105, 0xbfb8aa3b, v105
	v_med3_f32 v108, v93, s63, v196
	v_exp_f32_e32 v105, v105
	v_mul_f32_e32 v108, 0xbfb8aa3b, v108
	v_exp_f32_e32 v108, v108
	v_rcp_f32_e32 v110, v101
	v_add_f32_e32 v101, 1.0, v105
	v_rcp_f32_e32 v105, v101
	v_add_f32_e32 v101, 1.0, v108
	v_rcp_f32_e32 v111, v101
	v_pk_mul_f32 v[108:109], v[94:95], v[102:103]
	v_pk_mul_f32 v[104:105], v[96:97], v[104:105]
	v_pk_mul_f32 v[106:107], v[90:91], v[106:107]
	v_pk_mul_f32 v[102:103], v[92:93], v[110:111]
	s_mov_b64 s[40:41], 0
	s_mov_b64 s[34:35], -1
	s_branch .LBB0_574

; __device__ __forceinline__ unsigned pk_bf16(float lo, float hi) { const f32x2_t v = {lo, hi}; return __builtin_bit_cast(unsigned, __builtin_convertvector(v, bf16x2_t)); }
; __device__ __forceinline__ float silu_f(float x) { return x * sigmoid_f(x); }
;     __device__ __forceinline__ bool operator()(f32x4 (&acc)[2][2][4][2], const Unit& u, int wr, int wc, int fr, int fq) const {
;     ...
;                 for (int j = 0; j < 4; ++j) { a0[j] = (float)i00[j] * (rq * c00[j]); a1[j] = (float)i01[j] * (rq * c01[j]); b0[j] = (float)i10[j] * (rq * c10[j]); b1[j] = (float)i11[j] * (rq * c11[j]); }
;                 if (kind == 0 || kind == 3) {
;                     if (kind == 0) {
; #pragma unroll
;                         for (int j = 0; j < 4; ++j) { a0[j] = silu_f(a0[j]); a1[j] = silu_f(a1[j]); b0[j] = silu_f(b0[j]); b1[j] = silu_f(b1[j]); } }
;                     u32x4 w; w.x = pk_bf16(a0[0], a0[1]); w.y = pk_bf16(a0[2], a0[3]); w.z = pk_bf16(a1[0], a1[1]); w.w = pk_bf16(a1[2], a1[3]);
;                     *(u32x4*)(O + (size_t)row * 1024 + c0) = w;
;                     w.x = pk_bf16(b0[0], b0[1]); w.y = pk_bf16(b0[2], b0[3]); w.z = pk_bf16(b1[0], b1[1]); w.w = pk_bf16(b1[2], b1[3]);
;                     *(u32x4*)(O + (size_t)row * 1024 + c0 + HALF) = w;
;                 } else { f32x4 v0, v1;
;                     if (kind == 1) { v0 = a0 * b0; v1 = a1 * b1; }
;                     else {
; #pragma unroll
;                         for (int j = 0; j < 4; ++j) { v0[j] = a0[j] * silu_f(b0[j]); v1[j] = a1[j] * silu_f(b1[j]); } }
.LBB0_574:
	v_cvt_f32_i32_e32 v87, v87
	v_cvt_f32_i32_e32 v86, v86
	v_cvt_f32_i32_e32 v111, v83
	v_cvt_f32_i32_e32 v110, v82
	v_pk_mul_f32 v[82:83], v[218:219], v[100:101] op_sel_hi:[1,0]
	v_cvt_f32_i32_e32 v89, v89
	v_pk_mul_f32 v[82:83], v[82:83], v[86:87]
	v_pk_mul_f32 v[86:87], v[222:223], v[100:101] op_sel_hi:[1,0]
	v_cvt_f32_i32_e32 v88, v88
	v_pk_mul_f32 v[86:87], v[86:87], v[110:111]
	v_cvt_f32_i32_e32 v111, v85
	v_cvt_f32_i32_e32 v110, v84
	v_pk_mul_f32 v[84:85], v[220:221], v[100:101] op_sel_hi:[1,0]
	s_and_b64 vcc, exec, s[44:45]
	v_pk_mul_f32 v[84:85], v[84:85], v[88:89]
	v_pk_mul_f32 v[88:89], v[224:225], v[100:101] op_sel_hi:[1,0]
	s_nop 0
	v_pk_mul_f32 v[88:89], v[88:89], v[110:111]
	s_cbranch_vccz .LBB0_578
	s_cmp_lg_u32 s72, 1
	s_mov_b64 s[34:35], -1
	s_cbranch_scc0 .LBB0_577
	v_med3_f32 v109, v88, s63, v196
	v_med3_f32 v102, v94, s63, v196
	v_mul_f32_e32 v109, 0xbfb8aa3b, v109
	v_med3_f32 v101, v86, s63, v196
	v_mul_f32_e32 v102, 0xbfb8aa3b, v102
	v_exp_f32_e32 v109, v109
	v_mul_f32_e32 v101, 0xbfb8aa3b, v101
	v_exp_f32_e32 v103, v102
	v_exp_f32_e32 v101, v101
	v_med3_f32 v102, v90, s63, v196
	v_mul_f32_e32 v102, 0xbfb8aa3b, v102
	v_exp_f32_e32 v105, v102
	v_add_f32_e32 v109, 1.0, v109
	v_rcp_f32_e32 v114, v109
	v_add_f32_e32 v101, 1.0, v101
	v_med3_f32 v109, v96, s63, v196
	v_rcp_f32_e32 v102, v101
	v_add_f32_e32 v101, 1.0, v103
	v_mul_f32_e32 v109, 0xbfb8aa3b, v109
	v_med3_f32 v111, v85, s63, v196
	v_rcp_f32_e32 v104, v101
	v_add_f32_e32 v101, 1.0, v105
	v_exp_f32_e32 v109, v109
	v_mul_f32_e32 v111, 0xbfb8aa3b, v111
	v_med3_f32 v100, v82, s63, v196
	v_med3_f32 v103, v83, s63, v196
	v_med3_f32 v105, v87, s63, v196
	v_med3_f32 v108, v84, s63, v196
	v_exp_f32_e32 v111, v111
	v_mul_f32_e32 v100, 0xbfb8aa3b, v100
	v_mul_f32_e32 v103, 0xbfb8aa3b, v103
	v_mul_f32_e32 v105, 0xbfb8aa3b, v105
	v_mul_f32_e32 v108, 0xbfb8aa3b, v108
	v_exp_f32_e32 v100, v100
	v_exp_f32_e32 v103, v103
	v_exp_f32_e32 v105, v105
	v_exp_f32_e32 v108, v108
	v_add_f32_e32 v109, 1.0, v109
	v_med3_f32 v110, v92, s63, v196
	v_rcp_f32_e32 v118, v109
	v_add_f32_e32 v109, 1.0, v111
	v_mul_f32_e32 v110, 0xbfb8aa3b, v110
	v_med3_f32 v111, v89, s63, v196
	v_add_f32_e32 v100, 1.0, v100
	v_rcp_f32_e32 v106, v101
	v_add_f32_e32 v101, 1.0, v103
	v_add_f32_e32 v103, 1.0, v105
	v_add_f32_e32 v108, 1.0, v108
	v_exp_f32_e32 v110, v110
	v_mul_f32_e32 v111, 0xbfb8aa3b, v111
	v_rcp_f32_e32 v100, v100
	v_rcp_f32_e32 v101, v101
	v_rcp_f32_e32 v103, v103
	v_rcp_f32_e32 v108, v108
	v_rcp_f32_e32 v109, v109
	v_exp_f32_e32 v111, v111
	v_add_f32_e32 v110, 1.0, v110
	v_rcp_f32_e32 v122, v110
	v_pk_mul_f32 v[112:113], v[82:83], v[100:101]
	v_pk_mul_f32 v[100:101], v[84:85], v[108:109]
	v_add_f32_e32 v108, 1.0, v111
	v_pk_mul_f32 v[110:111], v[86:87], v[102:103]
	v_med3_f32 v102, v97, s63, v196
	v_med3_f32 v105, v95, s63, v196
	v_med3_f32 v107, v91, s63, v196
	v_mul_f32_e32 v102, 0xbfb8aa3b, v102
	v_med3_f32 v103, v93, s63, v196
	v_mul_f32_e32 v105, 0xbfb8aa3b, v105
	v_mul_f32_e32 v107, 0xbfb8aa3b, v107
	v_exp_f32_e32 v102, v102
	v_mul_f32_e32 v103, 0xbfb8aa3b, v103
	v_exp_f32_e32 v105, v105
	v_exp_f32_e32 v107, v107
	v_exp_f32_e32 v103, v103
	v_add_f32_e32 v102, 1.0, v102
	v_add_f32_e32 v105, 1.0, v105
	v_add_f32_e32 v107, 1.0, v107
	v_rcp_f32_e32 v119, v102
	v_add_f32_e32 v102, 1.0, v103
	v_rcp_f32_e32 v105, v105
	v_rcp_f32_e32 v107, v107
	v_rcp_f32_e32 v115, v108
	v_rcp_f32_e32 v123, v102
	v_pk_mul_f32 v[116:117], v[94:95], v[104:105]
	v_pk_mul_f32 v[118:119], v[96:97], v[118:119]
	v_pk_mul_f32 v[114:115], v[88:89], v[114:115]
	v_pk_mul_f32 v[120:121], v[90:91], v[106:107]
	v_pk_mul_f32 v[122:123], v[92:93], v[122:123]
	s_mov_b64 s[40:41], -1
	s_mov_b64 s[34:35], 0

; __device__ __forceinline__ unsigned pk_bf16(float lo, float hi) { const f32x2_t v = {lo, hi}; return __builtin_bit_cast(unsigned, __builtin_convertvector(v, bf16x2_t)); }
; __device__ __forceinline__ float silu_f(float x) { return x * sigmoid_f(x); }
;     __device__ __forceinline__ bool operator()(f32x4 (&acc)[2][2][4][2], const Unit& u, int wr, int wc, int fr, int fq) const {
;     ...
;             for (int m = 0; m < 4; ++m) { const int row = r0 + ai * HALF + m * 16; const float rq = rsc[row];
;                 const i32x4 i00 = __builtin_bit_cast(i32x4, acc[ai][0][m][0]), i01 = __builtin_bit_cast(i32x4, acc[ai][0][m][1]), i10 = __builtin_bit_cast(i32x4, acc[ai][1][m][0]), i11 = __builtin_bit_cast(i32x4, acc[ai][1][m][1]);
;                 f32x4 a0, a1, b0, b1;
; #pragma unroll
;                 for (int j = 0; j < 4; ++j) { a0[j] = (float)i00[j] * (rq * c00[j]); a1[j] = (float)i01[j] * (rq * c01[j]); b0[j] = (float)i10[j] * (rq * c10[j]); b1[j] = (float)i11[j] * (rq * c11[j]); }
;                 if (kind == 0 || kind == 3) {
;                     if (kind == 0) {
; #pragma unroll
;                         for (int j = 0; j < 4; ++j) { a0[j] = silu_f(a0[j]); a1[j] = silu_f(a1[j]); b0[j] = silu_f(b0[j]); b1[j] = silu_f(b1[j]); } }
;                     u32x4 w; w.x = pk_bf16(a0[0], a0[1]); w.y = pk_bf16(a0[2], a0[3]); w.z = pk_bf16(a1[0], a1[1]); w.w = pk_bf16(a1[2], a1[3]);
;                     *(u32x4*)(O + (size_t)row * 1024 + c0) = w;
;                     w.x = pk_bf16(b0[0], b0[1]); w.y = pk_bf16(b0[2], b0[3]); w.z = pk_bf16(b1[0], b1[1]); w.w = pk_bf16(b1[2], b1[3]);
;                     *(u32x4*)(O + (size_t)row * 1024 + c0 + HALF) = w;
;                 } else { f32x4 v0, v1;
;                     if (kind == 1) { v0 = a0 * b0; v1 = a1 * b1; }
;                     else {
; #pragma unroll
;                         for (int j = 0; j < 4; ++j) { v0[j] = a0[j] * silu_f(b0[j]); v1[j] = a1[j] * silu_f(b1[j]); } }
.LBB0_582:
	s_nop 1
	v_mov_b32_e32 v82, v252
	v_cvt_f32_i32_e32 v79, v79
	v_cvt_f32_i32_e32 v78, v78
	v_cvt_f32_i32_e32 v75, v75
	v_cvt_f32_i32_e32 v74, v74
	v_cvt_f32_i32_e32 v81, v81
	v_cvt_f32_i32_e32 v80, v80
	v_cvt_f32_i32_e32 v77, v77
	v_cvt_f32_i32_e32 v76, v76
	s_cmp_lt_i32 s72, 2
	s_nop 0
	v_pk_mul_f32 v[84:85], v[226:227], v[82:83] op_sel_hi:[1,0]
	v_pk_mul_f32 v[86:87], v[158:159], v[82:83] op_sel_hi:[1,0]
	v_pk_mul_f32 v[88:89], v[228:229], v[82:83] op_sel_hi:[1,0]
	v_pk_mul_f32 v[90:91], v[160:161], v[82:83] op_sel_hi:[1,0]
	v_pk_mul_f32 v[78:79], v[84:85], v[78:79]
	v_pk_mul_f32 v[74:75], v[86:87], v[74:75]
	v_pk_mul_f32 v[80:81], v[88:89], v[80:81]
	v_pk_mul_f32 v[76:77], v[90:91], v[76:77]
	s_cbranch_scc1 .LBB0_585
	s_mov_b64 s[40:41], -1
	s_mov_b64 s[44:45], 0
	s_cmp_lt_i32 s72, 3
	s_mov_b64 s[34:35], 0
	s_cbranch_scc0 .LBB0_586
	v_med3_f32 v83, v78, s63, v196
	v_mul_f32_e32 v83, 0xbfb8aa3b, v83
	v_med3_f32 v84, v74, s63, v196
	v_exp_f32_e32 v83, v83
	v_mul_f32_e32 v84, 0xbfb8aa3b, v84
	v_exp_f32_e32 v85, v84
	v_add_f32_e32 v83, 1.0, v83
	v_rcp_f32_e32 v84, v83
	v_add_f32_e32 v83, 1.0, v85
	v_med3_f32 v85, v79, s63, v196
	v_mul_f32_e32 v85, 0xbfb8aa3b, v85
	v_med3_f32 v86, v75, s63, v196
	v_exp_f32_e32 v85, v85
	v_mul_f32_e32 v86, 0xbfb8aa3b, v86
	v_exp_f32_e32 v86, v86
	v_rcp_f32_e32 v88, v83
	v_add_f32_e32 v83, 1.0, v85
	v_rcp_f32_e32 v85, v83
	v_add_f32_e32 v83, 1.0, v86
	v_med3_f32 v86, v80, s63, v196
	v_mul_f32_e32 v86, 0xbfb8aa3b, v86
	v_med3_f32 v87, v76, s63, v196
	v_exp_f32_e32 v86, v86
	v_mul_f32_e32 v87, 0xbfb8aa3b, v87
	v_exp_f32_e32 v87, v87
	v_rcp_f32_e32 v89, v83
	v_add_f32_e32 v83, 1.0, v86
	v_rcp_f32_e32 v86, v83
	v_add_f32_e32 v83, 1.0, v87
	v_med3_f32 v87, v81, s63, v196
	v_mul_f32_e32 v87, 0xbfb8aa3b, v87
	v_med3_f32 v90, v77, s63, v196
	v_exp_f32_e32 v87, v87
	v_mul_f32_e32 v90, 0xbfb8aa3b, v90
	v_exp_f32_e32 v90, v90
	v_rcp_f32_e32 v92, v83
	v_add_f32_e32 v83, 1.0, v87
	v_rcp_f32_e32 v87, v83
	v_add_f32_e32 v83, 1.0, v90
	v_rcp_f32_e32 v93, v83
	v_pk_mul_f32 v[90:91], v[78:79], v[84:85]
	v_pk_mul_f32 v[86:87], v[80:81], v[86:87]
	v_pk_mul_f32 v[88:89], v[74:75], v[88:89]
	v_pk_mul_f32 v[84:85], v[76:77], v[92:93]
	s_mov_b64 s[40:41], 0
	s_mov_b64 s[34:35], -1
	s_branch .LBB0_586

; __device__ __forceinline__ unsigned pk_bf16(float lo, float hi) { const f32x2_t v = {lo, hi}; return __builtin_bit_cast(unsigned, __builtin_convertvector(v, bf16x2_t)); }
; __device__ __forceinline__ float silu_f(float x) { return x * sigmoid_f(x); }
;     __device__ __forceinline__ bool operator()(f32x4 (&acc)[2][2][4][2], const Unit& u, int wr, int wc, int fr, int fq) const {
;     ...
;                 for (int j = 0; j < 4; ++j) { a0[j] = (float)i00[j] * (rq * c00[j]); a1[j] = (float)i01[j] * (rq * c01[j]); b0[j] = (float)i10[j] * (rq * c10[j]); b1[j] = (float)i11[j] * (rq * c11[j]); }
;                 if (kind == 0 || kind == 3) {
;                     if (kind == 0) {
; #pragma unroll
;                         for (int j = 0; j < 4; ++j) { a0[j] = silu_f(a0[j]); a1[j] = silu_f(a1[j]); b0[j] = silu_f(b0[j]); b1[j] = silu_f(b1[j]); } }
;                     u32x4 w; w.x = pk_bf16(a0[0], a0[1]); w.y = pk_bf16(a0[2], a0[3]); w.z = pk_bf16(a1[0], a1[1]); w.w = pk_bf16(a1[2], a1[3]);
;                     *(u32x4*)(O + (size_t)row * 1024 + c0) = w;
;                     w.x = pk_bf16(b0[0], b0[1]); w.y = pk_bf16(b0[2], b0[3]); w.z = pk_bf16(b1[0], b1[1]); w.w = pk_bf16(b1[2], b1[3]);
;                     *(u32x4*)(O + (size_t)row * 1024 + c0 + HALF) = w;
;                 } else { f32x4 v0, v1;
;                     if (kind == 1) { v0 = a0 * b0; v1 = a1 * b1; }
;                     else {
; #pragma unroll
;                         for (int j = 0; j < 4; ++j) { v0[j] = a0[j] * silu_f(b0[j]); v1[j] = a1[j] * silu_f(b1[j]); } }
.LBB0_586:
	v_cvt_f32_i32_e32 v71, v71
	v_cvt_f32_i32_e32 v70, v70
	v_cvt_f32_i32_e32 v93, v67
	v_cvt_f32_i32_e32 v92, v66
	v_pk_mul_f32 v[66:67], v[218:219], v[82:83] op_sel_hi:[1,0]
	v_cvt_f32_i32_e32 v73, v73
	v_pk_mul_f32 v[66:67], v[66:67], v[70:71]
	v_pk_mul_f32 v[70:71], v[222:223], v[82:83] op_sel_hi:[1,0]
	v_cvt_f32_i32_e32 v72, v72
	v_pk_mul_f32 v[70:71], v[70:71], v[92:93]
	v_cvt_f32_i32_e32 v93, v69
	v_cvt_f32_i32_e32 v92, v68
	v_pk_mul_f32 v[68:69], v[220:221], v[82:83] op_sel_hi:[1,0]
	s_and_b64 vcc, exec, s[44:45]
	v_pk_mul_f32 v[68:69], v[68:69], v[72:73]
	v_pk_mul_f32 v[72:73], v[224:225], v[82:83] op_sel_hi:[1,0]
	s_nop 0
	v_pk_mul_f32 v[72:73], v[72:73], v[92:93]
	s_cbranch_vccz .LBB0_590
	s_cmp_lg_u32 s72, 1
	s_mov_b64 s[34:35], -1
	s_cbranch_scc0 .LBB0_589
	v_med3_f32 v91, v72, s63, v196
	v_med3_f32 v84, v78, s63, v196
	v_mul_f32_e32 v91, 0xbfb8aa3b, v91
	v_med3_f32 v83, v70, s63, v196
	v_mul_f32_e32 v84, 0xbfb8aa3b, v84
	v_exp_f32_e32 v91, v91
	v_mul_f32_e32 v83, 0xbfb8aa3b, v83
	v_exp_f32_e32 v85, v84
	v_exp_f32_e32 v83, v83
	v_med3_f32 v84, v74, s63, v196
	v_mul_f32_e32 v84, 0xbfb8aa3b, v84
	v_exp_f32_e32 v87, v84
	v_add_f32_e32 v91, 1.0, v91
	v_rcp_f32_e32 v96, v91
	v_add_f32_e32 v83, 1.0, v83
	v_med3_f32 v91, v80, s63, v196
	v_rcp_f32_e32 v84, v83
	v_add_f32_e32 v83, 1.0, v85
	v_mul_f32_e32 v91, 0xbfb8aa3b, v91
	v_med3_f32 v93, v69, s63, v196
	v_rcp_f32_e32 v86, v83
	v_add_f32_e32 v83, 1.0, v87
	v_exp_f32_e32 v91, v91
	v_mul_f32_e32 v93, 0xbfb8aa3b, v93
	v_med3_f32 v82, v66, s63, v196
	v_med3_f32 v85, v67, s63, v196
	v_med3_f32 v87, v71, s63, v196
	v_med3_f32 v90, v68, s63, v196
	v_exp_f32_e32 v93, v93
	v_mul_f32_e32 v82, 0xbfb8aa3b, v82
	v_mul_f32_e32 v85, 0xbfb8aa3b, v85
	v_mul_f32_e32 v87, 0xbfb8aa3b, v87
	v_mul_f32_e32 v90, 0xbfb8aa3b, v90
	v_exp_f32_e32 v82, v82
	v_exp_f32_e32 v85, v85
	v_exp_f32_e32 v87, v87
	v_exp_f32_e32 v90, v90
	v_add_f32_e32 v91, 1.0, v91
	v_med3_f32 v92, v76, s63, v196
	v_rcp_f32_e32 v100, v91
	v_add_f32_e32 v91, 1.0, v93
	v_mul_f32_e32 v92, 0xbfb8aa3b, v92
	v_med3_f32 v93, v73, s63, v196
	v_add_f32_e32 v82, 1.0, v82
	v_rcp_f32_e32 v88, v83
	v_add_f32_e32 v83, 1.0, v85
	v_add_f32_e32 v85, 1.0, v87
	v_add_f32_e32 v90, 1.0, v90
	v_exp_f32_e32 v92, v92
	v_mul_f32_e32 v93, 0xbfb8aa3b, v93
	v_rcp_f32_e32 v82, v82
	v_rcp_f32_e32 v83, v83
	v_rcp_f32_e32 v85, v85
	v_rcp_f32_e32 v90, v90
	v_rcp_f32_e32 v91, v91
	v_exp_f32_e32 v93, v93
	v_add_f32_e32 v92, 1.0, v92
	v_rcp_f32_e32 v104, v92
	v_pk_mul_f32 v[94:95], v[66:67], v[82:83]
	v_pk_mul_f32 v[82:83], v[68:69], v[90:91]
	v_add_f32_e32 v90, 1.0, v93
	v_pk_mul_f32 v[92:93], v[70:71], v[84:85]
	v_med3_f32 v84, v81, s63, v196
	v_med3_f32 v87, v79, s63, v196
	v_med3_f32 v89, v75, s63, v196
	v_mul_f32_e32 v84, 0xbfb8aa3b, v84
	v_med3_f32 v85, v77, s63, v196
	v_mul_f32_e32 v87, 0xbfb8aa3b, v87
	v_mul_f32_e32 v89, 0xbfb8aa3b, v89
	v_exp_f32_e32 v84, v84
	v_mul_f32_e32 v85, 0xbfb8aa3b, v85
	v_exp_f32_e32 v87, v87
	v_exp_f32_e32 v89, v89
	v_exp_f32_e32 v85, v85
	v_add_f32_e32 v84, 1.0, v84
	v_add_f32_e32 v87, 1.0, v87
	v_add_f32_e32 v89, 1.0, v89
	v_rcp_f32_e32 v101, v84
	v_add_f32_e32 v84, 1.0, v85
	v_rcp_f32_e32 v87, v87
	v_rcp_f32_e32 v89, v89
	v_rcp_f32_e32 v97, v90
	v_rcp_f32_e32 v105, v84
	v_pk_mul_f32 v[98:99], v[78:79], v[86:87]
	v_pk_mul_f32 v[100:101], v[80:81], v[100:101]
	v_pk_mul_f32 v[96:97], v[72:73], v[96:97]
	v_pk_mul_f32 v[102:103], v[74:75], v[88:89]
	v_pk_mul_f32 v[104:105], v[76:77], v[104:105]
	s_mov_b64 s[40:41], -1
	s_mov_b64 s[34:35], 0

; __device__ __forceinline__ unsigned pk_bf16(float lo, float hi) { const f32x2_t v = {lo, hi}; return __builtin_bit_cast(unsigned, __builtin_convertvector(v, bf16x2_t)); }
; __device__ __forceinline__ float silu_f(float x) { return x * sigmoid_f(x); }
;     __device__ __forceinline__ bool operator()(f32x4 (&acc)[2][2][4][2], const Unit& u, int wr, int wc, int fr, int fq) const {
;     ...
;             for (int m = 0; m < 4; ++m) { const int row = r0 + ai * HALF + m * 16; const float rq = rsc[row];
;                 const i32x4 i00 = __builtin_bit_cast(i32x4, acc[ai][0][m][0]), i01 = __builtin_bit_cast(i32x4, acc[ai][0][m][1]), i10 = __builtin_bit_cast(i32x4, acc[ai][1][m][0]), i11 = __builtin_bit_cast(i32x4, acc[ai][1][m][1]);
;                 f32x4 a0, a1, b0, b1;
; #pragma unroll
;                 for (int j = 0; j < 4; ++j) { a0[j] = (float)i00[j] * (rq * c00[j]); a1[j] = (float)i01[j] * (rq * c01[j]); b0[j] = (float)i10[j] * (rq * c10[j]); b1[j] = (float)i11[j] * (rq * c11[j]); }
;                 if (kind == 0 || kind == 3) {
;                     if (kind == 0) {
; #pragma unroll
;                         for (int j = 0; j < 4; ++j) { a0[j] = silu_f(a0[j]); a1[j] = silu_f(a1[j]); b0[j] = silu_f(b0[j]); b1[j] = silu_f(b1[j]); } }
;                     u32x4 w; w.x = pk_bf16(a0[0], a0[1]); w.y = pk_bf16(a0[2], a0[3]); w.z = pk_bf16(a1[0], a1[1]); w.w = pk_bf16(a1[2], a1[3]);
;                     *(u32x4*)(O + (size_t)row * 1024 + c0) = w;
;                     w.x = pk_bf16(b0[0], b0[1]); w.y = pk_bf16(b0[2], b0[3]); w.z = pk_bf16(b1[0], b1[1]); w.w = pk_bf16(b1[2], b1[3]);
;                     *(u32x4*)(O + (size_t)row * 1024 + c0 + HALF) = w;
;                 } else { f32x4 v0, v1;
;                     if (kind == 1) { v0 = a0 * b0; v1 = a1 * b1; }
;                     else {
; #pragma unroll
;                         for (int j = 0; j < 4; ++j) { v0[j] = a0[j] * silu_f(b0[j]); v1[j] = a1[j] * silu_f(b1[j]); } }
.LBB0_595:
	s_nop 1
	v_mov_b32_e32 v66, v253
	v_cvt_f32_i32_e32 v63, v63
	v_cvt_f32_i32_e32 v62, v62
	v_cvt_f32_i32_e32 v59, v59
	v_cvt_f32_i32_e32 v58, v58
	v_cvt_f32_i32_e32 v65, v65
	v_cvt_f32_i32_e32 v64, v64
	v_cvt_f32_i32_e32 v61, v61
	v_cvt_f32_i32_e32 v60, v60
	s_cmp_lt_i32 s72, 2
	s_nop 0
	v_pk_mul_f32 v[68:69], v[226:227], v[66:67] op_sel_hi:[1,0]
	v_pk_mul_f32 v[70:71], v[158:159], v[66:67] op_sel_hi:[1,0]
	v_pk_mul_f32 v[72:73], v[228:229], v[66:67] op_sel_hi:[1,0]
	v_pk_mul_f32 v[74:75], v[160:161], v[66:67] op_sel_hi:[1,0]
	v_pk_mul_f32 v[62:63], v[68:69], v[62:63]
	v_pk_mul_f32 v[58:59], v[70:71], v[58:59]
	v_pk_mul_f32 v[64:65], v[72:73], v[64:65]
	v_pk_mul_f32 v[60:61], v[74:75], v[60:61]
	s_cbranch_scc1 .LBB0_598
	s_mov_b64 s[40:41], -1
	s_mov_b64 s[44:45], 0
	s_cmp_lt_i32 s72, 3
	s_mov_b64 s[34:35], 0
	s_cbranch_scc0 .LBB0_599
	v_med3_f32 v67, v62, s63, v196
	v_mul_f32_e32 v67, 0xbfb8aa3b, v67
	v_med3_f32 v68, v58, s63, v196
	v_exp_f32_e32 v67, v67
	v_mul_f32_e32 v68, 0xbfb8aa3b, v68
	v_exp_f32_e32 v69, v68
	v_add_f32_e32 v67, 1.0, v67
	v_rcp_f32_e32 v68, v67
	v_add_f32_e32 v67, 1.0, v69
	v_med3_f32 v69, v63, s63, v196
	v_mul_f32_e32 v69, 0xbfb8aa3b, v69
	v_med3_f32 v70, v59, s63, v196
	v_exp_f32_e32 v69, v69
	v_mul_f32_e32 v70, 0xbfb8aa3b, v70
	v_exp_f32_e32 v70, v70
	v_rcp_f32_e32 v72, v67
	v_add_f32_e32 v67, 1.0, v69
	v_rcp_f32_e32 v69, v67
	v_add_f32_e32 v67, 1.0, v70
	v_med3_f32 v70, v64, s63, v196
	v_mul_f32_e32 v70, 0xbfb8aa3b, v70
	v_med3_f32 v71, v60, s63, v196
	v_exp_f32_e32 v70, v70
	v_mul_f32_e32 v71, 0xbfb8aa3b, v71
	v_exp_f32_e32 v71, v71
	v_rcp_f32_e32 v73, v67
	v_add_f32_e32 v67, 1.0, v70
	v_rcp_f32_e32 v70, v67
	v_add_f32_e32 v67, 1.0, v71
	v_med3_f32 v71, v65, s63, v196
	v_mul_f32_e32 v71, 0xbfb8aa3b, v71
	v_med3_f32 v74, v61, s63, v196
	v_exp_f32_e32 v71, v71
	v_mul_f32_e32 v74, 0xbfb8aa3b, v74
	v_exp_f32_e32 v74, v74
	v_rcp_f32_e32 v76, v67
	v_add_f32_e32 v67, 1.0, v71
	v_rcp_f32_e32 v71, v67
	v_add_f32_e32 v67, 1.0, v74
	v_rcp_f32_e32 v77, v67
	v_pk_mul_f32 v[74:75], v[62:63], v[68:69]
	v_pk_mul_f32 v[70:71], v[64:65], v[70:71]
	v_pk_mul_f32 v[72:73], v[58:59], v[72:73]
	v_pk_mul_f32 v[68:69], v[60:61], v[76:77]
	s_mov_b64 s[40:41], 0
	s_mov_b64 s[34:35], -1
	s_branch .LBB0_599

; __device__ __forceinline__ unsigned pk_bf16(float lo, float hi) { const f32x2_t v = {lo, hi}; return __builtin_bit_cast(unsigned, __builtin_convertvector(v, bf16x2_t)); }
; __device__ __forceinline__ float silu_f(float x) { return x * sigmoid_f(x); }
;     __device__ __forceinline__ bool operator()(f32x4 (&acc)[2][2][4][2], const Unit& u, int wr, int wc, int fr, int fq) const {
;     ...
;                 for (int j = 0; j < 4; ++j) { a0[j] = (float)i00[j] * (rq * c00[j]); a1[j] = (float)i01[j] * (rq * c01[j]); b0[j] = (float)i10[j] * (rq * c10[j]); b1[j] = (float)i11[j] * (rq * c11[j]); }
;                 if (kind == 0 || kind == 3) {
;                     if (kind == 0) {
; #pragma unroll
;                         for (int j = 0; j < 4; ++j) { a0[j] = silu_f(a0[j]); a1[j] = silu_f(a1[j]); b0[j] = silu_f(b0[j]); b1[j] = silu_f(b1[j]); } }
;                     u32x4 w; w.x = pk_bf16(a0[0], a0[1]); w.y = pk_bf16(a0[2], a0[3]); w.z = pk_bf16(a1[0], a1[1]); w.w = pk_bf16(a1[2], a1[3]);
;                     *(u32x4*)(O + (size_t)row * 1024 + c0) = w;
;                     w.x = pk_bf16(b0[0], b0[1]); w.y = pk_bf16(b0[2], b0[3]); w.z = pk_bf16(b1[0], b1[1]); w.w = pk_bf16(b1[2], b1[3]);
;                     *(u32x4*)(O + (size_t)row * 1024 + c0 + HALF) = w;
;                 } else { f32x4 v0, v1;
;                     if (kind == 1) { v0 = a0 * b0; v1 = a1 * b1; }
;                     else {
; #pragma unroll
;                         for (int j = 0; j < 4; ++j) { v0[j] = a0[j] * silu_f(b0[j]); v1[j] = a1[j] * silu_f(b1[j]); } }
.LBB0_599:
	v_cvt_f32_i32_e32 v55, v55
	v_cvt_f32_i32_e32 v54, v54
	v_cvt_f32_i32_e32 v77, v51
	v_cvt_f32_i32_e32 v76, v50
	v_pk_mul_f32 v[50:51], v[218:219], v[66:67] op_sel_hi:[1,0]
	v_cvt_f32_i32_e32 v57, v57
	v_pk_mul_f32 v[50:51], v[50:51], v[54:55]
	v_pk_mul_f32 v[54:55], v[222:223], v[66:67] op_sel_hi:[1,0]
	v_cvt_f32_i32_e32 v56, v56
	v_pk_mul_f32 v[54:55], v[54:55], v[76:77]
	v_cvt_f32_i32_e32 v77, v53
	v_cvt_f32_i32_e32 v76, v52
	v_pk_mul_f32 v[52:53], v[220:221], v[66:67] op_sel_hi:[1,0]
	s_and_b64 vcc, exec, s[44:45]
	v_pk_mul_f32 v[52:53], v[52:53], v[56:57]
	v_pk_mul_f32 v[56:57], v[224:225], v[66:67] op_sel_hi:[1,0]
	s_nop 0
	v_pk_mul_f32 v[56:57], v[56:57], v[76:77]
	s_cbranch_vccz .LBB0_603
	s_cmp_lg_u32 s72, 1
	s_mov_b64 s[34:35], -1
	s_cbranch_scc0 .LBB0_602
	v_med3_f32 v75, v56, s63, v196
	v_med3_f32 v68, v62, s63, v196
	v_mul_f32_e32 v75, 0xbfb8aa3b, v75
	v_med3_f32 v67, v54, s63, v196
	v_mul_f32_e32 v68, 0xbfb8aa3b, v68
	v_exp_f32_e32 v75, v75
	v_mul_f32_e32 v67, 0xbfb8aa3b, v67
	v_exp_f32_e32 v69, v68
	v_exp_f32_e32 v67, v67
	v_med3_f32 v68, v58, s63, v196
	v_mul_f32_e32 v68, 0xbfb8aa3b, v68
	v_exp_f32_e32 v71, v68
	v_add_f32_e32 v75, 1.0, v75
	v_rcp_f32_e32 v80, v75
	v_add_f32_e32 v67, 1.0, v67
	v_med3_f32 v75, v64, s63, v196
	v_rcp_f32_e32 v68, v67
	v_add_f32_e32 v67, 1.0, v69
	v_mul_f32_e32 v75, 0xbfb8aa3b, v75
	v_med3_f32 v77, v53, s63, v196
	v_rcp_f32_e32 v70, v67
	v_add_f32_e32 v67, 1.0, v71
	v_exp_f32_e32 v75, v75
	v_mul_f32_e32 v77, 0xbfb8aa3b, v77
	v_med3_f32 v66, v50, s63, v196
	v_med3_f32 v69, v51, s63, v196
	v_med3_f32 v71, v55, s63, v196
	v_med3_f32 v74, v52, s63, v196
	v_exp_f32_e32 v77, v77
	v_mul_f32_e32 v66, 0xbfb8aa3b, v66
	v_mul_f32_e32 v69, 0xbfb8aa3b, v69
	v_mul_f32_e32 v71, 0xbfb8aa3b, v71
	v_mul_f32_e32 v74, 0xbfb8aa3b, v74
	v_exp_f32_e32 v66, v66
	v_exp_f32_e32 v69, v69
	v_exp_f32_e32 v71, v71
	v_exp_f32_e32 v74, v74
	v_add_f32_e32 v75, 1.0, v75
	v_med3_f32 v76, v60, s63, v196
	v_rcp_f32_e32 v84, v75
	v_add_f32_e32 v75, 1.0, v77
	v_mul_f32_e32 v76, 0xbfb8aa3b, v76
	v_med3_f32 v77, v57, s63, v196
	v_add_f32_e32 v66, 1.0, v66
	v_rcp_f32_e32 v72, v67
	v_add_f32_e32 v67, 1.0, v69
	v_add_f32_e32 v69, 1.0, v71
	v_add_f32_e32 v74, 1.0, v74
	v_exp_f32_e32 v76, v76
	v_mul_f32_e32 v77, 0xbfb8aa3b, v77
	v_rcp_f32_e32 v66, v66
	v_rcp_f32_e32 v67, v67
	v_rcp_f32_e32 v69, v69
	v_rcp_f32_e32 v74, v74
	v_rcp_f32_e32 v75, v75
	v_exp_f32_e32 v77, v77
	v_add_f32_e32 v76, 1.0, v76
	v_rcp_f32_e32 v88, v76
	v_pk_mul_f32 v[78:79], v[50:51], v[66:67]
	v_pk_mul_f32 v[66:67], v[52:53], v[74:75]
	v_add_f32_e32 v74, 1.0, v77
	v_pk_mul_f32 v[76:77], v[54:55], v[68:69]
	v_med3_f32 v68, v65, s63, v196
	v_med3_f32 v71, v63, s63, v196
	v_med3_f32 v73, v59, s63, v196
	v_mul_f32_e32 v68, 0xbfb8aa3b, v68
	v_med3_f32 v69, v61, s63, v196
	v_mul_f32_e32 v71, 0xbfb8aa3b, v71
	v_mul_f32_e32 v73, 0xbfb8aa3b, v73
	v_exp_f32_e32 v68, v68
	v_mul_f32_e32 v69, 0xbfb8aa3b, v69
	v_exp_f32_e32 v71, v71
	v_exp_f32_e32 v73, v73
	v_exp_f32_e32 v69, v69
	v_add_f32_e32 v68, 1.0, v68
	v_add_f32_e32 v71, 1.0, v71
	v_add_f32_e32 v73, 1.0, v73
	v_rcp_f32_e32 v85, v68
	v_add_f32_e32 v68, 1.0, v69
	v_rcp_f32_e32 v71, v71
	v_rcp_f32_e32 v73, v73
	v_rcp_f32_e32 v81, v74
	v_rcp_f32_e32 v89, v68
	v_pk_mul_f32 v[82:83], v[62:63], v[70:71]
	v_pk_mul_f32 v[84:85], v[64:65], v[84:85]
	v_pk_mul_f32 v[80:81], v[56:57], v[80:81]
	v_pk_mul_f32 v[86:87], v[58:59], v[72:73]
	v_pk_mul_f32 v[88:89], v[60:61], v[88:89]
	s_mov_b64 s[40:41], -1
	s_mov_b64 s[34:35], 0

; __device__ __forceinline__ unsigned pk_bf16(float lo, float hi) { const f32x2_t v = {lo, hi}; return __builtin_bit_cast(unsigned, __builtin_convertvector(v, bf16x2_t)); }
; __device__ __forceinline__ float silu_f(float x) { return x * sigmoid_f(x); }
;     __device__ __forceinline__ bool operator()(f32x4 (&acc)[2][2][4][2], const Unit& u, int wr, int wc, int fr, int fq) const {
;     ...
;             for (int m = 0; m < 4; ++m) { const int row = r0 + ai * HALF + m * 16; const float rq = rsc[row];
;                 const i32x4 i00 = __builtin_bit_cast(i32x4, acc[ai][0][m][0]), i01 = __builtin_bit_cast(i32x4, acc[ai][0][m][1]), i10 = __builtin_bit_cast(i32x4, acc[ai][1][m][0]), i11 = __builtin_bit_cast(i32x4, acc[ai][1][m][1]);
;                 f32x4 a0, a1, b0, b1;
; #pragma unroll
;                 for (int j = 0; j < 4; ++j) { a0[j] = (float)i00[j] * (rq * c00[j]); a1[j] = (float)i01[j] * (rq * c01[j]); b0[j] = (float)i10[j] * (rq * c10[j]); b1[j] = (float)i11[j] * (rq * c11[j]); }
;                 if (kind == 0 || kind == 3) {
;                     if (kind == 0) {
; #pragma unroll
;                         for (int j = 0; j < 4; ++j) { a0[j] = silu_f(a0[j]); a1[j] = silu_f(a1[j]); b0[j] = silu_f(b0[j]); b1[j] = silu_f(b1[j]); } }
;                     u32x4 w; w.x = pk_bf16(a0[0], a0[1]); w.y = pk_bf16(a0[2], a0[3]); w.z = pk_bf16(a1[0], a1[1]); w.w = pk_bf16(a1[2], a1[3]);
;                     *(u32x4*)(O + (size_t)row * 1024 + c0) = w;
;                     w.x = pk_bf16(b0[0], b0[1]); w.y = pk_bf16(b0[2], b0[3]); w.z = pk_bf16(b1[0], b1[1]); w.w = pk_bf16(b1[2], b1[3]);
;                     *(u32x4*)(O + (size_t)row * 1024 + c0 + HALF) = w;
;                 } else { f32x4 v0, v1;
;                     if (kind == 1) { v0 = a0 * b0; v1 = a1 * b1; }
;                     else {
; #pragma unroll
;                         for (int j = 0; j < 4; ++j) { v0[j] = a0[j] * silu_f(b0[j]); v1[j] = a1[j] * silu_f(b1[j]); } }
.LBB0_608:
	s_nop 1
	v_mov_b32_e32 v50, v254
	v_cvt_f32_i32_e32 v31, v31
	v_cvt_f32_i32_e32 v30, v30
	v_cvt_f32_i32_e32 v27, v27
	v_cvt_f32_i32_e32 v26, v26
	v_cvt_f32_i32_e32 v33, v33
	v_cvt_f32_i32_e32 v32, v32
	v_cvt_f32_i32_e32 v29, v29
	v_cvt_f32_i32_e32 v28, v28
	s_cmp_lt_i32 s72, 2
	s_nop 0
	v_pk_mul_f32 v[52:53], v[226:227], v[50:51] op_sel_hi:[1,0]
	v_pk_mul_f32 v[54:55], v[158:159], v[50:51] op_sel_hi:[1,0]
	v_pk_mul_f32 v[56:57], v[228:229], v[50:51] op_sel_hi:[1,0]
	v_pk_mul_f32 v[58:59], v[160:161], v[50:51] op_sel_hi:[1,0]
	v_pk_mul_f32 v[30:31], v[52:53], v[30:31]
	v_pk_mul_f32 v[26:27], v[54:55], v[26:27]
	v_pk_mul_f32 v[32:33], v[56:57], v[32:33]
	v_pk_mul_f32 v[28:29], v[58:59], v[28:29]
	s_cbranch_scc1 .LBB0_611
	s_mov_b64 s[40:41], -1
	s_mov_b64 s[44:45], 0
	s_cmp_lt_i32 s72, 3
	s_mov_b64 s[34:35], 0
	s_cbranch_scc0 .LBB0_612
	v_med3_f32 v51, v30, s63, v196
	v_mul_f32_e32 v51, 0xbfb8aa3b, v51
	v_med3_f32 v52, v26, s63, v196
	v_exp_f32_e32 v51, v51
	v_mul_f32_e32 v52, 0xbfb8aa3b, v52
	v_exp_f32_e32 v53, v52
	v_add_f32_e32 v51, 1.0, v51
	v_rcp_f32_e32 v52, v51
	v_add_f32_e32 v51, 1.0, v53
	v_med3_f32 v53, v31, s63, v196
	v_mul_f32_e32 v53, 0xbfb8aa3b, v53
	v_med3_f32 v54, v27, s63, v196
	v_exp_f32_e32 v53, v53
	v_mul_f32_e32 v54, 0xbfb8aa3b, v54
	v_exp_f32_e32 v54, v54
	v_rcp_f32_e32 v56, v51
	v_add_f32_e32 v51, 1.0, v53
	v_rcp_f32_e32 v53, v51
	v_add_f32_e32 v51, 1.0, v54
	v_med3_f32 v54, v32, s63, v196
	v_mul_f32_e32 v54, 0xbfb8aa3b, v54
	v_med3_f32 v55, v28, s63, v196
	v_exp_f32_e32 v54, v54
	v_mul_f32_e32 v55, 0xbfb8aa3b, v55
	v_exp_f32_e32 v55, v55
	v_rcp_f32_e32 v57, v51
	v_add_f32_e32 v51, 1.0, v54
	v_rcp_f32_e32 v54, v51
	v_add_f32_e32 v51, 1.0, v55
	v_med3_f32 v55, v33, s63, v196
	v_mul_f32_e32 v55, 0xbfb8aa3b, v55
	v_med3_f32 v58, v29, s63, v196
	v_exp_f32_e32 v55, v55
	v_mul_f32_e32 v58, 0xbfb8aa3b, v58
	v_exp_f32_e32 v58, v58
	v_rcp_f32_e32 v60, v51
	v_add_f32_e32 v51, 1.0, v55
	v_rcp_f32_e32 v55, v51
	v_add_f32_e32 v51, 1.0, v58
	v_rcp_f32_e32 v61, v51
	v_pk_mul_f32 v[58:59], v[30:31], v[52:53]
	v_pk_mul_f32 v[54:55], v[32:33], v[54:55]
	v_pk_mul_f32 v[56:57], v[26:27], v[56:57]
	v_pk_mul_f32 v[52:53], v[28:29], v[60:61]
	s_mov_b64 s[40:41], 0
	s_mov_b64 s[34:35], -1
	s_branch .LBB0_612

; __device__ __forceinline__ unsigned pk_bf16(float lo, float hi) { const f32x2_t v = {lo, hi}; return __builtin_bit_cast(unsigned, __builtin_convertvector(v, bf16x2_t)); }
; __device__ __forceinline__ float silu_f(float x) { return x * sigmoid_f(x); }
;     __device__ __forceinline__ bool operator()(f32x4 (&acc)[2][2][4][2], const Unit& u, int wr, int wc, int fr, int fq) const {
;     ...
;                 for (int j = 0; j < 4; ++j) { a0[j] = (float)i00[j] * (rq * c00[j]); a1[j] = (float)i01[j] * (rq * c01[j]); b0[j] = (float)i10[j] * (rq * c10[j]); b1[j] = (float)i11[j] * (rq * c11[j]); }
;                 if (kind == 0 || kind == 3) {
;                     if (kind == 0) {
; #pragma unroll
;                         for (int j = 0; j < 4; ++j) { a0[j] = silu_f(a0[j]); a1[j] = silu_f(a1[j]); b0[j] = silu_f(b0[j]); b1[j] = silu_f(b1[j]); } }
;                     u32x4 w; w.x = pk_bf16(a0[0], a0[1]); w.y = pk_bf16(a0[2], a0[3]); w.z = pk_bf16(a1[0], a1[1]); w.w = pk_bf16(a1[2], a1[3]);
;                     *(u32x4*)(O + (size_t)row * 1024 + c0) = w;
;                     w.x = pk_bf16(b0[0], b0[1]); w.y = pk_bf16(b0[2], b0[3]); w.z = pk_bf16(b1[0], b1[1]); w.w = pk_bf16(b1[2], b1[3]);
;                     *(u32x4*)(O + (size_t)row * 1024 + c0 + HALF) = w;
;                 } else { f32x4 v0, v1;
;                     if (kind == 1) { v0 = a0 * b0; v1 = a1 * b1; }
;                     else {
; #pragma unroll
;                         for (int j = 0; j < 4; ++j) { v0[j] = a0[j] * silu_f(b0[j]); v1[j] = a1[j] * silu_f(b1[j]); } }
.LBB0_612:
	v_cvt_f32_i32_e32 v23, v23
	v_cvt_f32_i32_e32 v22, v22
	v_cvt_f32_i32_e32 v61, v19
	v_cvt_f32_i32_e32 v60, v18
	v_pk_mul_f32 v[18:19], v[218:219], v[50:51] op_sel_hi:[1,0]
	v_cvt_f32_i32_e32 v25, v25
	v_pk_mul_f32 v[18:19], v[18:19], v[22:23]
	v_pk_mul_f32 v[22:23], v[222:223], v[50:51] op_sel_hi:[1,0]
	v_cvt_f32_i32_e32 v24, v24
	v_pk_mul_f32 v[22:23], v[22:23], v[60:61]
	v_cvt_f32_i32_e32 v61, v21
	v_cvt_f32_i32_e32 v60, v20
	v_pk_mul_f32 v[20:21], v[220:221], v[50:51] op_sel_hi:[1,0]
	s_and_b64 vcc, exec, s[44:45]
	v_pk_mul_f32 v[20:21], v[20:21], v[24:25]
	v_pk_mul_f32 v[24:25], v[224:225], v[50:51] op_sel_hi:[1,0]
	s_nop 0
	v_pk_mul_f32 v[24:25], v[24:25], v[60:61]
	s_cbranch_vccz .LBB0_616
	s_cmp_lg_u32 s72, 1
	s_mov_b64 s[34:35], -1
	s_cbranch_scc0 .LBB0_615
	v_med3_f32 v59, v24, s63, v196
	v_med3_f32 v52, v30, s63, v196
	v_mul_f32_e32 v59, 0xbfb8aa3b, v59
	v_med3_f32 v51, v22, s63, v196
	v_mul_f32_e32 v52, 0xbfb8aa3b, v52
	v_exp_f32_e32 v59, v59
	v_mul_f32_e32 v51, 0xbfb8aa3b, v51
	v_exp_f32_e32 v53, v52
	v_exp_f32_e32 v51, v51
	v_med3_f32 v52, v26, s63, v196
	v_mul_f32_e32 v52, 0xbfb8aa3b, v52
	v_exp_f32_e32 v55, v52
	v_add_f32_e32 v59, 1.0, v59
	v_rcp_f32_e32 v64, v59
	v_add_f32_e32 v51, 1.0, v51
	v_med3_f32 v59, v32, s63, v196
	v_rcp_f32_e32 v52, v51
	v_add_f32_e32 v51, 1.0, v53
	v_mul_f32_e32 v59, 0xbfb8aa3b, v59
	v_med3_f32 v61, v21, s63, v196
	v_rcp_f32_e32 v54, v51
	v_add_f32_e32 v51, 1.0, v55
	v_exp_f32_e32 v59, v59
	v_mul_f32_e32 v61, 0xbfb8aa3b, v61
	v_med3_f32 v50, v18, s63, v196
	v_med3_f32 v53, v19, s63, v196
	v_med3_f32 v55, v23, s63, v196
	v_med3_f32 v58, v20, s63, v196
	v_exp_f32_e32 v61, v61
	v_mul_f32_e32 v50, 0xbfb8aa3b, v50
	v_mul_f32_e32 v53, 0xbfb8aa3b, v53
	v_mul_f32_e32 v55, 0xbfb8aa3b, v55
	v_mul_f32_e32 v58, 0xbfb8aa3b, v58
	v_exp_f32_e32 v50, v50
	v_exp_f32_e32 v53, v53
	v_exp_f32_e32 v55, v55
	v_exp_f32_e32 v58, v58
	v_add_f32_e32 v59, 1.0, v59
	v_med3_f32 v60, v28, s63, v196
	v_rcp_f32_e32 v68, v59
	v_add_f32_e32 v59, 1.0, v61
	v_mul_f32_e32 v60, 0xbfb8aa3b, v60
	v_med3_f32 v61, v25, s63, v196
	v_add_f32_e32 v50, 1.0, v50
	v_rcp_f32_e32 v56, v51
	v_add_f32_e32 v51, 1.0, v53
	v_add_f32_e32 v53, 1.0, v55
	v_add_f32_e32 v58, 1.0, v58
	v_exp_f32_e32 v60, v60
	v_mul_f32_e32 v61, 0xbfb8aa3b, v61
	v_rcp_f32_e32 v50, v50
	v_rcp_f32_e32 v51, v51
	v_rcp_f32_e32 v53, v53
	v_rcp_f32_e32 v58, v58
	v_rcp_f32_e32 v59, v59
	v_exp_f32_e32 v61, v61
	v_add_f32_e32 v60, 1.0, v60
	v_rcp_f32_e32 v72, v60
	v_pk_mul_f32 v[62:63], v[18:19], v[50:51]
	v_pk_mul_f32 v[50:51], v[20:21], v[58:59]
	v_add_f32_e32 v58, 1.0, v61
	v_pk_mul_f32 v[60:61], v[22:23], v[52:53]
	v_med3_f32 v52, v33, s63, v196
	v_med3_f32 v55, v31, s63, v196
	v_med3_f32 v57, v27, s63, v196
	v_mul_f32_e32 v52, 0xbfb8aa3b, v52
	v_med3_f32 v53, v29, s63, v196
	v_mul_f32_e32 v55, 0xbfb8aa3b, v55
	v_mul_f32_e32 v57, 0xbfb8aa3b, v57
	v_exp_f32_e32 v52, v52
	v_mul_f32_e32 v53, 0xbfb8aa3b, v53
	v_exp_f32_e32 v55, v55
	v_exp_f32_e32 v57, v57
	v_exp_f32_e32 v53, v53
	v_add_f32_e32 v52, 1.0, v52
	v_add_f32_e32 v55, 1.0, v55
	v_add_f32_e32 v57, 1.0, v57
	v_rcp_f32_e32 v69, v52
	v_add_f32_e32 v52, 1.0, v53
	v_rcp_f32_e32 v55, v55
	v_rcp_f32_e32 v57, v57
	v_rcp_f32_e32 v65, v58
	v_rcp_f32_e32 v73, v52
	v_pk_mul_f32 v[66:67], v[30:31], v[54:55]
	v_pk_mul_f32 v[68:69], v[32:33], v[68:69]
	v_pk_mul_f32 v[64:65], v[24:25], v[64:65]
	v_pk_mul_f32 v[70:71], v[26:27], v[56:57]
	v_pk_mul_f32 v[72:73], v[28:29], v[72:73]
	s_mov_b64 s[40:41], -1
	s_mov_b64 s[34:35], 0

; __device__ __forceinline__ unsigned pk_bf16(float lo, float hi) { const f32x2_t v = {lo, hi}; return __builtin_bit_cast(unsigned, __builtin_convertvector(v, bf16x2_t)); }
; __device__ __forceinline__ float silu_f(float x) { return x * sigmoid_f(x); }
;     __device__ __forceinline__ bool operator()(f32x4 (&acc)[2][2][4][2], const Unit& u, int wr, int wc, int fr, int fq) const {
;     ...
;             for (int m = 0; m < 4; ++m) { const int row = r0 + ai * HALF + m * 16; const float rq = rsc[row];
;                 const i32x4 i00 = __builtin_bit_cast(i32x4, acc[ai][0][m][0]), i01 = __builtin_bit_cast(i32x4, acc[ai][0][m][1]), i10 = __builtin_bit_cast(i32x4, acc[ai][1][m][0]), i11 = __builtin_bit_cast(i32x4, acc[ai][1][m][1]);
;                 f32x4 a0, a1, b0, b1;
; #pragma unroll
;                 for (int j = 0; j < 4; ++j) { a0[j] = (float)i00[j] * (rq * c00[j]); a1[j] = (float)i01[j] * (rq * c01[j]); b0[j] = (float)i10[j] * (rq * c10[j]); b1[j] = (float)i11[j] * (rq * c11[j]); }
;                 if (kind == 0 || kind == 3) {
;                     if (kind == 0) {
; #pragma unroll
;                         for (int j = 0; j < 4; ++j) { a0[j] = silu_f(a0[j]); a1[j] = silu_f(a1[j]); b0[j] = silu_f(b0[j]); b1[j] = silu_f(b1[j]); } }
;                     u32x4 w; w.x = pk_bf16(a0[0], a0[1]); w.y = pk_bf16(a0[2], a0[3]); w.z = pk_bf16(a1[0], a1[1]); w.w = pk_bf16(a1[2], a1[3]);
;                     *(u32x4*)(O + (size_t)row * 1024 + c0) = w;
;                     w.x = pk_bf16(b0[0], b0[1]); w.y = pk_bf16(b0[2], b0[3]); w.z = pk_bf16(b1[0], b1[1]); w.w = pk_bf16(b1[2], b1[3]);
;                     *(u32x4*)(O + (size_t)row * 1024 + c0 + HALF) = w;
;                 } else { f32x4 v0, v1;
;                     if (kind == 1) { v0 = a0 * b0; v1 = a1 * b1; }
;                     else {
; #pragma unroll
;                         for (int j = 0; j < 4; ++j) { v0[j] = a0[j] * silu_f(b0[j]); v1[j] = a1[j] * silu_f(b1[j]); } }
.LBB0_621:
	s_nop 1
	v_mov_b32_e32 v18, v255
	v_cvt_f32_i32_e32 v15, v15
	v_cvt_f32_i32_e32 v14, v14
	v_cvt_f32_i32_e32 v11, v11
	v_cvt_f32_i32_e32 v10, v10
	v_cvt_f32_i32_e32 v17, v17
	v_cvt_f32_i32_e32 v16, v16
	v_cvt_f32_i32_e32 v13, v13
	v_cvt_f32_i32_e32 v12, v12
	s_cmp_lt_i32 s72, 2
	s_nop 0
	v_pk_mul_f32 v[20:21], v[226:227], v[18:19] op_sel_hi:[1,0]
	v_pk_mul_f32 v[22:23], v[158:159], v[18:19] op_sel_hi:[1,0]
	v_pk_mul_f32 v[24:25], v[228:229], v[18:19] op_sel_hi:[1,0]
	v_pk_mul_f32 v[26:27], v[160:161], v[18:19] op_sel_hi:[1,0]
	v_pk_mul_f32 v[14:15], v[20:21], v[14:15]
	v_pk_mul_f32 v[10:11], v[22:23], v[10:11]
	v_pk_mul_f32 v[16:17], v[24:25], v[16:17]
	v_pk_mul_f32 v[12:13], v[26:27], v[12:13]
	s_cbranch_scc1 .LBB0_624
	s_mov_b64 s[40:41], -1
	s_mov_b64 s[44:45], 0
	s_cmp_lt_i32 s72, 3
	s_mov_b64 s[34:35], 0
	s_cbranch_scc0 .LBB0_625
	v_med3_f32 v19, v14, s63, v196
	v_mul_f32_e32 v19, 0xbfb8aa3b, v19
	v_med3_f32 v20, v10, s63, v196
	v_exp_f32_e32 v19, v19
	v_mul_f32_e32 v20, 0xbfb8aa3b, v20
	v_exp_f32_e32 v21, v20
	v_add_f32_e32 v19, 1.0, v19
	v_rcp_f32_e32 v20, v19
	v_add_f32_e32 v19, 1.0, v21
	v_med3_f32 v21, v15, s63, v196
	v_mul_f32_e32 v21, 0xbfb8aa3b, v21
	v_med3_f32 v22, v11, s63, v196
	v_exp_f32_e32 v21, v21
	v_mul_f32_e32 v22, 0xbfb8aa3b, v22
	v_exp_f32_e32 v22, v22
	v_rcp_f32_e32 v24, v19
	v_add_f32_e32 v19, 1.0, v21
	v_rcp_f32_e32 v21, v19
	v_add_f32_e32 v19, 1.0, v22
	v_med3_f32 v22, v16, s63, v196
	v_mul_f32_e32 v22, 0xbfb8aa3b, v22
	v_med3_f32 v23, v12, s63, v196
	v_exp_f32_e32 v22, v22
	v_mul_f32_e32 v23, 0xbfb8aa3b, v23
	v_exp_f32_e32 v23, v23
	v_rcp_f32_e32 v25, v19
	v_add_f32_e32 v19, 1.0, v22
	v_rcp_f32_e32 v22, v19
	v_add_f32_e32 v19, 1.0, v23
	v_med3_f32 v23, v17, s63, v196
	v_mul_f32_e32 v23, 0xbfb8aa3b, v23
	v_med3_f32 v26, v13, s63, v196
	v_exp_f32_e32 v23, v23
	v_mul_f32_e32 v26, 0xbfb8aa3b, v26
	v_exp_f32_e32 v26, v26
	v_rcp_f32_e32 v28, v19
	v_add_f32_e32 v19, 1.0, v23
	v_rcp_f32_e32 v23, v19
	v_add_f32_e32 v19, 1.0, v26
	v_rcp_f32_e32 v29, v19
	v_pk_mul_f32 v[26:27], v[14:15], v[20:21]
	v_pk_mul_f32 v[22:23], v[16:17], v[22:23]
	v_pk_mul_f32 v[24:25], v[10:11], v[24:25]
	v_pk_mul_f32 v[20:21], v[12:13], v[28:29]
	s_mov_b64 s[40:41], 0
	s_mov_b64 s[34:35], -1
	s_branch .LBB0_625

; __device__ __forceinline__ unsigned pk_bf16(float lo, float hi) { const f32x2_t v = {lo, hi}; return __builtin_bit_cast(unsigned, __builtin_convertvector(v, bf16x2_t)); }
; __device__ __forceinline__ float silu_f(float x) { return x * sigmoid_f(x); }
;     __device__ __forceinline__ bool operator()(f32x4 (&acc)[2][2][4][2], const Unit& u, int wr, int wc, int fr, int fq) const {
;     ...
;                 for (int j = 0; j < 4; ++j) { a0[j] = (float)i00[j] * (rq * c00[j]); a1[j] = (float)i01[j] * (rq * c01[j]); b0[j] = (float)i10[j] * (rq * c10[j]); b1[j] = (float)i11[j] * (rq * c11[j]); }
;                 if (kind == 0 || kind == 3) {
;                     if (kind == 0) {
; #pragma unroll
;                         for (int j = 0; j < 4; ++j) { a0[j] = silu_f(a0[j]); a1[j] = silu_f(a1[j]); b0[j] = silu_f(b0[j]); b1[j] = silu_f(b1[j]); } }
;                     u32x4 w; w.x = pk_bf16(a0[0], a0[1]); w.y = pk_bf16(a0[2], a0[3]); w.z = pk_bf16(a1[0], a1[1]); w.w = pk_bf16(a1[2], a1[3]);
;                     *(u32x4*)(O + (size_t)row * 1024 + c0) = w;
;                     w.x = pk_bf16(b0[0], b0[1]); w.y = pk_bf16(b0[2], b0[3]); w.z = pk_bf16(b1[0], b1[1]); w.w = pk_bf16(b1[2], b1[3]);
;                     *(u32x4*)(O + (size_t)row * 1024 + c0 + HALF) = w;
;                 } else { f32x4 v0, v1;
;                     if (kind == 1) { v0 = a0 * b0; v1 = a1 * b1; }
;                     else {
; #pragma unroll
;                         for (int j = 0; j < 4; ++j) { v0[j] = a0[j] * silu_f(b0[j]); v1[j] = a1[j] * silu_f(b1[j]); } }
.LBB0_625:
	v_cvt_f32_i32_e32 v7, v7
	v_cvt_f32_i32_e32 v6, v6
	v_cvt_f32_i32_e32 v29, v3
	v_cvt_f32_i32_e32 v28, v2
	v_pk_mul_f32 v[2:3], v[218:219], v[18:19] op_sel_hi:[1,0]
	v_cvt_f32_i32_e32 v9, v9
	v_pk_mul_f32 v[2:3], v[2:3], v[6:7]
	v_pk_mul_f32 v[6:7], v[222:223], v[18:19] op_sel_hi:[1,0]
	v_cvt_f32_i32_e32 v8, v8
	v_pk_mul_f32 v[6:7], v[6:7], v[28:29]
	v_cvt_f32_i32_e32 v29, v5
	v_cvt_f32_i32_e32 v28, v4
	v_pk_mul_f32 v[4:5], v[220:221], v[18:19] op_sel_hi:[1,0]
	s_and_b64 vcc, exec, s[44:45]
	v_pk_mul_f32 v[4:5], v[4:5], v[8:9]
	v_pk_mul_f32 v[8:9], v[224:225], v[18:19] op_sel_hi:[1,0]
	s_nop 0
	v_pk_mul_f32 v[8:9], v[8:9], v[28:29]
	s_cbranch_vccz .LBB0_629
	s_cmp_lg_u32 s72, 1
	s_mov_b64 s[34:35], -1
	s_cbranch_scc0 .LBB0_628
	v_med3_f32 v27, v8, s63, v196
	v_med3_f32 v20, v14, s63, v196
	v_mul_f32_e32 v27, 0xbfb8aa3b, v27
	v_med3_f32 v19, v6, s63, v196
	v_mul_f32_e32 v20, 0xbfb8aa3b, v20
	v_exp_f32_e32 v27, v27
	v_mul_f32_e32 v19, 0xbfb8aa3b, v19
	v_exp_f32_e32 v21, v20
	v_exp_f32_e32 v19, v19
	v_med3_f32 v20, v10, s63, v196
	v_mul_f32_e32 v20, 0xbfb8aa3b, v20
	v_exp_f32_e32 v23, v20
	v_add_f32_e32 v27, 1.0, v27
	v_rcp_f32_e32 v32, v27
	v_add_f32_e32 v19, 1.0, v19
	v_med3_f32 v27, v16, s63, v196
	v_rcp_f32_e32 v20, v19
	v_add_f32_e32 v19, 1.0, v21
	v_mul_f32_e32 v27, 0xbfb8aa3b, v27
	v_med3_f32 v29, v5, s63, v196
	v_rcp_f32_e32 v22, v19
	v_add_f32_e32 v19, 1.0, v23
	v_exp_f32_e32 v27, v27
	v_mul_f32_e32 v29, 0xbfb8aa3b, v29
	v_med3_f32 v18, v2, s63, v196
	v_med3_f32 v21, v3, s63, v196
	v_med3_f32 v23, v7, s63, v196
	v_med3_f32 v26, v4, s63, v196
	v_exp_f32_e32 v29, v29
	v_mul_f32_e32 v18, 0xbfb8aa3b, v18
	v_mul_f32_e32 v21, 0xbfb8aa3b, v21
	v_mul_f32_e32 v23, 0xbfb8aa3b, v23
	v_mul_f32_e32 v26, 0xbfb8aa3b, v26
	v_exp_f32_e32 v18, v18
	v_exp_f32_e32 v21, v21
	v_exp_f32_e32 v23, v23
	v_exp_f32_e32 v26, v26
	v_add_f32_e32 v27, 1.0, v27
	v_med3_f32 v28, v12, s63, v196
	v_rcp_f32_e32 v36, v27
	v_add_f32_e32 v27, 1.0, v29
	v_mul_f32_e32 v28, 0xbfb8aa3b, v28
	v_med3_f32 v29, v9, s63, v196
	v_add_f32_e32 v18, 1.0, v18
	v_rcp_f32_e32 v24, v19
	v_add_f32_e32 v19, 1.0, v21
	v_add_f32_e32 v21, 1.0, v23
	v_add_f32_e32 v26, 1.0, v26
	v_exp_f32_e32 v28, v28
	v_mul_f32_e32 v29, 0xbfb8aa3b, v29
	v_rcp_f32_e32 v18, v18
	v_rcp_f32_e32 v19, v19
	v_rcp_f32_e32 v21, v21
	v_rcp_f32_e32 v26, v26
	v_rcp_f32_e32 v27, v27
	v_exp_f32_e32 v29, v29
	v_add_f32_e32 v28, 1.0, v28
	v_rcp_f32_e32 v40, v28
	v_pk_mul_f32 v[30:31], v[2:3], v[18:19]
	v_pk_mul_f32 v[18:19], v[4:5], v[26:27]
	v_add_f32_e32 v26, 1.0, v29
	v_pk_mul_f32 v[28:29], v[6:7], v[20:21]
	v_med3_f32 v20, v17, s63, v196
	v_med3_f32 v23, v15, s63, v196
	v_med3_f32 v25, v11, s63, v196
	v_mul_f32_e32 v20, 0xbfb8aa3b, v20
	v_med3_f32 v21, v13, s63, v196
	v_mul_f32_e32 v23, 0xbfb8aa3b, v23
	v_mul_f32_e32 v25, 0xbfb8aa3b, v25
	v_exp_f32_e32 v20, v20
	v_mul_f32_e32 v21, 0xbfb8aa3b, v21
	v_exp_f32_e32 v23, v23
	v_exp_f32_e32 v25, v25
	v_exp_f32_e32 v21, v21
	v_add_f32_e32 v20, 1.0, v20
	v_add_f32_e32 v23, 1.0, v23
	v_add_f32_e32 v25, 1.0, v25
	v_rcp_f32_e32 v37, v20
	v_add_f32_e32 v20, 1.0, v21
	v_rcp_f32_e32 v23, v23
	v_rcp_f32_e32 v25, v25
	v_rcp_f32_e32 v33, v26
	v_rcp_f32_e32 v41, v20
	v_pk_mul_f32 v[34:35], v[14:15], v[22:23]
	v_pk_mul_f32 v[36:37], v[16:17], v[36:37]
	v_pk_mul_f32 v[32:33], v[8:9], v[32:33]
	v_pk_mul_f32 v[38:39], v[10:11], v[24:25]
	v_pk_mul_f32 v[40:41], v[12:13], v[40:41]
	s_mov_b64 s[40:41], -1
	s_mov_b64 s[34:35], 0

; #define G_STAGE(bufoff, gbase, voff) do { _Pragma("unroll") for (int _i = 0; _i < 2; ++_i) \
;         __builtin_amdgcn_global_load_lds((const unsigned*)((const char*)(gbase) + (voff)[_i]), (LAS unsigned*)(lds + (bufoff) + ldsw + _i * 8192), 16, 0, 0); } while (0)
; #define G_WAIT_V(n) asm volatile("s_waitcnt vmcnt(" #n ")" ::: "memory")
; #define G_WAIT_L(n) asm volatile("s_waitcnt lgkmcnt(" #n ")" ::: "memory")
; #define G_BAR __builtin_amdgcn_s_barrier()
; #define G_SCHED __builtin_amdgcn_sched_barrier(0)
; template <int MODE  , class Epi, class Sched>
; __device__ __forceinline__ void gemm_phase(LAS unsigned char* lds, const GemmDesc g, const Sched& S, const Epi& E) {
;     ...
;             G_LDB(B0, 0, 0); G_SCHED; G_LDA(At, 0, 0); G_STAGE(G_SA(1, 1), a1 + hstepA, voffA);
;             G_WAIT_L(8); G_BAR; G_WAIT_L(0); G_MMA(0, 0, At, B0); G_BAR; G_SCHED;
;             G_LDB(B1, 0, 1); G_STAGE(G_SB(0, 0), b2, voffB);
;             G_BAR; G_WAIT_L(0); G_MMA(0, 1, At, B1); G_BAR;
;             G_LDA(At, 0, 1); G_STAGE(G_SA(0, 0), a2, voffA);
;             G_BAR; G_WAIT_L(0); G_MMA(1, 0, At, B0); G_BAR; G_SCHED;
;             G_STAGE(G_SB(0, 1), b2 + hstepB, voffB);
;             G_WAIT_V(6); G_BAR; G_MMA(1, 1, At, B1); G_BAR;
.Lnodb_p1b:
.LBB0_737:
	ds_read_b128 v[2:5], v168
	ds_read_b128 v[6:9], v168 offset:1024
	ds_read_b128 v[10:13], v168 offset:2048
	ds_read_b128 v[14:17], v168 offset:3072
	s_add_u32 s46, s50, 0x100
	s_addc_u32 s47, s51, 0
	s_cmp_eq_u32 s79, 12
	s_cselect_b32 s55, s45, s47
	s_cselect_b32 s54, s44, s46
	s_cselect_b32 s53, s3, s78
	s_cselect_b32 s52, s2, s77
	v_lshl_add_u64 v[158:159], s[50:51], 0, v[154:155]
	s_add_i32 m0, s62, 0xc000
	ds_read_b128 v[174:177], v169
	ds_read_b128 v[178:181], v169 offset:1024
	ds_read_b128 v[182:185], v169 offset:2048
	ds_read_b128 v[186:189], v169 offset:3072
	ds_read_b128 v[192:195], v169 offset:4096
	ds_read_b128 v[196:199], v169 offset:5120
	ds_read_b128 v[200:203], v169 offset:6144
	ds_read_b128 v[204:207], v169 offset:7168
	global_load_lds_dwordx4 v[158:159], off
	v_lshl_add_u64 v[158:159], s[50:51], 0, v[156:157]
	s_add_i32 m0, s62, 0xe000
	s_nop 0
	global_load_lds_dwordx4 v[158:159], off
	s_waitcnt lgkmcnt(8)
	s_barrier
	s_waitcnt lgkmcnt(0)
	s_setprio 1
	s_waitcnt lgkmcnt(0)
	v_mfma_scale_f32_16x16x128_f8f6f4 v[142:145], v[2:9], v[174:181], v[142:145], v170, v170 op_sel_hi:[0,0,0]
	v_mfma_scale_f32_16x16x128_f8f6f4 v[138:141], v[10:17], v[174:181], v[138:141], v170, v170 op_sel_hi:[0,0,0]
	v_mfma_scale_f32_16x16x128_f8f6f4 v[126:129], v[2:9], v[182:189], v[126:129], v170, v170 op_sel_hi:[0,0,0]
	v_mfma_scale_f32_16x16x128_f8f6f4 v[122:125], v[10:17], v[182:189], v[122:125], v170, v170 op_sel_hi:[0,0,0]
	v_mfma_scale_f32_16x16x128_f8f6f4 v[110:113], v[2:9], v[192:199], v[110:113], v170, v170 op_sel_hi:[0,0,0]
	v_mfma_scale_f32_16x16x128_f8f6f4 v[106:109], v[10:17], v[192:199], v[106:109], v170, v170 op_sel_hi:[0,0,0]
	v_mfma_scale_f32_16x16x128_f8f6f4 v[94:97], v[2:9], v[200:207], v[94:97], v170, v170 op_sel_hi:[0,0,0]
	v_mfma_scale_f32_16x16x128_f8f6f4 v[90:93], v[10:17], v[200:207], v[90:93], v170, v170 op_sel_hi:[0,0,0]
	s_setprio 0
	s_barrier
	s_add_i32 s0, s69, s60
	v_lshl_add_u64 v[158:159], s[52:53], 0, v[150:151]
	s_mov_b32 m0, s0
	ds_read_b128 v[208:211], v171
	ds_read_b128 v[212:215], v171 offset:1024
	ds_read_b128 v[216:219], v171 offset:2048
	ds_read_b128 v[220:223], v171 offset:3072
	global_load_lds_dwordx4 v[158:159], off
	v_lshl_add_u64 v[160:161], s[52:53], 0, v[146:147]
	s_add_i32 m0, s0, 0x2000
	s_nop 0
	global_load_lds_dwordx4 v[160:161], off
	s_barrier
	s_waitcnt lgkmcnt(0)
	s_setprio 1
	s_waitcnt lgkmcnt(0)
	v_mfma_scale_f32_16x16x128_f8f6f4 v[134:137], v[208:215], v[174:181], v[134:137], v170, v170 op_sel_hi:[0,0,0]
	v_mfma_scale_f32_16x16x128_f8f6f4 v[130:133], v[216:223], v[174:181], v[130:133], v170, v170 op_sel_hi:[0,0,0]
	v_mfma_scale_f32_16x16x128_f8f6f4 v[118:121], v[208:215], v[182:189], v[118:121], v170, v170 op_sel_hi:[0,0,0]
	v_mfma_scale_f32_16x16x128_f8f6f4 v[114:117], v[216:223], v[182:189], v[114:117], v170, v170 op_sel_hi:[0,0,0]
	v_mfma_scale_f32_16x16x128_f8f6f4 v[102:105], v[208:215], v[192:199], v[102:105], v170, v170 op_sel_hi:[0,0,0]
	v_mfma_scale_f32_16x16x128_f8f6f4 v[98:101], v[216:223], v[192:199], v[98:101], v170, v170 op_sel_hi:[0,0,0]
	v_mfma_scale_f32_16x16x128_f8f6f4 v[86:89], v[208:215], v[200:207], v[86:89], v170, v170 op_sel_hi:[0,0,0]
	v_mfma_scale_f32_16x16x128_f8f6f4 v[82:85], v[216:223], v[200:207], v[82:85], v170, v170 op_sel_hi:[0,0,0]
	s_setprio 0
	s_mov_b32 m0, s62
	v_lshl_add_u64 v[162:163], s[54:55], 0, v[152:153]
	s_barrier
	ds_read_b128 v[174:177], v169 offset:16384
	ds_read_b128 v[178:181], v169 offset:17408
	ds_read_b128 v[182:185], v169 offset:18432
	ds_read_b128 v[186:189], v169 offset:19456
	ds_read_b128 v[192:195], v169 offset:20480
	ds_read_b128 v[196:199], v169 offset:21504
	ds_read_b128 v[200:203], v169 offset:22528
	ds_read_b128 v[204:207], v169 offset:23552
	global_load_lds_dwordx4 v[162:163], off
	v_lshl_add_u64 v[164:165], s[54:55], 0, v[148:149]
	s_mov_b32 m0, s63
	s_nop 0
	global_load_lds_dwordx4 v[164:165], off
	s_barrier
	s_waitcnt lgkmcnt(0)
	s_setprio 1
	s_waitcnt lgkmcnt(0)
	v_mfma_scale_f32_16x16x128_f8f6f4 v[78:81], v[2:9], v[174:181], v[78:81], v170, v170 op_sel_hi:[0,0,0]
	v_mfma_scale_f32_16x16x128_f8f6f4 v[74:77], v[10:17], v[174:181], v[74:77], v170, v170 op_sel_hi:[0,0,0]
	v_mfma_scale_f32_16x16x128_f8f6f4 v[62:65], v[2:9], v[182:189], v[62:65], v170, v170 op_sel_hi:[0,0,0]
	v_mfma_scale_f32_16x16x128_f8f6f4 v[58:61], v[10:17], v[182:189], v[58:61], v170, v170 op_sel_hi:[0,0,0]
	v_mfma_scale_f32_16x16x128_f8f6f4 v[46:49], v[2:9], v[192:199], v[46:49], v170, v170 op_sel_hi:[0,0,0]
	v_mfma_scale_f32_16x16x128_f8f6f4 v[42:45], v[10:17], v[192:199], v[42:45], v170, v170 op_sel_hi:[0,0,0]
	v_mfma_scale_f32_16x16x128_f8f6f4 v[30:33], v[2:9], v[200:207], v[30:33], v170, v170 op_sel_hi:[0,0,0]
	v_mfma_scale_f32_16x16x128_f8f6f4 v[26:29], v[10:17], v[200:207], v[26:29], v170, v170 op_sel_hi:[0,0,0]
	s_setprio 0
	s_barrier
	s_add_u32 s0, s52, 0x44000
	s_addc_u32 s1, s53, 0
	s_add_i32 s10, s70, s60
	v_lshl_add_u64 v[2:3], s[0:1], 0, v[150:151]
	s_mov_b32 m0, s10
	s_nop 0
	global_load_lds_dwordx4 v[2:3], off
	v_lshl_add_u64 v[2:3], s[0:1], 0, v[146:147]
	s_add_i32 m0, s10, 0x2000
	s_nop 0
	global_load_lds_dwordx4 v[2:3], off
	s_waitcnt vmcnt(6)
	s_barrier
; #define G_STAGE(bufoff, gbase, voff) do { _Pragma("unroll") for (int _i = 0; _i < 2; ++_i) \
;         __builtin_amdgcn_global_load_lds((const unsigned*)((const char*)(gbase) + (voff)[_i]), (LAS unsigned*)(lds + (bufoff) + ldsw + _i * 8192), 16, 0, 0); } while (0)
; #define G_WAIT_V(n) asm volatile("s_waitcnt vmcnt(" #n ")" ::: "memory")
; #define G_WAIT_L(n) asm volatile("s_waitcnt lgkmcnt(" #n ")" ::: "memory")
; #define G_BAR __builtin_amdgcn_s_barrier()
; #define G_SCHED __builtin_amdgcn_sched_barrier(0)
; template <int MODE  , class Epi, class Sched>
; __device__ __forceinline__ void gemm_phase(LAS unsigned char* lds, const GemmDesc g, const Sched& S, const Epi& E) {
;     ...
;             G_WAIT_V(6); G_BAR; G_MMA(1, 1, At, B1); G_BAR;
;             G_LDB(B0, 1, 0); G_SCHED; G_LDA(At, 1, 0); G_STAGE(G_SA(0, 1), a2 + hstepA, voffA);
;             G_WAIT_L(8); G_BAR; G_WAIT_L(0); G_MMA(0, 0, At, B0); G_BAR; G_SCHED;
;             G_LDB(B1, 1, 1); G_STAGE(G_SB(1, 0), b3, voffB);
	s_setprio 1
	v_mfma_scale_f32_16x16x128_f8f6f4 v[70:73], v[208:215], v[174:181], v[70:73], v170, v170 op_sel_hi:[0,0,0]
	v_mfma_scale_f32_16x16x128_f8f6f4 v[66:69], v[216:223], v[174:181], v[66:69], v170, v170 op_sel_hi:[0,0,0]
	v_mfma_scale_f32_16x16x128_f8f6f4 v[54:57], v[208:215], v[182:189], v[54:57], v170, v170 op_sel_hi:[0,0,0]
	v_mfma_scale_f32_16x16x128_f8f6f4 v[50:53], v[216:223], v[182:189], v[50:53], v170, v170 op_sel_hi:[0,0,0]
	v_mfma_scale_f32_16x16x128_f8f6f4 v[38:41], v[208:215], v[192:199], v[38:41], v170, v170 op_sel_hi:[0,0,0]
	v_mfma_scale_f32_16x16x128_f8f6f4 v[34:37], v[216:223], v[192:199], v[34:37], v170, v170 op_sel_hi:[0,0,0]
	v_mfma_scale_f32_16x16x128_f8f6f4 v[22:25], v[208:215], v[200:207], v[22:25], v170, v170 op_sel_hi:[0,0,0]
	v_mfma_scale_f32_16x16x128_f8f6f4 v[18:21], v[216:223], v[200:207], v[18:21], v170, v170 op_sel_hi:[0,0,0]
	s_setprio 0
	s_add_i32 s10, 0, 0x18000
	v_add_u32_e32 v14, s10, v166
	s_barrier
	ds_read_b128 v[2:5], v14
	ds_read_b128 v[6:9], v14 offset:1024
	ds_read_b128 v[10:13], v14 offset:2048
	ds_read_b128 v[14:17], v14 offset:3072
	s_add_u32 s0, s54, 0x44000
	s_addc_u32 s1, s55, 0
	s_mov_b32 m0, s64
	v_lshl_add_u64 v[208:209], s[0:1], 0, v[152:153]
	ds_read_b128 v[174:177], v169 offset:32768
	ds_read_b128 v[178:181], v169 offset:33792
	ds_read_b128 v[182:185], v169 offset:34816
	ds_read_b128 v[186:189], v169 offset:35840
	ds_read_b128 v[192:195], v169 offset:36864
	ds_read_b128 v[196:199], v169 offset:37888
	ds_read_b128 v[200:203], v169 offset:38912
	ds_read_b128 v[204:207], v169 offset:39936
	global_load_lds_dwordx4 v[208:209], off
	v_lshl_add_u64 v[208:209], s[0:1], 0, v[148:149]
	s_mov_b32 m0, s65
	s_nop 0
	global_load_lds_dwordx4 v[208:209], off
	s_waitcnt lgkmcnt(8)
	s_barrier
	s_waitcnt lgkmcnt(0)
	s_setprio 1
	s_waitcnt lgkmcnt(0)
	v_mfma_scale_f32_16x16x128_f8f6f4 v[142:145], v[2:9], v[174:181], v[142:145], v170, v170 op_sel_hi:[0,0,0]
	v_mfma_scale_f32_16x16x128_f8f6f4 v[138:141], v[10:17], v[174:181], v[138:141], v170, v170 op_sel_hi:[0,0,0]
	v_mfma_scale_f32_16x16x128_f8f6f4 v[126:129], v[2:9], v[182:189], v[126:129], v170, v170 op_sel_hi:[0,0,0]
	v_mfma_scale_f32_16x16x128_f8f6f4 v[122:125], v[10:17], v[182:189], v[122:125], v170, v170 op_sel_hi:[0,0,0]
	v_mfma_scale_f32_16x16x128_f8f6f4 v[110:113], v[2:9], v[192:199], v[110:113], v170, v170 op_sel_hi:[0,0,0]
	v_mfma_scale_f32_16x16x128_f8f6f4 v[106:109], v[10:17], v[192:199], v[106:109], v170, v170 op_sel_hi:[0,0,0]
	v_mfma_scale_f32_16x16x128_f8f6f4 v[94:97], v[2:9], v[200:207], v[94:97], v170, v170 op_sel_hi:[0,0,0]
	v_mfma_scale_f32_16x16x128_f8f6f4 v[90:93], v[10:17], v[200:207], v[90:93], v170, v170 op_sel_hi:[0,0,0]
	s_setprio 0
	s_barrier
	s_add_i32 s11, 0, 0x1c000
	s_add_i32 s0, s10, s60
	v_add_u32_e32 v173, s11, v166
	v_lshl_add_u64 v[158:159], v[158:159], 0, s[12:13]
	s_mov_b32 m0, s0
	ds_read_b128 v[208:211], v173
	ds_read_b128 v[212:215], v173 offset:1024
	ds_read_b128 v[216:219], v173 offset:2048
	ds_read_b128 v[220:223], v173 offset:3072
	global_load_lds_dwordx4 v[158:159], off
	v_lshl_add_u64 v[158:159], v[160:161], 0, s[12:13]
	s_add_i32 m0, s0, 0x2000
	s_nop 0
	global_load_lds_dwordx4 v[158:159], off
	s_barrier
; #define G_STAGE(bufoff, gbase, voff) do { _Pragma("unroll") for (int _i = 0; _i < 2; ++_i) \
;         __builtin_amdgcn_global_load_lds((const unsigned*)((const char*)(gbase) + (voff)[_i]), (LAS unsigned*)(lds + (bufoff) + ldsw + _i * 8192), 16, 0, 0); } while (0)
; #define G_WAIT_V(n) asm volatile("s_waitcnt vmcnt(" #n ")" ::: "memory")
; #define G_WAIT_L(n) asm volatile("s_waitcnt lgkmcnt(" #n ")" ::: "memory")
; #define G_BAR __builtin_amdgcn_s_barrier()
; #define G_SCHED __builtin_amdgcn_sched_barrier(0)
; template <int MODE  , class Epi, class Sched>
; __device__ __forceinline__ void gemm_phase(LAS unsigned char* lds, const GemmDesc g, const Sched& S, const Epi& E) {
;     ...
;             G_LDB(B1, 1, 1); G_STAGE(G_SB(1, 0), b3, voffB);
;             G_BAR; G_WAIT_L(0); G_MMA(0, 1, At, B1); G_BAR;
;             G_LDA(At, 1, 1); G_STAGE(G_SA(1, 0), a3, voffA);
;             G_BAR; G_WAIT_L(0); G_MMA(1, 0, At, B0); G_BAR; G_SCHED;
;             G_STAGE(G_SB(1, 1), b3 + hstepB, voffB);
;             G_WAIT_V(6); G_BAR; G_MMA(1, 1, At, B1); G_BAR;
	s_waitcnt lgkmcnt(0)
	s_setprio 1
	s_waitcnt lgkmcnt(0)
	v_mfma_scale_f32_16x16x128_f8f6f4 v[134:137], v[208:215], v[174:181], v[134:137], v170, v170 op_sel_hi:[0,0,0]
	v_mfma_scale_f32_16x16x128_f8f6f4 v[130:133], v[216:223], v[174:181], v[130:133], v170, v170 op_sel_hi:[0,0,0]
	v_mfma_scale_f32_16x16x128_f8f6f4 v[118:121], v[208:215], v[182:189], v[118:121], v170, v170 op_sel_hi:[0,0,0]
	v_mfma_scale_f32_16x16x128_f8f6f4 v[114:117], v[216:223], v[182:189], v[114:117], v170, v170 op_sel_hi:[0,0,0]
	v_mfma_scale_f32_16x16x128_f8f6f4 v[102:105], v[208:215], v[192:199], v[102:105], v170, v170 op_sel_hi:[0,0,0]
	v_mfma_scale_f32_16x16x128_f8f6f4 v[98:101], v[216:223], v[192:199], v[98:101], v170, v170 op_sel_hi:[0,0,0]
	v_mfma_scale_f32_16x16x128_f8f6f4 v[86:89], v[208:215], v[200:207], v[86:89], v170, v170 op_sel_hi:[0,0,0]
	v_mfma_scale_f32_16x16x128_f8f6f4 v[82:85], v[216:223], v[200:207], v[82:85], v170, v170 op_sel_hi:[0,0,0]
	s_setprio 0
	s_mov_b32 m0, s67
	v_lshl_add_u64 v[158:159], v[162:163], 0, s[12:13]
	s_barrier
	ds_read_b128 v[174:177], v169 offset:49152
	ds_read_b128 v[178:181], v169 offset:50176
	ds_read_b128 v[182:185], v169 offset:51200
	ds_read_b128 v[186:189], v169 offset:52224
	ds_read_b128 v[192:195], v169 offset:53248
	ds_read_b128 v[196:199], v169 offset:54272
	ds_read_b128 v[200:203], v169 offset:55296
	ds_read_b128 v[204:207], v169 offset:56320
	global_load_lds_dwordx4 v[158:159], off
	v_lshl_add_u64 v[158:159], v[164:165], 0, s[12:13]
	s_mov_b32 m0, s68
	s_nop 0
	global_load_lds_dwordx4 v[158:159], off
	s_barrier
	s_waitcnt lgkmcnt(0)
	s_setprio 1
	s_waitcnt lgkmcnt(0)
	v_mfma_scale_f32_16x16x128_f8f6f4 v[78:81], v[2:9], v[174:181], v[78:81], v170, v170 op_sel_hi:[0,0,0]
	v_mfma_scale_f32_16x16x128_f8f6f4 v[74:77], v[10:17], v[174:181], v[74:77], v170, v170 op_sel_hi:[0,0,0]
	v_mfma_scale_f32_16x16x128_f8f6f4 v[62:65], v[2:9], v[182:189], v[62:65], v170, v170 op_sel_hi:[0,0,0]
	v_mfma_scale_f32_16x16x128_f8f6f4 v[58:61], v[10:17], v[182:189], v[58:61], v170, v170 op_sel_hi:[0,0,0]
	v_mfma_scale_f32_16x16x128_f8f6f4 v[46:49], v[2:9], v[192:199], v[46:49], v170, v170 op_sel_hi:[0,0,0]
	v_mfma_scale_f32_16x16x128_f8f6f4 v[42:45], v[10:17], v[192:199], v[42:45], v170, v170 op_sel_hi:[0,0,0]
	v_mfma_scale_f32_16x16x128_f8f6f4 v[30:33], v[2:9], v[200:207], v[30:33], v170, v170 op_sel_hi:[0,0,0]
	v_mfma_scale_f32_16x16x128_f8f6f4 v[26:29], v[10:17], v[200:207], v[26:29], v170, v170 op_sel_hi:[0,0,0]
	s_setprio 0
	s_barrier
	s_add_u32 s0, s52, 0x44080
	s_addc_u32 s1, s53, 0
	s_add_i32 s10, s11, s60
	v_lshl_add_u64 v[2:3], s[0:1], 0, v[150:151]
	s_mov_b32 m0, s10
	s_nop 0
	global_load_lds_dwordx4 v[2:3], off
	v_lshl_add_u64 v[2:3], s[0:1], 0, v[146:147]
	s_add_i32 m0, s10, 0x2000
	s_nop 0
	global_load_lds_dwordx4 v[2:3], off
	s_waitcnt vmcnt(6)
	s_barrier
	s_setprio 1
	v_mfma_scale_f32_16x16x128_f8f6f4 v[70:73], v[208:215], v[174:181], v[70:73], v170, v170 op_sel_hi:[0,0,0]
	s_add_i32 s79, s79, 2
	s_add_u32 s77, s77, 0x100
	s_addc_u32 s78, s78, 0
	s_cmp_gt_u32 s79, 13
	s_mov_b64 s[50:51], s[46:47]
	v_mfma_scale_f32_16x16x128_f8f6f4 v[66:69], v[216:223], v[174:181], v[66:69], v170, v170 op_sel_hi:[0,0,0]
	v_mfma_scale_f32_16x16x128_f8f6f4 v[54:57], v[208:215], v[182:189], v[54:57], v170, v170 op_sel_hi:[0,0,0]
	v_mfma_scale_f32_16x16x128_f8f6f4 v[50:53], v[216:223], v[182:189], v[50:53], v170, v170 op_sel_hi:[0,0,0]
	v_mfma_scale_f32_16x16x128_f8f6f4 v[38:41], v[208:215], v[192:199], v[38:41], v170, v170 op_sel_hi:[0,0,0]
	v_mfma_scale_f32_16x16x128_f8f6f4 v[34:37], v[216:223], v[192:199], v[34:37], v170, v170 op_sel_hi:[0,0,0]
	v_mfma_scale_f32_16x16x128_f8f6f4 v[22:25], v[208:215], v[200:207], v[22:25], v170, v170 op_sel_hi:[0,0,0]
	v_mfma_scale_f32_16x16x128_f8f6f4 v[18:21], v[216:223], v[200:207], v[18:21], v170, v170 op_sel_hi:[0,0,0]
	s_setprio 0
	s_cbranch_scc1 .Lkdone_p1b
	s_barrier
	s_branch .LBB0_737

; #define G_STAGE(bufoff, gbase, voff) do { _Pragma("unroll") for (int _i = 0; _i < 2; ++_i) \
;         __builtin_amdgcn_global_load_lds((const unsigned*)((const char*)(gbase) + (voff)[_i]), (LAS unsigned*)(lds + (bufoff) + ldsw + _i * 8192), 16, 0, 0); } while (0)
; #define G_WAIT_L(n) asm volatile("s_waitcnt lgkmcnt(" #n ")" ::: "memory")
; #define G_BAR __builtin_amdgcn_s_barrier()
; #define G_SCHED __builtin_amdgcn_sched_barrier(0)
; template <int MODE  , class Epi, class Sched>
; __device__ __forceinline__ void gemm_phase(LAS unsigned char* lds, const GemmDesc g, const Sched& S, const Epi& E) {
;     ...
;             G_LDB(B0, 0, 0); G_SCHED; G_LDA(At, 0, 0); G_STAGE(G_SA(1, 1), a1 + hstepA, voffA);
;             G_WAIT_L(8); G_BAR; G_WAIT_L(0); G_MMA(0, 0, At, B0); G_BAR; G_SCHED;
;             G_LDB(B1, 0, 1); G_STAGE(G_SB(0, 0), b2, voffB);
;             G_BAR; G_WAIT_L(0); G_MMA(0, 1, At, B1); G_BAR;
;             G_LDA(At, 0, 1); G_STAGE(G_SA(0, 0), a2, voffA);
;             G_BAR; G_WAIT_L(0); G_MMA(1, 0, At, B0); G_BAR; G_SCHED;
.Lnodb_sa:
.LBB0_815:
	v_add_u32_e32 v142, s58, v172
	ds_read_b128 v[130:133], v142
	ds_read_b128 v[134:137], v142 offset:1024
	ds_read_b128 v[138:141], v142 offset:2048
	ds_read_b128 v[142:145], v142 offset:3072
	s_add_u32 s44, s42, 0x100
	s_addc_u32 s45, s43, 0
	s_cmp_eq_u32 s68, 12
	s_cselect_b32 s49, s35, s45
	s_cselect_b32 s48, s34, s44
	s_cselect_b32 s47, s3, s67
	s_cselect_b32 s46, s2, s21
	v_lshl_add_u64 v[170:171], s[42:43], 0, v[154:155]
	s_add_i32 m0, s52, 0xc000
	ds_read_b128 v[158:161], v174
	ds_read_b128 v[162:165], v174 offset:1024
	ds_read_b128 v[166:169], v174 offset:2048
	ds_read_b128 v[176:179], v174 offset:3072
	ds_read_b128 v[180:183], v174 offset:4096
	ds_read_b128 v[184:187], v174 offset:5120
	ds_read_b128 v[192:195], v174 offset:6144
	ds_read_b128 v[196:199], v174 offset:7168
	global_load_lds_dwordx4 v[170:171], off
	v_lshl_add_u64 v[170:171], s[42:43], 0, v[156:157]
	s_add_i32 m0, s52, 0xe000
	s_nop 0
	global_load_lds_dwordx4 v[170:171], off
	s_waitcnt lgkmcnt(8)
	s_barrier
	s_waitcnt lgkmcnt(0)
	s_setprio 1
	s_waitcnt lgkmcnt(0)
	v_mfma_f32_16x16x32_bf16 v[126:129], v[130:133], v[158:161], v[126:129]
	v_mfma_f32_16x16x32_bf16 v[122:125], v[138:141], v[158:161], v[122:125]
	v_mfma_f32_16x16x32_bf16 v[118:121], v[130:133], v[166:169], v[118:121]
	v_mfma_f32_16x16x32_bf16 v[114:117], v[138:141], v[166:169], v[114:117]
	v_mfma_f32_16x16x32_bf16 v[110:113], v[130:133], v[180:183], v[110:113]
	v_mfma_f32_16x16x32_bf16 v[106:109], v[138:141], v[180:183], v[106:109]
	v_mfma_f32_16x16x32_bf16 v[102:105], v[130:133], v[192:195], v[102:105]
	v_mfma_f32_16x16x32_bf16 v[98:101], v[138:141], v[192:195], v[98:101]
	v_mfma_f32_16x16x32_bf16 v[126:129], v[134:137], v[162:165], v[126:129]
	v_mfma_f32_16x16x32_bf16 v[122:125], v[142:145], v[162:165], v[122:125]
	v_mfma_f32_16x16x32_bf16 v[118:121], v[134:137], v[176:179], v[118:121]
	v_mfma_f32_16x16x32_bf16 v[114:117], v[142:145], v[176:179], v[114:117]
	v_mfma_f32_16x16x32_bf16 v[110:113], v[134:137], v[184:187], v[110:113]
	v_mfma_f32_16x16x32_bf16 v[106:109], v[142:145], v[184:187], v[106:109]
	v_mfma_f32_16x16x32_bf16 v[102:105], v[134:137], v[196:199], v[102:105]
	v_mfma_f32_16x16x32_bf16 v[98:101], v[142:145], v[196:199], v[98:101]
	s_setprio 0
	s_barrier
	v_add_u32_e32 v170, s59, v172
	s_add_i32 s0, s58, s51
	ds_read_b128 v[200:203], v170
	ds_read_b128 v[204:207], v170 offset:1024
	ds_read_b128 v[208:211], v170 offset:2048
	ds_read_b128 v[212:215], v170 offset:3072
	v_lshl_add_u64 v[170:171], s[46:47], 0, v[148:149]
	s_mov_b32 m0, s0
	v_lshl_add_u64 v[188:189], s[46:47], 0, v[152:153]
	global_load_lds_dwordx4 v[170:171], off
	s_add_i32 m0, s0, 0x2000
	s_nop 0
	global_load_lds_dwordx4 v[188:189], off
	s_barrier
	s_waitcnt lgkmcnt(0)
	s_setprio 1
	s_waitcnt lgkmcnt(0)
	v_mfma_f32_16x16x32_bf16 v[94:97], v[200:203], v[158:161], v[94:97]
	v_mfma_f32_16x16x32_bf16 v[90:93], v[208:211], v[158:161], v[90:93]
	v_mfma_f32_16x16x32_bf16 v[86:89], v[200:203], v[166:169], v[86:89]
	v_mfma_f32_16x16x32_bf16 v[82:85], v[208:211], v[166:169], v[82:85]
	v_mfma_f32_16x16x32_bf16 v[78:81], v[200:203], v[180:183], v[78:81]
	v_mfma_f32_16x16x32_bf16 v[74:77], v[208:211], v[180:183], v[74:77]
	v_mfma_f32_16x16x32_bf16 v[70:73], v[200:203], v[192:195], v[70:73]
	v_mfma_f32_16x16x32_bf16 v[66:69], v[208:211], v[192:195], v[66:69]
	v_mfma_f32_16x16x32_bf16 v[94:97], v[204:207], v[162:165], v[94:97]
	v_mfma_f32_16x16x32_bf16 v[90:93], v[212:215], v[162:165], v[90:93]
	v_mfma_f32_16x16x32_bf16 v[86:89], v[204:207], v[176:179], v[86:89]
	v_mfma_f32_16x16x32_bf16 v[82:85], v[212:215], v[176:179], v[82:85]
	v_mfma_f32_16x16x32_bf16 v[78:81], v[204:207], v[184:187], v[78:81]
	v_mfma_f32_16x16x32_bf16 v[74:77], v[212:215], v[184:187], v[74:77]
	v_mfma_f32_16x16x32_bf16 v[70:73], v[204:207], v[196:199], v[70:73]
	v_mfma_f32_16x16x32_bf16 v[66:69], v[212:215], v[196:199], v[66:69]
	s_setprio 0
	s_mov_b32 m0, s52
	v_lshl_add_u64 v[216:217], s[48:49], 0, v[146:147]
	s_barrier
	ds_read_b128 v[158:161], v174 offset:16384
	ds_read_b128 v[162:165], v174 offset:17408
	ds_read_b128 v[166:169], v174 offset:18432
	ds_read_b128 v[176:179], v174 offset:19456
	ds_read_b128 v[180:183], v174 offset:20480
	ds_read_b128 v[184:187], v174 offset:21504
	ds_read_b128 v[192:195], v174 offset:22528
	ds_read_b128 v[196:199], v174 offset:23552
	global_load_lds_dwordx4 v[216:217], off
	v_lshl_add_u64 v[218:219], s[48:49], 0, v[150:151]
	s_mov_b32 m0, s53
	s_nop 0
	global_load_lds_dwordx4 v[218:219], off
	s_barrier
	s_waitcnt lgkmcnt(0)
	s_setprio 1
	s_waitcnt lgkmcnt(0)
	v_mfma_f32_16x16x32_bf16 v[62:65], v[130:133], v[158:161], v[62:65]
	v_mfma_f32_16x16x32_bf16 v[58:61], v[138:141], v[158:161], v[58:61]
	v_mfma_f32_16x16x32_bf16 v[54:57], v[130:133], v[166:169], v[54:57]
	v_mfma_f32_16x16x32_bf16 v[50:53], v[138:141], v[166:169], v[50:53]
	v_mfma_f32_16x16x32_bf16 v[46:49], v[130:133], v[180:183], v[46:49]
	v_mfma_f32_16x16x32_bf16 v[42:45], v[138:141], v[180:183], v[42:45]
	v_mfma_f32_16x16x32_bf16 v[38:41], v[130:133], v[192:195], v[38:41]
	v_mfma_f32_16x16x32_bf16 v[34:37], v[138:141], v[192:195], v[34:37]
	v_mfma_f32_16x16x32_bf16 v[62:65], v[134:137], v[162:165], v[62:65]
	v_mfma_f32_16x16x32_bf16 v[58:61], v[142:145], v[162:165], v[58:61]
	v_mfma_f32_16x16x32_bf16 v[54:57], v[134:137], v[176:179], v[54:57]
	v_mfma_f32_16x16x32_bf16 v[50:53], v[142:145], v[176:179], v[50:53]
	v_mfma_f32_16x16x32_bf16 v[46:49], v[134:137], v[184:187], v[46:49]
	v_mfma_f32_16x16x32_bf16 v[42:45], v[142:145], v[184:187], v[42:45]
	v_mfma_f32_16x16x32_bf16 v[38:41], v[134:137], v[196:199], v[38:41]
	v_mfma_f32_16x16x32_bf16 v[34:37], v[142:145], v[196:199], v[34:37]
	s_setprio 0
	s_barrier
; #define G_STAGE(bufoff, gbase, voff) do { _Pragma("unroll") for (int _i = 0; _i < 2; ++_i) \
;         __builtin_amdgcn_global_load_lds((const unsigned*)((const char*)(gbase) + (voff)[_i]), (LAS unsigned*)(lds + (bufoff) + ldsw + _i * 8192), 16, 0, 0); } while (0)
; #define G_WAIT_V(n) asm volatile("s_waitcnt vmcnt(" #n ")" ::: "memory")
; #define G_WAIT_L(n) asm volatile("s_waitcnt lgkmcnt(" #n ")" ::: "memory")
; #define G_BAR __builtin_amdgcn_s_barrier()
; #define G_SCHED __builtin_amdgcn_sched_barrier(0)
; template <int MODE  , class Epi, class Sched>
; __device__ __forceinline__ void gemm_phase(LAS unsigned char* lds, const GemmDesc g, const Sched& S, const Epi& E) {
;     ...
;             G_STAGE(G_SB(0, 1), b2 + hstepB, voffB);
;             G_WAIT_V(6); G_BAR; G_MMA(1, 1, At, B1); G_BAR;
;             G_LDB(B0, 1, 0); G_SCHED; G_LDA(At, 1, 0); G_STAGE(G_SA(0, 1), a2 + hstepA, voffA);
;             G_WAIT_L(8); G_BAR; G_WAIT_L(0); G_MMA(0, 0, At, B0); G_BAR; G_SCHED;
;             G_LDB(B1, 1, 1); G_STAGE(G_SB(1, 0), b3, voffB);
	s_add_u32 s0, s46, 0x84000
	s_addc_u32 s1, s47, 0
	s_add_i32 s10, s59, s51
	v_lshl_add_u64 v[130:131], s[0:1], 0, v[148:149]
	s_mov_b32 m0, s10
	s_nop 0
	global_load_lds_dwordx4 v[130:131], off
	v_lshl_add_u64 v[130:131], s[0:1], 0, v[152:153]
	s_add_i32 m0, s10, 0x2000
	s_nop 0
	global_load_lds_dwordx4 v[130:131], off
	s_waitcnt vmcnt(6)
	s_barrier
	s_setprio 1
	v_mfma_f32_16x16x32_bf16 v[30:33], v[200:203], v[158:161], v[30:33]
	v_mfma_f32_16x16x32_bf16 v[26:29], v[208:211], v[158:161], v[26:29]
	v_mfma_f32_16x16x32_bf16 v[22:25], v[200:203], v[166:169], v[22:25]
	v_mfma_f32_16x16x32_bf16 v[18:21], v[208:211], v[166:169], v[18:21]
	v_mfma_f32_16x16x32_bf16 v[14:17], v[200:203], v[180:183], v[14:17]
	v_mfma_f32_16x16x32_bf16 v[10:13], v[208:211], v[180:183], v[10:13]
	v_mfma_f32_16x16x32_bf16 v[6:9], v[200:203], v[192:195], v[6:9]
	v_mfma_f32_16x16x32_bf16 v[2:5], v[208:211], v[192:195], v[2:5]
	v_mfma_f32_16x16x32_bf16 v[30:33], v[204:207], v[162:165], v[30:33]
	v_mfma_f32_16x16x32_bf16 v[26:29], v[212:215], v[162:165], v[26:29]
	v_mfma_f32_16x16x32_bf16 v[22:25], v[204:207], v[176:179], v[22:25]
	v_mfma_f32_16x16x32_bf16 v[18:21], v[212:215], v[176:179], v[18:21]
	v_mfma_f32_16x16x32_bf16 v[14:17], v[204:207], v[184:187], v[14:17]
	v_mfma_f32_16x16x32_bf16 v[10:13], v[212:215], v[184:187], v[10:13]
	v_mfma_f32_16x16x32_bf16 v[6:9], v[204:207], v[196:199], v[6:9]
	v_mfma_f32_16x16x32_bf16 v[2:5], v[212:215], v[196:199], v[2:5]
	s_setprio 0
	s_add_i32 s10, 0, 0x18000
	v_add_u32_e32 v142, s10, v172
	s_barrier
	ds_read_b128 v[130:133], v142
	ds_read_b128 v[134:137], v142 offset:1024
	ds_read_b128 v[138:141], v142 offset:2048
	ds_read_b128 v[142:145], v142 offset:3072
	s_add_u32 s0, s48, 0x84000
	s_addc_u32 s1, s49, 0
	s_mov_b32 m0, s54
	v_lshl_add_u64 v[200:201], s[0:1], 0, v[146:147]
	ds_read_b128 v[158:161], v174 offset:32768
	ds_read_b128 v[162:165], v174 offset:33792
	ds_read_b128 v[166:169], v174 offset:34816
	ds_read_b128 v[176:179], v174 offset:35840
	ds_read_b128 v[180:183], v174 offset:36864
	ds_read_b128 v[184:187], v174 offset:37888
	ds_read_b128 v[192:195], v174 offset:38912
	ds_read_b128 v[196:199], v174 offset:39936
	global_load_lds_dwordx4 v[200:201], off
	v_lshl_add_u64 v[200:201], s[0:1], 0, v[150:151]
	s_mov_b32 m0, s55
	s_nop 0
	global_load_lds_dwordx4 v[200:201], off
	s_waitcnt lgkmcnt(8)
	s_barrier
	s_waitcnt lgkmcnt(0)
	s_setprio 1
	s_waitcnt lgkmcnt(0)
	v_mfma_f32_16x16x32_bf16 v[126:129], v[130:133], v[158:161], v[126:129]
	v_mfma_f32_16x16x32_bf16 v[122:125], v[138:141], v[158:161], v[122:125]
	v_mfma_f32_16x16x32_bf16 v[118:121], v[130:133], v[166:169], v[118:121]
	v_mfma_f32_16x16x32_bf16 v[114:117], v[138:141], v[166:169], v[114:117]
	v_mfma_f32_16x16x32_bf16 v[110:113], v[130:133], v[180:183], v[110:113]
	v_mfma_f32_16x16x32_bf16 v[106:109], v[138:141], v[180:183], v[106:109]
	v_mfma_f32_16x16x32_bf16 v[102:105], v[130:133], v[192:195], v[102:105]
	v_mfma_f32_16x16x32_bf16 v[98:101], v[138:141], v[192:195], v[98:101]
	v_mfma_f32_16x16x32_bf16 v[126:129], v[134:137], v[162:165], v[126:129]
	v_mfma_f32_16x16x32_bf16 v[122:125], v[142:145], v[162:165], v[122:125]
	v_mfma_f32_16x16x32_bf16 v[118:121], v[134:137], v[176:179], v[118:121]
	v_mfma_f32_16x16x32_bf16 v[114:117], v[142:145], v[176:179], v[114:117]
	v_mfma_f32_16x16x32_bf16 v[110:113], v[134:137], v[184:187], v[110:113]
	v_mfma_f32_16x16x32_bf16 v[106:109], v[142:145], v[184:187], v[106:109]
	v_mfma_f32_16x16x32_bf16 v[102:105], v[134:137], v[196:199], v[102:105]
	v_mfma_f32_16x16x32_bf16 v[98:101], v[142:145], v[196:199], v[98:101]
	s_setprio 0
	s_barrier
	s_add_i32 s11, 0, 0x1c000
	s_add_i32 s0, s10, s51
	v_add_u32_e32 v175, s11, v172
	v_lshl_add_u64 v[170:171], v[170:171], 0, s[18:19]
	s_mov_b32 m0, s0
	ds_read_b128 v[200:203], v175
	ds_read_b128 v[204:207], v175 offset:1024
	ds_read_b128 v[208:211], v175 offset:2048
	ds_read_b128 v[212:215], v175 offset:3072
	global_load_lds_dwordx4 v[170:171], off
	v_lshl_add_u64 v[170:171], v[188:189], 0, s[18:19]
	s_add_i32 m0, s0, 0x2000
	s_nop 0
	global_load_lds_dwordx4 v[170:171], off
	s_barrier
; #define G_STAGE(bufoff, gbase, voff) do { _Pragma("unroll") for (int _i = 0; _i < 2; ++_i) \
;         __builtin_amdgcn_global_load_lds((const unsigned*)((const char*)(gbase) + (voff)[_i]), (LAS unsigned*)(lds + (bufoff) + ldsw + _i * 8192), 16, 0, 0); } while (0)
; #define G_WAIT_V(n) asm volatile("s_waitcnt vmcnt(" #n ")" ::: "memory")
; #define G_WAIT_L(n) asm volatile("s_waitcnt lgkmcnt(" #n ")" ::: "memory")
; #define G_BAR __builtin_amdgcn_s_barrier()
; #define G_SCHED __builtin_amdgcn_sched_barrier(0)
; template <int MODE  , class Epi, class Sched>
; __device__ __forceinline__ void gemm_phase(LAS unsigned char* lds, const GemmDesc g, const Sched& S, const Epi& E) {
;     ...
;             G_LDB(B1, 1, 1); G_STAGE(G_SB(1, 0), b3, voffB);
;             G_BAR; G_WAIT_L(0); G_MMA(0, 1, At, B1); G_BAR;
;             G_LDA(At, 1, 1); G_STAGE(G_SA(1, 0), a3, voffA);
;             G_BAR; G_WAIT_L(0); G_MMA(1, 0, At, B0); G_BAR; G_SCHED;
;             G_STAGE(G_SB(1, 1), b3 + hstepB, voffB);
;             G_WAIT_V(6); G_BAR; G_MMA(1, 1, At, B1); G_BAR;
	s_waitcnt lgkmcnt(0)
	s_setprio 1
	s_waitcnt lgkmcnt(0)
	v_mfma_f32_16x16x32_bf16 v[94:97], v[200:203], v[158:161], v[94:97]
	v_mfma_f32_16x16x32_bf16 v[90:93], v[208:211], v[158:161], v[90:93]
	v_mfma_f32_16x16x32_bf16 v[86:89], v[200:203], v[166:169], v[86:89]
	v_mfma_f32_16x16x32_bf16 v[82:85], v[208:211], v[166:169], v[82:85]
	v_mfma_f32_16x16x32_bf16 v[78:81], v[200:203], v[180:183], v[78:81]
	v_mfma_f32_16x16x32_bf16 v[74:77], v[208:211], v[180:183], v[74:77]
	v_mfma_f32_16x16x32_bf16 v[70:73], v[200:203], v[192:195], v[70:73]
	v_mfma_f32_16x16x32_bf16 v[66:69], v[208:211], v[192:195], v[66:69]
	v_mfma_f32_16x16x32_bf16 v[94:97], v[204:207], v[162:165], v[94:97]
	v_mfma_f32_16x16x32_bf16 v[90:93], v[212:215], v[162:165], v[90:93]
	v_mfma_f32_16x16x32_bf16 v[86:89], v[204:207], v[176:179], v[86:89]
	v_mfma_f32_16x16x32_bf16 v[82:85], v[212:215], v[176:179], v[82:85]
	v_mfma_f32_16x16x32_bf16 v[78:81], v[204:207], v[184:187], v[78:81]
	v_mfma_f32_16x16x32_bf16 v[74:77], v[212:215], v[184:187], v[74:77]
	v_mfma_f32_16x16x32_bf16 v[70:73], v[204:207], v[196:199], v[70:73]
	v_mfma_f32_16x16x32_bf16 v[66:69], v[212:215], v[196:199], v[66:69]
	s_setprio 0
	s_mov_b32 m0, s56
	v_lshl_add_u64 v[170:171], v[216:217], 0, s[18:19]
	s_barrier
	ds_read_b128 v[158:161], v174 offset:49152
	ds_read_b128 v[162:165], v174 offset:50176
	ds_read_b128 v[166:169], v174 offset:51200
	ds_read_b128 v[176:179], v174 offset:52224
	ds_read_b128 v[180:183], v174 offset:53248
	ds_read_b128 v[184:187], v174 offset:54272
	ds_read_b128 v[192:195], v174 offset:55296
	ds_read_b128 v[196:199], v174 offset:56320
	global_load_lds_dwordx4 v[170:171], off
	v_lshl_add_u64 v[170:171], v[218:219], 0, s[18:19]
	s_mov_b32 m0, s57
	s_nop 0
	global_load_lds_dwordx4 v[170:171], off
	s_barrier
	s_waitcnt lgkmcnt(0)
	s_setprio 1
	s_waitcnt lgkmcnt(0)
	v_mfma_f32_16x16x32_bf16 v[62:65], v[130:133], v[158:161], v[62:65]
	v_mfma_f32_16x16x32_bf16 v[58:61], v[138:141], v[158:161], v[58:61]
	v_mfma_f32_16x16x32_bf16 v[54:57], v[130:133], v[166:169], v[54:57]
	v_mfma_f32_16x16x32_bf16 v[50:53], v[138:141], v[166:169], v[50:53]
	v_mfma_f32_16x16x32_bf16 v[46:49], v[130:133], v[180:183], v[46:49]
	v_mfma_f32_16x16x32_bf16 v[42:45], v[138:141], v[180:183], v[42:45]
	v_mfma_f32_16x16x32_bf16 v[38:41], v[130:133], v[192:195], v[38:41]
	v_mfma_f32_16x16x32_bf16 v[34:37], v[138:141], v[192:195], v[34:37]
	v_mfma_f32_16x16x32_bf16 v[62:65], v[134:137], v[162:165], v[62:65]
	v_mfma_f32_16x16x32_bf16 v[58:61], v[142:145], v[162:165], v[58:61]
	v_mfma_f32_16x16x32_bf16 v[54:57], v[134:137], v[176:179], v[54:57]
	v_mfma_f32_16x16x32_bf16 v[50:53], v[142:145], v[176:179], v[50:53]
	v_mfma_f32_16x16x32_bf16 v[46:49], v[134:137], v[184:187], v[46:49]
	v_mfma_f32_16x16x32_bf16 v[42:45], v[142:145], v[184:187], v[42:45]
	v_mfma_f32_16x16x32_bf16 v[38:41], v[134:137], v[196:199], v[38:41]
	v_mfma_f32_16x16x32_bf16 v[34:37], v[142:145], v[196:199], v[34:37]
	s_setprio 0
	s_barrier
	s_add_u32 s0, s46, 0x84080
	s_addc_u32 s1, s47, 0
	s_add_i32 s10, s11, s51
	v_lshl_add_u64 v[130:131], s[0:1], 0, v[148:149]
	s_mov_b32 m0, s10
	s_nop 0
	global_load_lds_dwordx4 v[130:131], off
	v_lshl_add_u64 v[130:131], s[0:1], 0, v[152:153]
	s_add_i32 m0, s10, 0x2000
	s_nop 0
	global_load_lds_dwordx4 v[130:131], off
	s_waitcnt vmcnt(6)
	s_barrier
	s_setprio 1
	v_mfma_f32_16x16x32_bf16 v[30:33], v[200:203], v[158:161], v[30:33]
	s_add_i32 s68, s68, 2
	s_add_u32 s21, s21, 0x100
	s_addc_u32 s67, s67, 0
	s_cmp_gt_u32 s68, 13
	s_mov_b64 s[42:43], s[44:45]
	v_mfma_f32_16x16x32_bf16 v[26:29], v[208:211], v[158:161], v[26:29]
	v_mfma_f32_16x16x32_bf16 v[22:25], v[200:203], v[166:169], v[22:25]
	v_mfma_f32_16x16x32_bf16 v[18:21], v[208:211], v[166:169], v[18:21]
	v_mfma_f32_16x16x32_bf16 v[14:17], v[200:203], v[180:183], v[14:17]
	v_mfma_f32_16x16x32_bf16 v[10:13], v[208:211], v[180:183], v[10:13]
	v_mfma_f32_16x16x32_bf16 v[6:9], v[200:203], v[192:195], v[6:9]
	v_mfma_f32_16x16x32_bf16 v[2:5], v[208:211], v[192:195], v[2:5]
	v_mfma_f32_16x16x32_bf16 v[30:33], v[204:207], v[162:165], v[30:33]
	v_mfma_f32_16x16x32_bf16 v[26:29], v[212:215], v[162:165], v[26:29]
	v_mfma_f32_16x16x32_bf16 v[22:25], v[204:207], v[176:179], v[22:25]
	v_mfma_f32_16x16x32_bf16 v[18:21], v[212:215], v[176:179], v[18:21]
	v_mfma_f32_16x16x32_bf16 v[14:17], v[204:207], v[184:187], v[14:17]
	v_mfma_f32_16x16x32_bf16 v[10:13], v[212:215], v[184:187], v[10:13]
	v_mfma_f32_16x16x32_bf16 v[6:9], v[204:207], v[196:199], v[6:9]
	v_mfma_f32_16x16x32_bf16 v[2:5], v[212:215], v[196:199], v[2:5]
	s_setprio 0
	s_cbranch_scc1 .Lkdone_sa
	s_barrier
	s_branch .LBB0_815

; #define G_STAGE(bufoff, gbase, voff) do { _Pragma("unroll") for (int _i = 0; _i < 2; ++_i) \
;         __builtin_amdgcn_global_load_lds((const unsigned*)((const char*)(gbase) + (voff)[_i]), (LAS unsigned*)(lds + (bufoff) + ldsw + _i * 8192), 16, 0, 0); } while (0)
; #define G_WAIT_L(n) asm volatile("s_waitcnt lgkmcnt(" #n ")" ::: "memory")
; #define G_BAR __builtin_amdgcn_s_barrier()
; #define G_SCHED __builtin_amdgcn_sched_barrier(0)
; template <int MODE  , class Epi, class Sched>
; __device__ __forceinline__ void gemm_phase(LAS unsigned char* lds, const GemmDesc g, const Sched& S, const Epi& E) {
;     ...
;             G_LDB(B0, 0, 0); G_SCHED; G_LDA(At, 0, 0); G_STAGE(G_SA(1, 1), a1 + hstepA, voffA);
;             G_WAIT_L(8); G_BAR; G_WAIT_L(0); G_MMA(0, 0, At, B0); G_BAR; G_SCHED;
;             G_LDB(B1, 0, 1); G_STAGE(G_SB(0, 0), b2, voffB);
;             G_BAR; G_WAIT_L(0); G_MMA(0, 1, At, B1); G_BAR;
;             G_LDA(At, 0, 1); G_STAGE(G_SA(0, 0), a2, voffA);
;             G_BAR; G_WAIT_L(0); G_MMA(1, 0, At, B0); G_BAR; G_SCHED;
.Lnodb_sb:
.LBB0_897:
	v_add_u32_e32 v142, s57, v174
	ds_read_b128 v[130:133], v142
	ds_read_b128 v[134:137], v142 offset:1024
	ds_read_b128 v[138:141], v142 offset:2048
	ds_read_b128 v[142:145], v142 offset:3072
	s_add_u32 s42, s40, 0x100
	s_addc_u32 s43, s41, 0
	s_cmp_eq_u32 s71, 12
	s_cselect_b32 s47, s21, s43
	s_cselect_b32 s46, s20, s42
	s_cselect_b32 s45, s3, s70
	s_cselect_b32 s44, s2, s19
	v_lshl_add_u64 v[196:197], s[40:41], 0, v[154:155]
	s_add_i32 m0, s50, 0xc000
	ds_read_b128 v[158:161], v176
	ds_read_b128 v[162:165], v176 offset:1024
	ds_read_b128 v[166:169], v176 offset:2048
	ds_read_b128 v[170:173], v176 offset:3072
	ds_read_b128 v[178:181], v176 offset:4096
	ds_read_b128 v[182:185], v176 offset:5120
	ds_read_b128 v[186:189], v176 offset:6144
	ds_read_b128 v[192:195], v176 offset:7168
	global_load_lds_dwordx4 v[196:197], off
	v_lshl_add_u64 v[196:197], s[40:41], 0, v[156:157]
	s_add_i32 m0, s50, 0xe000
	s_nop 0
	global_load_lds_dwordx4 v[196:197], off
	s_waitcnt lgkmcnt(8)
	s_barrier
	s_waitcnt lgkmcnt(0)
	s_setprio 1
	s_waitcnt lgkmcnt(0)
	v_mfma_f32_16x16x32_bf16 v[126:129], v[130:133], v[158:161], v[126:129]
	v_mfma_f32_16x16x32_bf16 v[122:125], v[138:141], v[158:161], v[122:125]
	v_mfma_f32_16x16x32_bf16 v[118:121], v[130:133], v[166:169], v[118:121]
	v_mfma_f32_16x16x32_bf16 v[114:117], v[138:141], v[166:169], v[114:117]
	v_mfma_f32_16x16x32_bf16 v[110:113], v[130:133], v[178:181], v[110:113]
	v_mfma_f32_16x16x32_bf16 v[106:109], v[138:141], v[178:181], v[106:109]
	v_mfma_f32_16x16x32_bf16 v[102:105], v[130:133], v[186:189], v[102:105]
	v_mfma_f32_16x16x32_bf16 v[98:101], v[138:141], v[186:189], v[98:101]
	v_mfma_f32_16x16x32_bf16 v[126:129], v[134:137], v[162:165], v[126:129]
	v_mfma_f32_16x16x32_bf16 v[122:125], v[142:145], v[162:165], v[122:125]
	v_mfma_f32_16x16x32_bf16 v[118:121], v[134:137], v[170:173], v[118:121]
	v_mfma_f32_16x16x32_bf16 v[114:117], v[142:145], v[170:173], v[114:117]
	v_mfma_f32_16x16x32_bf16 v[110:113], v[134:137], v[182:185], v[110:113]
	v_mfma_f32_16x16x32_bf16 v[106:109], v[142:145], v[182:185], v[106:109]
	v_mfma_f32_16x16x32_bf16 v[102:105], v[134:137], v[192:195], v[102:105]
	v_mfma_f32_16x16x32_bf16 v[98:101], v[142:145], v[192:195], v[98:101]
	s_setprio 0
	s_barrier
	s_add_i32 s0, s57, s49
	v_add_u32_e32 v177, s58, v174
	v_lshl_add_u64 v[212:213], s[44:45], 0, v[148:149]
	s_mov_b32 m0, s0
	ds_read_b128 v[196:199], v177
	ds_read_b128 v[200:203], v177 offset:1024
	ds_read_b128 v[204:207], v177 offset:2048
	ds_read_b128 v[208:211], v177 offset:3072
	global_load_lds_dwordx4 v[212:213], off
	v_lshl_add_u64 v[214:215], s[44:45], 0, v[152:153]
	s_add_i32 m0, s0, 0x2000
	s_nop 0
	global_load_lds_dwordx4 v[214:215], off
	s_barrier
	s_waitcnt lgkmcnt(0)
	s_setprio 1
	s_waitcnt lgkmcnt(0)
	v_mfma_f32_16x16x32_bf16 v[94:97], v[196:199], v[158:161], v[94:97]
	v_mfma_f32_16x16x32_bf16 v[90:93], v[204:207], v[158:161], v[90:93]
	v_mfma_f32_16x16x32_bf16 v[86:89], v[196:199], v[166:169], v[86:89]
	v_mfma_f32_16x16x32_bf16 v[82:85], v[204:207], v[166:169], v[82:85]
	v_mfma_f32_16x16x32_bf16 v[78:81], v[196:199], v[178:181], v[78:81]
	v_mfma_f32_16x16x32_bf16 v[74:77], v[204:207], v[178:181], v[74:77]
	v_mfma_f32_16x16x32_bf16 v[70:73], v[196:199], v[186:189], v[70:73]
	v_mfma_f32_16x16x32_bf16 v[66:69], v[204:207], v[186:189], v[66:69]
	v_mfma_f32_16x16x32_bf16 v[94:97], v[200:203], v[162:165], v[94:97]
	v_mfma_f32_16x16x32_bf16 v[90:93], v[208:211], v[162:165], v[90:93]
	v_mfma_f32_16x16x32_bf16 v[86:89], v[200:203], v[170:173], v[86:89]
	v_mfma_f32_16x16x32_bf16 v[82:85], v[208:211], v[170:173], v[82:85]
	v_mfma_f32_16x16x32_bf16 v[78:81], v[200:203], v[182:185], v[78:81]
	v_mfma_f32_16x16x32_bf16 v[74:77], v[208:211], v[182:185], v[74:77]
	v_mfma_f32_16x16x32_bf16 v[70:73], v[200:203], v[192:195], v[70:73]
	v_mfma_f32_16x16x32_bf16 v[66:69], v[208:211], v[192:195], v[66:69]
	s_setprio 0
	s_mov_b32 m0, s50
	v_lshl_add_u64 v[216:217], s[46:47], 0, v[146:147]
	s_barrier
	ds_read_b128 v[158:161], v176 offset:16384
	ds_read_b128 v[162:165], v176 offset:17408
	ds_read_b128 v[166:169], v176 offset:18432
	ds_read_b128 v[170:173], v176 offset:19456
	ds_read_b128 v[178:181], v176 offset:20480
	ds_read_b128 v[182:185], v176 offset:21504
	ds_read_b128 v[186:189], v176 offset:22528
	ds_read_b128 v[192:195], v176 offset:23552
	global_load_lds_dwordx4 v[216:217], off
	v_lshl_add_u64 v[218:219], s[46:47], 0, v[150:151]
	s_mov_b32 m0, s51
	s_nop 0
	global_load_lds_dwordx4 v[218:219], off
	s_barrier
	s_waitcnt lgkmcnt(0)
	s_setprio 1
	s_waitcnt lgkmcnt(0)
	v_mfma_f32_16x16x32_bf16 v[62:65], v[130:133], v[158:161], v[62:65]
	v_mfma_f32_16x16x32_bf16 v[58:61], v[138:141], v[158:161], v[58:61]
	v_mfma_f32_16x16x32_bf16 v[54:57], v[130:133], v[166:169], v[54:57]
	v_mfma_f32_16x16x32_bf16 v[50:53], v[138:141], v[166:169], v[50:53]
	v_mfma_f32_16x16x32_bf16 v[46:49], v[130:133], v[178:181], v[46:49]
	v_mfma_f32_16x16x32_bf16 v[42:45], v[138:141], v[178:181], v[42:45]
	v_mfma_f32_16x16x32_bf16 v[38:41], v[130:133], v[186:189], v[38:41]
	v_mfma_f32_16x16x32_bf16 v[34:37], v[138:141], v[186:189], v[34:37]
	v_mfma_f32_16x16x32_bf16 v[62:65], v[134:137], v[162:165], v[62:65]
	v_mfma_f32_16x16x32_bf16 v[58:61], v[142:145], v[162:165], v[58:61]
	v_mfma_f32_16x16x32_bf16 v[54:57], v[134:137], v[170:173], v[54:57]
	v_mfma_f32_16x16x32_bf16 v[50:53], v[142:145], v[170:173], v[50:53]
	v_mfma_f32_16x16x32_bf16 v[46:49], v[134:137], v[182:185], v[46:49]
	v_mfma_f32_16x16x32_bf16 v[42:45], v[142:145], v[182:185], v[42:45]
	v_mfma_f32_16x16x32_bf16 v[38:41], v[134:137], v[192:195], v[38:41]
	v_mfma_f32_16x16x32_bf16 v[34:37], v[142:145], v[192:195], v[34:37]
	s_setprio 0
	s_barrier
; #define G_STAGE(bufoff, gbase, voff) do { _Pragma("unroll") for (int _i = 0; _i < 2; ++_i) \
;         __builtin_amdgcn_global_load_lds((const unsigned*)((const char*)(gbase) + (voff)[_i]), (LAS unsigned*)(lds + (bufoff) + ldsw + _i * 8192), 16, 0, 0); } while (0)
; #define G_WAIT_V(n) asm volatile("s_waitcnt vmcnt(" #n ")" ::: "memory")
; #define G_WAIT_L(n) asm volatile("s_waitcnt lgkmcnt(" #n ")" ::: "memory")
; #define G_BAR __builtin_amdgcn_s_barrier()
; #define G_SCHED __builtin_amdgcn_sched_barrier(0)
; template <int MODE  , class Epi, class Sched>
; __device__ __forceinline__ void gemm_phase(LAS unsigned char* lds, const GemmDesc g, const Sched& S, const Epi& E) {
;     ...
;             G_STAGE(G_SB(0, 1), b2 + hstepB, voffB);
;             G_WAIT_V(6); G_BAR; G_MMA(1, 1, At, B1); G_BAR;
;             G_LDB(B0, 1, 0); G_SCHED; G_LDA(At, 1, 0); G_STAGE(G_SA(0, 1), a2 + hstepA, voffA);
;             G_WAIT_L(8); G_BAR; G_WAIT_L(0); G_MMA(0, 0, At, B0); G_BAR; G_SCHED;
;             G_LDB(B1, 1, 1); G_STAGE(G_SB(1, 0), b3, voffB);
	s_add_u32 s0, s44, 0x84000
	s_addc_u32 s1, s45, 0
	s_add_i32 s10, s58, s49
	v_lshl_add_u64 v[130:131], s[0:1], 0, v[148:149]
	s_mov_b32 m0, s10
	s_nop 0
	global_load_lds_dwordx4 v[130:131], off
	v_lshl_add_u64 v[130:131], s[0:1], 0, v[152:153]
	s_add_i32 m0, s10, 0x2000
	s_nop 0
	global_load_lds_dwordx4 v[130:131], off
	s_waitcnt vmcnt(6)
	s_barrier
	s_setprio 1
	v_mfma_f32_16x16x32_bf16 v[30:33], v[196:199], v[158:161], v[30:33]
	v_mfma_f32_16x16x32_bf16 v[26:29], v[204:207], v[158:161], v[26:29]
	v_mfma_f32_16x16x32_bf16 v[22:25], v[196:199], v[166:169], v[22:25]
	v_mfma_f32_16x16x32_bf16 v[18:21], v[204:207], v[166:169], v[18:21]
	v_mfma_f32_16x16x32_bf16 v[14:17], v[196:199], v[178:181], v[14:17]
	v_mfma_f32_16x16x32_bf16 v[10:13], v[204:207], v[178:181], v[10:13]
	v_mfma_f32_16x16x32_bf16 v[6:9], v[196:199], v[186:189], v[6:9]
	v_mfma_f32_16x16x32_bf16 v[2:5], v[204:207], v[186:189], v[2:5]
	v_mfma_f32_16x16x32_bf16 v[30:33], v[200:203], v[162:165], v[30:33]
	v_mfma_f32_16x16x32_bf16 v[26:29], v[208:211], v[162:165], v[26:29]
	v_mfma_f32_16x16x32_bf16 v[22:25], v[200:203], v[170:173], v[22:25]
	v_mfma_f32_16x16x32_bf16 v[18:21], v[208:211], v[170:173], v[18:21]
	v_mfma_f32_16x16x32_bf16 v[14:17], v[200:203], v[182:185], v[14:17]
	v_mfma_f32_16x16x32_bf16 v[10:13], v[208:211], v[182:185], v[10:13]
	v_mfma_f32_16x16x32_bf16 v[6:9], v[200:203], v[192:195], v[6:9]
	v_mfma_f32_16x16x32_bf16 v[2:5], v[208:211], v[192:195], v[2:5]
	s_setprio 0
	s_add_i32 s10, 0, 0x18000
	v_add_u32_e32 v142, s10, v174
	s_barrier
	ds_read_b128 v[130:133], v142
	ds_read_b128 v[134:137], v142 offset:1024
	ds_read_b128 v[138:141], v142 offset:2048
	ds_read_b128 v[142:145], v142 offset:3072
	s_add_u32 s0, s46, 0x84000
	s_addc_u32 s1, s47, 0
	s_mov_b32 m0, s52
	v_lshl_add_u64 v[196:197], s[0:1], 0, v[146:147]
	ds_read_b128 v[158:161], v176 offset:32768
	ds_read_b128 v[162:165], v176 offset:33792
	ds_read_b128 v[166:169], v176 offset:34816
	ds_read_b128 v[170:173], v176 offset:35840
	ds_read_b128 v[178:181], v176 offset:36864
	ds_read_b128 v[182:185], v176 offset:37888
	ds_read_b128 v[186:189], v176 offset:38912
	ds_read_b128 v[192:195], v176 offset:39936
	global_load_lds_dwordx4 v[196:197], off
	v_lshl_add_u64 v[196:197], s[0:1], 0, v[150:151]
	s_mov_b32 m0, s53
	s_nop 0
	global_load_lds_dwordx4 v[196:197], off
	s_waitcnt lgkmcnt(8)
	s_barrier
	s_waitcnt lgkmcnt(0)
	s_setprio 1
	s_waitcnt lgkmcnt(0)
	v_mfma_f32_16x16x32_bf16 v[126:129], v[130:133], v[158:161], v[126:129]
	v_mfma_f32_16x16x32_bf16 v[122:125], v[138:141], v[158:161], v[122:125]
	v_mfma_f32_16x16x32_bf16 v[118:121], v[130:133], v[166:169], v[118:121]
	v_mfma_f32_16x16x32_bf16 v[114:117], v[138:141], v[166:169], v[114:117]
	v_mfma_f32_16x16x32_bf16 v[110:113], v[130:133], v[178:181], v[110:113]
	v_mfma_f32_16x16x32_bf16 v[106:109], v[138:141], v[178:181], v[106:109]
	v_mfma_f32_16x16x32_bf16 v[102:105], v[130:133], v[186:189], v[102:105]
	v_mfma_f32_16x16x32_bf16 v[98:101], v[138:141], v[186:189], v[98:101]
	v_mfma_f32_16x16x32_bf16 v[126:129], v[134:137], v[162:165], v[126:129]
	v_mfma_f32_16x16x32_bf16 v[122:125], v[142:145], v[162:165], v[122:125]
	v_mfma_f32_16x16x32_bf16 v[118:121], v[134:137], v[170:173], v[118:121]
	v_mfma_f32_16x16x32_bf16 v[114:117], v[142:145], v[170:173], v[114:117]
	v_mfma_f32_16x16x32_bf16 v[110:113], v[134:137], v[182:185], v[110:113]
	v_mfma_f32_16x16x32_bf16 v[106:109], v[142:145], v[182:185], v[106:109]
	v_mfma_f32_16x16x32_bf16 v[102:105], v[134:137], v[192:195], v[102:105]
	v_mfma_f32_16x16x32_bf16 v[98:101], v[142:145], v[192:195], v[98:101]
	s_setprio 0
	s_barrier
	s_add_i32 s11, 0, 0x1c000
	s_add_i32 s0, s10, s49
	v_add_u32_e32 v177, s11, v174
	v_lshl_add_u64 v[212:213], v[212:213], 0, s[16:17]
	s_mov_b32 m0, s0
	ds_read_b128 v[196:199], v177
	ds_read_b128 v[200:203], v177 offset:1024
	ds_read_b128 v[204:207], v177 offset:2048
	ds_read_b128 v[208:211], v177 offset:3072
	global_load_lds_dwordx4 v[212:213], off
	v_lshl_add_u64 v[212:213], v[214:215], 0, s[16:17]
	s_add_i32 m0, s0, 0x2000
	s_nop 0
	global_load_lds_dwordx4 v[212:213], off
	s_barrier
; #define G_STAGE(bufoff, gbase, voff) do { _Pragma("unroll") for (int _i = 0; _i < 2; ++_i) \
;         __builtin_amdgcn_global_load_lds((const unsigned*)((const char*)(gbase) + (voff)[_i]), (LAS unsigned*)(lds + (bufoff) + ldsw + _i * 8192), 16, 0, 0); } while (0)
; #define G_WAIT_V(n) asm volatile("s_waitcnt vmcnt(" #n ")" ::: "memory")
; #define G_WAIT_L(n) asm volatile("s_waitcnt lgkmcnt(" #n ")" ::: "memory")
; #define G_BAR __builtin_amdgcn_s_barrier()
; #define G_SCHED __builtin_amdgcn_sched_barrier(0)
; template <int MODE  , class Epi, class Sched>
; __device__ __forceinline__ void gemm_phase(LAS unsigned char* lds, const GemmDesc g, const Sched& S, const Epi& E) {
;     ...
;             G_LDB(B1, 1, 1); G_STAGE(G_SB(1, 0), b3, voffB);
;             G_BAR; G_WAIT_L(0); G_MMA(0, 1, At, B1); G_BAR;
;             G_LDA(At, 1, 1); G_STAGE(G_SA(1, 0), a3, voffA);
;             G_BAR; G_WAIT_L(0); G_MMA(1, 0, At, B0); G_BAR; G_SCHED;
;             G_STAGE(G_SB(1, 1), b3 + hstepB, voffB);
;             G_WAIT_V(6); G_BAR; G_MMA(1, 1, At, B1); G_BAR;
	s_waitcnt lgkmcnt(0)
	s_setprio 1
	s_waitcnt lgkmcnt(0)
	v_mfma_f32_16x16x32_bf16 v[94:97], v[196:199], v[158:161], v[94:97]
	v_mfma_f32_16x16x32_bf16 v[90:93], v[204:207], v[158:161], v[90:93]
	v_mfma_f32_16x16x32_bf16 v[86:89], v[196:199], v[166:169], v[86:89]
	v_mfma_f32_16x16x32_bf16 v[82:85], v[204:207], v[166:169], v[82:85]
	v_mfma_f32_16x16x32_bf16 v[78:81], v[196:199], v[178:181], v[78:81]
	v_mfma_f32_16x16x32_bf16 v[74:77], v[204:207], v[178:181], v[74:77]
	v_mfma_f32_16x16x32_bf16 v[70:73], v[196:199], v[186:189], v[70:73]
	v_mfma_f32_16x16x32_bf16 v[66:69], v[204:207], v[186:189], v[66:69]
	v_mfma_f32_16x16x32_bf16 v[94:97], v[200:203], v[162:165], v[94:97]
	v_mfma_f32_16x16x32_bf16 v[90:93], v[208:211], v[162:165], v[90:93]
	v_mfma_f32_16x16x32_bf16 v[86:89], v[200:203], v[170:173], v[86:89]
	v_mfma_f32_16x16x32_bf16 v[82:85], v[208:211], v[170:173], v[82:85]
	v_mfma_f32_16x16x32_bf16 v[78:81], v[200:203], v[182:185], v[78:81]
	v_mfma_f32_16x16x32_bf16 v[74:77], v[208:211], v[182:185], v[74:77]
	v_mfma_f32_16x16x32_bf16 v[70:73], v[200:203], v[192:195], v[70:73]
	v_mfma_f32_16x16x32_bf16 v[66:69], v[208:211], v[192:195], v[66:69]
	s_setprio 0
	s_mov_b32 m0, s54
	v_lshl_add_u64 v[212:213], v[216:217], 0, s[16:17]
	s_barrier
	ds_read_b128 v[158:161], v176 offset:49152
	ds_read_b128 v[162:165], v176 offset:50176
	ds_read_b128 v[166:169], v176 offset:51200
	ds_read_b128 v[170:173], v176 offset:52224
	ds_read_b128 v[178:181], v176 offset:53248
	ds_read_b128 v[182:185], v176 offset:54272
	ds_read_b128 v[186:189], v176 offset:55296
	ds_read_b128 v[192:195], v176 offset:56320
	global_load_lds_dwordx4 v[212:213], off
	v_lshl_add_u64 v[212:213], v[218:219], 0, s[16:17]
	s_mov_b32 m0, s55
	s_nop 0
	global_load_lds_dwordx4 v[212:213], off
	s_barrier
	s_waitcnt lgkmcnt(0)
	s_setprio 1
	s_waitcnt lgkmcnt(0)
	v_mfma_f32_16x16x32_bf16 v[62:65], v[130:133], v[158:161], v[62:65]
	v_mfma_f32_16x16x32_bf16 v[58:61], v[138:141], v[158:161], v[58:61]
	v_mfma_f32_16x16x32_bf16 v[54:57], v[130:133], v[166:169], v[54:57]
	v_mfma_f32_16x16x32_bf16 v[50:53], v[138:141], v[166:169], v[50:53]
	v_mfma_f32_16x16x32_bf16 v[46:49], v[130:133], v[178:181], v[46:49]
	v_mfma_f32_16x16x32_bf16 v[42:45], v[138:141], v[178:181], v[42:45]
	v_mfma_f32_16x16x32_bf16 v[38:41], v[130:133], v[186:189], v[38:41]
	v_mfma_f32_16x16x32_bf16 v[34:37], v[138:141], v[186:189], v[34:37]
	v_mfma_f32_16x16x32_bf16 v[62:65], v[134:137], v[162:165], v[62:65]
	v_mfma_f32_16x16x32_bf16 v[58:61], v[142:145], v[162:165], v[58:61]
	v_mfma_f32_16x16x32_bf16 v[54:57], v[134:137], v[170:173], v[54:57]
	v_mfma_f32_16x16x32_bf16 v[50:53], v[142:145], v[170:173], v[50:53]
	v_mfma_f32_16x16x32_bf16 v[46:49], v[134:137], v[182:185], v[46:49]
	v_mfma_f32_16x16x32_bf16 v[42:45], v[142:145], v[182:185], v[42:45]
	v_mfma_f32_16x16x32_bf16 v[38:41], v[134:137], v[192:195], v[38:41]
	v_mfma_f32_16x16x32_bf16 v[34:37], v[142:145], v[192:195], v[34:37]
	s_setprio 0
	s_barrier
	s_add_u32 s0, s44, 0x84080
	s_addc_u32 s1, s45, 0
	s_add_i32 s10, s11, s49
	v_lshl_add_u64 v[130:131], s[0:1], 0, v[148:149]
	s_mov_b32 m0, s10
	s_nop 0
	global_load_lds_dwordx4 v[130:131], off
	v_lshl_add_u64 v[130:131], s[0:1], 0, v[152:153]
	s_add_i32 m0, s10, 0x2000
	s_nop 0
	global_load_lds_dwordx4 v[130:131], off
	s_waitcnt vmcnt(6)
	s_barrier
	s_setprio 1
	v_mfma_f32_16x16x32_bf16 v[30:33], v[196:199], v[158:161], v[30:33]
	s_add_i32 s71, s71, 2
	s_add_u32 s19, s19, 0x100
	s_addc_u32 s70, s70, 0
	s_cmp_gt_u32 s71, 13
	s_mov_b64 s[40:41], s[42:43]
	v_mfma_f32_16x16x32_bf16 v[26:29], v[204:207], v[158:161], v[26:29]
	v_mfma_f32_16x16x32_bf16 v[22:25], v[196:199], v[166:169], v[22:25]
	v_mfma_f32_16x16x32_bf16 v[18:21], v[204:207], v[166:169], v[18:21]
	v_mfma_f32_16x16x32_bf16 v[14:17], v[196:199], v[178:181], v[14:17]
	v_mfma_f32_16x16x32_bf16 v[10:13], v[204:207], v[178:181], v[10:13]
	v_mfma_f32_16x16x32_bf16 v[6:9], v[196:199], v[186:189], v[6:9]
	v_mfma_f32_16x16x32_bf16 v[2:5], v[204:207], v[186:189], v[2:5]
	v_mfma_f32_16x16x32_bf16 v[30:33], v[200:203], v[162:165], v[30:33]
	v_mfma_f32_16x16x32_bf16 v[26:29], v[208:211], v[162:165], v[26:29]
	v_mfma_f32_16x16x32_bf16 v[22:25], v[200:203], v[170:173], v[22:25]
	v_mfma_f32_16x16x32_bf16 v[18:21], v[208:211], v[170:173], v[18:21]
	v_mfma_f32_16x16x32_bf16 v[14:17], v[200:203], v[182:185], v[14:17]
	v_mfma_f32_16x16x32_bf16 v[10:13], v[208:211], v[182:185], v[10:13]
	v_mfma_f32_16x16x32_bf16 v[6:9], v[200:203], v[192:195], v[6:9]
	v_mfma_f32_16x16x32_bf16 v[2:5], v[208:211], v[192:195], v[2:5]
	s_setprio 0
	s_cbranch_scc1 .Lkdone_sb
	s_barrier
	s_branch .LBB0_897

; #define G_STAGE(bufoff, gbase, voff) do { _Pragma("unroll") for (int _i = 0; _i < 2; ++_i) \
;         __builtin_amdgcn_global_load_lds((const unsigned*)((const char*)(gbase) + (voff)[_i]), (LAS unsigned*)(lds + (bufoff) + ldsw + _i * 8192), 16, 0, 0); } while (0)
; #define G_WAIT_L(n) asm volatile("s_waitcnt lgkmcnt(" #n ")" ::: "memory")
; #define G_BAR __builtin_amdgcn_s_barrier()
; #define G_SCHED __builtin_amdgcn_sched_barrier(0)
; template <int MODE  , class Epi, class Sched>
; __device__ __forceinline__ void gemm_phase(LAS unsigned char* lds, const GemmDesc g, const Sched& S, const Epi& E) {
;     ...
;             G_LDB(B0, 0, 0); G_SCHED; G_LDA(At, 0, 0); G_STAGE(G_SA(1, 1), a1 + hstepA, voffA);
;             G_WAIT_L(8); G_BAR; G_WAIT_L(0); G_MMA(0, 0, At, B0); G_BAR; G_SCHED;
;             G_LDB(B1, 0, 1); G_STAGE(G_SB(0, 0), b2, voffB);
;             G_BAR; G_WAIT_L(0); G_MMA(0, 1, At, B1); G_BAR;
;             G_LDA(At, 0, 1); G_STAGE(G_SA(0, 0), a2, voffA);
;             G_BAR; G_WAIT_L(0); G_MMA(1, 0, At, B0); G_BAR; G_SCHED;
.Lnodb_sc:
.LBB0_987:
	v_add_u32_e32 v145, s50, v142
	ds_read_b128 v[146:149], v145
	ds_read_b128 v[150:153], v145 offset:1024
	ds_read_b128 v[154:157], v145 offset:2048
	ds_read_b128 v[158:161], v145 offset:3072
	s_add_u32 s34, s20, 0x100
	s_addc_u32 s35, s21, 0
	s_cmp_eq_u32 s60, 12
	s_cselect_b32 s43, s17, s35
	s_cselect_b32 s42, s16, s34
	s_cselect_b32 s41, s3, s59
	s_cselect_b32 s40, s2, s15
	v_lshl_add_u64 v[196:197], s[20:21], 0, v[138:139]
	s_add_i32 m0, s44, 0xc000
	ds_read_b128 v[162:165], v144
	ds_read_b128 v[166:169], v144 offset:1024
	ds_read_b128 v[170:173], v144 offset:2048
	ds_read_b128 v[174:177], v144 offset:3072
	ds_read_b128 v[178:181], v144 offset:4096
	ds_read_b128 v[182:185], v144 offset:5120
	ds_read_b128 v[186:189], v144 offset:6144
	ds_read_b128 v[192:195], v144 offset:7168
	global_load_lds_dwordx4 v[196:197], off
	v_lshl_add_u64 v[196:197], s[20:21], 0, v[140:141]
	s_add_i32 m0, s44, 0xe000
	s_nop 0
	global_load_lds_dwordx4 v[196:197], off
	s_waitcnt lgkmcnt(8)
	s_barrier
	s_waitcnt lgkmcnt(0)
	s_setprio 1
	s_waitcnt lgkmcnt(0)
	v_mfma_f32_16x16x32_bf16 v[126:129], v[146:149], v[162:165], v[126:129]
	v_mfma_f32_16x16x32_bf16 v[122:125], v[154:157], v[162:165], v[122:125]
	v_mfma_f32_16x16x32_bf16 v[118:121], v[146:149], v[170:173], v[118:121]
	v_mfma_f32_16x16x32_bf16 v[114:117], v[154:157], v[170:173], v[114:117]
	v_mfma_f32_16x16x32_bf16 v[110:113], v[146:149], v[178:181], v[110:113]
	v_mfma_f32_16x16x32_bf16 v[106:109], v[154:157], v[178:181], v[106:109]
	v_mfma_f32_16x16x32_bf16 v[102:105], v[146:149], v[186:189], v[102:105]
	v_mfma_f32_16x16x32_bf16 v[98:101], v[154:157], v[186:189], v[98:101]
	v_mfma_f32_16x16x32_bf16 v[126:129], v[150:153], v[166:169], v[126:129]
	v_mfma_f32_16x16x32_bf16 v[122:125], v[158:161], v[166:169], v[122:125]
	v_mfma_f32_16x16x32_bf16 v[118:121], v[150:153], v[174:177], v[118:121]
	v_mfma_f32_16x16x32_bf16 v[114:117], v[158:161], v[174:177], v[114:117]
	v_mfma_f32_16x16x32_bf16 v[110:113], v[150:153], v[182:185], v[110:113]
	v_mfma_f32_16x16x32_bf16 v[106:109], v[158:161], v[182:185], v[106:109]
	v_mfma_f32_16x16x32_bf16 v[102:105], v[150:153], v[192:195], v[102:105]
	v_mfma_f32_16x16x32_bf16 v[98:101], v[158:161], v[192:195], v[98:101]
	s_setprio 0
	s_barrier
	s_add_i32 s0, s50, s31
	v_add_u32_e32 v145, s51, v142
	v_lshl_add_u64 v[212:213], s[40:41], 0, v[132:133]
	s_mov_b32 m0, s0
	ds_read_b128 v[196:199], v145
	ds_read_b128 v[200:203], v145 offset:1024
	ds_read_b128 v[204:207], v145 offset:2048
	ds_read_b128 v[208:211], v145 offset:3072
	global_load_lds_dwordx4 v[212:213], off
	v_lshl_add_u64 v[214:215], s[40:41], 0, v[136:137]
	s_add_i32 m0, s0, 0x2000
	s_nop 0
	global_load_lds_dwordx4 v[214:215], off
	s_barrier
	s_waitcnt lgkmcnt(0)
	s_setprio 1
	s_waitcnt lgkmcnt(0)
	v_mfma_f32_16x16x32_bf16 v[94:97], v[196:199], v[162:165], v[94:97]
	v_mfma_f32_16x16x32_bf16 v[90:93], v[204:207], v[162:165], v[90:93]
	v_mfma_f32_16x16x32_bf16 v[86:89], v[196:199], v[170:173], v[86:89]
	v_mfma_f32_16x16x32_bf16 v[82:85], v[204:207], v[170:173], v[82:85]
	v_mfma_f32_16x16x32_bf16 v[78:81], v[196:199], v[178:181], v[78:81]
	v_mfma_f32_16x16x32_bf16 v[74:77], v[204:207], v[178:181], v[74:77]
	v_mfma_f32_16x16x32_bf16 v[70:73], v[196:199], v[186:189], v[70:73]
	v_mfma_f32_16x16x32_bf16 v[66:69], v[204:207], v[186:189], v[66:69]
	v_mfma_f32_16x16x32_bf16 v[94:97], v[200:203], v[166:169], v[94:97]
	v_mfma_f32_16x16x32_bf16 v[90:93], v[208:211], v[166:169], v[90:93]
	v_mfma_f32_16x16x32_bf16 v[86:89], v[200:203], v[174:177], v[86:89]
	v_mfma_f32_16x16x32_bf16 v[82:85], v[208:211], v[174:177], v[82:85]
	v_mfma_f32_16x16x32_bf16 v[78:81], v[200:203], v[182:185], v[78:81]
	v_mfma_f32_16x16x32_bf16 v[74:77], v[208:211], v[182:185], v[74:77]
	v_mfma_f32_16x16x32_bf16 v[70:73], v[200:203], v[192:195], v[70:73]
	v_mfma_f32_16x16x32_bf16 v[66:69], v[208:211], v[192:195], v[66:69]
	s_setprio 0
	s_mov_b32 m0, s44
	v_lshl_add_u64 v[216:217], s[42:43], 0, v[130:131]
	s_barrier
	ds_read_b128 v[162:165], v144 offset:16384
	ds_read_b128 v[166:169], v144 offset:17408
	ds_read_b128 v[170:173], v144 offset:18432
	ds_read_b128 v[174:177], v144 offset:19456
	ds_read_b128 v[178:181], v144 offset:20480
	ds_read_b128 v[182:185], v144 offset:21504
	ds_read_b128 v[186:189], v144 offset:22528
	ds_read_b128 v[192:195], v144 offset:23552
	global_load_lds_dwordx4 v[216:217], off
	v_lshl_add_u64 v[218:219], s[42:43], 0, v[134:135]
	s_mov_b32 m0, s45
	s_nop 0
	global_load_lds_dwordx4 v[218:219], off
	s_barrier
	s_waitcnt lgkmcnt(0)
	s_setprio 1
	s_waitcnt lgkmcnt(0)
	v_mfma_f32_16x16x32_bf16 v[62:65], v[146:149], v[162:165], v[62:65]
	v_mfma_f32_16x16x32_bf16 v[58:61], v[154:157], v[162:165], v[58:61]
	v_mfma_f32_16x16x32_bf16 v[54:57], v[146:149], v[170:173], v[54:57]
	v_mfma_f32_16x16x32_bf16 v[50:53], v[154:157], v[170:173], v[50:53]
	v_mfma_f32_16x16x32_bf16 v[46:49], v[146:149], v[178:181], v[46:49]
	v_mfma_f32_16x16x32_bf16 v[42:45], v[154:157], v[178:181], v[42:45]
	v_mfma_f32_16x16x32_bf16 v[38:41], v[146:149], v[186:189], v[38:41]
	v_mfma_f32_16x16x32_bf16 v[34:37], v[154:157], v[186:189], v[34:37]
	v_mfma_f32_16x16x32_bf16 v[62:65], v[150:153], v[166:169], v[62:65]
	v_mfma_f32_16x16x32_bf16 v[58:61], v[158:161], v[166:169], v[58:61]
	v_mfma_f32_16x16x32_bf16 v[54:57], v[150:153], v[174:177], v[54:57]
	v_mfma_f32_16x16x32_bf16 v[50:53], v[158:161], v[174:177], v[50:53]
	v_mfma_f32_16x16x32_bf16 v[46:49], v[150:153], v[182:185], v[46:49]
	v_mfma_f32_16x16x32_bf16 v[42:45], v[158:161], v[182:185], v[42:45]
	v_mfma_f32_16x16x32_bf16 v[38:41], v[150:153], v[192:195], v[38:41]
	v_mfma_f32_16x16x32_bf16 v[34:37], v[158:161], v[192:195], v[34:37]
	s_setprio 0
	s_barrier
; #define G_STAGE(bufoff, gbase, voff) do { _Pragma("unroll") for (int _i = 0; _i < 2; ++_i) \
;         __builtin_amdgcn_global_load_lds((const unsigned*)((const char*)(gbase) + (voff)[_i]), (LAS unsigned*)(lds + (bufoff) + ldsw + _i * 8192), 16, 0, 0); } while (0)
; #define G_WAIT_V(n) asm volatile("s_waitcnt vmcnt(" #n ")" ::: "memory")
; #define G_WAIT_L(n) asm volatile("s_waitcnt lgkmcnt(" #n ")" ::: "memory")
; #define G_BAR __builtin_amdgcn_s_barrier()
; #define G_SCHED __builtin_amdgcn_sched_barrier(0)
; template <int MODE  , class Epi, class Sched>
; __device__ __forceinline__ void gemm_phase(LAS unsigned char* lds, const GemmDesc g, const Sched& S, const Epi& E) {
;     ...
;             G_STAGE(G_SB(0, 1), b2 + hstepB, voffB);
;             G_WAIT_V(6); G_BAR; G_MMA(1, 1, At, B1); G_BAR;
;             G_LDB(B0, 1, 0); G_SCHED; G_LDA(At, 1, 0); G_STAGE(G_SA(0, 1), a2 + hstepA, voffA);
;             G_WAIT_L(8); G_BAR; G_WAIT_L(0); G_MMA(0, 0, At, B0); G_BAR; G_SCHED;
;             G_LDB(B1, 1, 1); G_STAGE(G_SB(1, 0), b3, voffB);
	s_add_u32 s0, s40, 0x84000
	s_addc_u32 s1, s41, 0
	s_add_i32 s10, s51, s31
	v_lshl_add_u64 v[146:147], s[0:1], 0, v[132:133]
	s_mov_b32 m0, s10
	s_nop 0
	global_load_lds_dwordx4 v[146:147], off
	v_lshl_add_u64 v[146:147], s[0:1], 0, v[136:137]
	s_add_i32 m0, s10, 0x2000
	s_nop 0
	global_load_lds_dwordx4 v[146:147], off
	s_waitcnt vmcnt(6)
	s_barrier
	s_setprio 1
	v_mfma_f32_16x16x32_bf16 v[30:33], v[196:199], v[162:165], v[30:33]
	v_mfma_f32_16x16x32_bf16 v[26:29], v[204:207], v[162:165], v[26:29]
	v_mfma_f32_16x16x32_bf16 v[22:25], v[196:199], v[170:173], v[22:25]
	v_mfma_f32_16x16x32_bf16 v[18:21], v[204:207], v[170:173], v[18:21]
	v_mfma_f32_16x16x32_bf16 v[14:17], v[196:199], v[178:181], v[14:17]
	v_mfma_f32_16x16x32_bf16 v[10:13], v[204:207], v[178:181], v[10:13]
	v_mfma_f32_16x16x32_bf16 v[6:9], v[196:199], v[186:189], v[6:9]
	v_mfma_f32_16x16x32_bf16 v[2:5], v[204:207], v[186:189], v[2:5]
	v_mfma_f32_16x16x32_bf16 v[30:33], v[200:203], v[166:169], v[30:33]
	v_mfma_f32_16x16x32_bf16 v[26:29], v[208:211], v[166:169], v[26:29]
	v_mfma_f32_16x16x32_bf16 v[22:25], v[200:203], v[174:177], v[22:25]
	v_mfma_f32_16x16x32_bf16 v[18:21], v[208:211], v[174:177], v[18:21]
	v_mfma_f32_16x16x32_bf16 v[14:17], v[200:203], v[182:185], v[14:17]
	v_mfma_f32_16x16x32_bf16 v[10:13], v[208:211], v[182:185], v[10:13]
	v_mfma_f32_16x16x32_bf16 v[6:9], v[200:203], v[192:195], v[6:9]
	v_mfma_f32_16x16x32_bf16 v[2:5], v[208:211], v[192:195], v[2:5]
	s_setprio 0
	s_add_i32 s10, 0, 0x18000
	v_add_u32_e32 v145, s10, v142
	s_barrier
	ds_read_b128 v[146:149], v145
	ds_read_b128 v[150:153], v145 offset:1024
	ds_read_b128 v[154:157], v145 offset:2048
	ds_read_b128 v[158:161], v145 offset:3072
	s_add_u32 s0, s42, 0x84000
	s_addc_u32 s1, s43, 0
	s_mov_b32 m0, s46
	v_lshl_add_u64 v[196:197], s[0:1], 0, v[130:131]
	ds_read_b128 v[162:165], v144 offset:32768
	ds_read_b128 v[166:169], v144 offset:33792
	ds_read_b128 v[170:173], v144 offset:34816
	ds_read_b128 v[174:177], v144 offset:35840
	ds_read_b128 v[178:181], v144 offset:36864
	ds_read_b128 v[182:185], v144 offset:37888
	ds_read_b128 v[186:189], v144 offset:38912
	ds_read_b128 v[192:195], v144 offset:39936
	global_load_lds_dwordx4 v[196:197], off
	v_lshl_add_u64 v[196:197], s[0:1], 0, v[134:135]
	s_mov_b32 m0, s47
	s_nop 0
	global_load_lds_dwordx4 v[196:197], off
	s_waitcnt lgkmcnt(8)
	s_barrier
	s_waitcnt lgkmcnt(0)
	s_setprio 1
	s_waitcnt lgkmcnt(0)
	v_mfma_f32_16x16x32_bf16 v[126:129], v[146:149], v[162:165], v[126:129]
	v_mfma_f32_16x16x32_bf16 v[122:125], v[154:157], v[162:165], v[122:125]
	v_mfma_f32_16x16x32_bf16 v[118:121], v[146:149], v[170:173], v[118:121]
	v_mfma_f32_16x16x32_bf16 v[114:117], v[154:157], v[170:173], v[114:117]
	v_mfma_f32_16x16x32_bf16 v[110:113], v[146:149], v[178:181], v[110:113]
	v_mfma_f32_16x16x32_bf16 v[106:109], v[154:157], v[178:181], v[106:109]
	v_mfma_f32_16x16x32_bf16 v[102:105], v[146:149], v[186:189], v[102:105]
	v_mfma_f32_16x16x32_bf16 v[98:101], v[154:157], v[186:189], v[98:101]
	v_mfma_f32_16x16x32_bf16 v[126:129], v[150:153], v[166:169], v[126:129]
	v_mfma_f32_16x16x32_bf16 v[122:125], v[158:161], v[166:169], v[122:125]
	v_mfma_f32_16x16x32_bf16 v[118:121], v[150:153], v[174:177], v[118:121]
	v_mfma_f32_16x16x32_bf16 v[114:117], v[158:161], v[174:177], v[114:117]
	v_mfma_f32_16x16x32_bf16 v[110:113], v[150:153], v[182:185], v[110:113]
	v_mfma_f32_16x16x32_bf16 v[106:109], v[158:161], v[182:185], v[106:109]
	v_mfma_f32_16x16x32_bf16 v[102:105], v[150:153], v[192:195], v[102:105]
	v_mfma_f32_16x16x32_bf16 v[98:101], v[158:161], v[192:195], v[98:101]
	s_setprio 0
	s_barrier
	s_add_i32 s11, 0, 0x1c000
	s_add_i32 s0, s10, s31
	v_add_u32_e32 v145, s11, v142
	v_lshl_add_u64 v[212:213], v[212:213], 0, s[4:5]
	s_mov_b32 m0, s0
	ds_read_b128 v[196:199], v145
	ds_read_b128 v[200:203], v145 offset:1024
	ds_read_b128 v[204:207], v145 offset:2048
	ds_read_b128 v[208:211], v145 offset:3072
	global_load_lds_dwordx4 v[212:213], off
	v_lshl_add_u64 v[212:213], v[214:215], 0, s[4:5]
	s_add_i32 m0, s0, 0x2000
	s_nop 0
	global_load_lds_dwordx4 v[212:213], off
	s_barrier
; #define G_STAGE(bufoff, gbase, voff) do { _Pragma("unroll") for (int _i = 0; _i < 2; ++_i) \
;         __builtin_amdgcn_global_load_lds((const unsigned*)((const char*)(gbase) + (voff)[_i]), (LAS unsigned*)(lds + (bufoff) + ldsw + _i * 8192), 16, 0, 0); } while (0)
; #define G_WAIT_V(n) asm volatile("s_waitcnt vmcnt(" #n ")" ::: "memory")
; #define G_WAIT_L(n) asm volatile("s_waitcnt lgkmcnt(" #n ")" ::: "memory")
; #define G_BAR __builtin_amdgcn_s_barrier()
; #define G_SCHED __builtin_amdgcn_sched_barrier(0)
; template <int MODE  , class Epi, class Sched>
; __device__ __forceinline__ void gemm_phase(LAS unsigned char* lds, const GemmDesc g, const Sched& S, const Epi& E) {
;     ...
;             G_LDB(B1, 1, 1); G_STAGE(G_SB(1, 0), b3, voffB);
;             G_BAR; G_WAIT_L(0); G_MMA(0, 1, At, B1); G_BAR;
;             G_LDA(At, 1, 1); G_STAGE(G_SA(1, 0), a3, voffA);
;             G_BAR; G_WAIT_L(0); G_MMA(1, 0, At, B0); G_BAR; G_SCHED;
;             G_STAGE(G_SB(1, 1), b3 + hstepB, voffB);
;             G_WAIT_V(6); G_BAR; G_MMA(1, 1, At, B1); G_BAR;
	s_waitcnt lgkmcnt(0)
	s_setprio 1
	s_waitcnt lgkmcnt(0)
	v_mfma_f32_16x16x32_bf16 v[94:97], v[196:199], v[162:165], v[94:97]
	v_mfma_f32_16x16x32_bf16 v[90:93], v[204:207], v[162:165], v[90:93]
	v_mfma_f32_16x16x32_bf16 v[86:89], v[196:199], v[170:173], v[86:89]
	v_mfma_f32_16x16x32_bf16 v[82:85], v[204:207], v[170:173], v[82:85]
	v_mfma_f32_16x16x32_bf16 v[78:81], v[196:199], v[178:181], v[78:81]
	v_mfma_f32_16x16x32_bf16 v[74:77], v[204:207], v[178:181], v[74:77]
	v_mfma_f32_16x16x32_bf16 v[70:73], v[196:199], v[186:189], v[70:73]
	v_mfma_f32_16x16x32_bf16 v[66:69], v[204:207], v[186:189], v[66:69]
	v_mfma_f32_16x16x32_bf16 v[94:97], v[200:203], v[166:169], v[94:97]
	v_mfma_f32_16x16x32_bf16 v[90:93], v[208:211], v[166:169], v[90:93]
	v_mfma_f32_16x16x32_bf16 v[86:89], v[200:203], v[174:177], v[86:89]
	v_mfma_f32_16x16x32_bf16 v[82:85], v[208:211], v[174:177], v[82:85]
	v_mfma_f32_16x16x32_bf16 v[78:81], v[200:203], v[182:185], v[78:81]
	v_mfma_f32_16x16x32_bf16 v[74:77], v[208:211], v[182:185], v[74:77]
	v_mfma_f32_16x16x32_bf16 v[70:73], v[200:203], v[192:195], v[70:73]
	v_mfma_f32_16x16x32_bf16 v[66:69], v[208:211], v[192:195], v[66:69]
	s_setprio 0
	s_mov_b32 m0, s48
	v_lshl_add_u64 v[212:213], v[216:217], 0, s[4:5]
	s_barrier
	ds_read_b128 v[162:165], v144 offset:49152
	ds_read_b128 v[166:169], v144 offset:50176
	ds_read_b128 v[170:173], v144 offset:51200
	ds_read_b128 v[174:177], v144 offset:52224
	ds_read_b128 v[178:181], v144 offset:53248
	ds_read_b128 v[182:185], v144 offset:54272
	ds_read_b128 v[186:189], v144 offset:55296
	ds_read_b128 v[192:195], v144 offset:56320
	global_load_lds_dwordx4 v[212:213], off
	v_lshl_add_u64 v[212:213], v[218:219], 0, s[4:5]
	s_mov_b32 m0, s49
	s_nop 0
	global_load_lds_dwordx4 v[212:213], off
	s_barrier
	s_waitcnt lgkmcnt(0)
	s_setprio 1
	s_waitcnt lgkmcnt(0)
	v_mfma_f32_16x16x32_bf16 v[62:65], v[146:149], v[162:165], v[62:65]
	v_mfma_f32_16x16x32_bf16 v[58:61], v[154:157], v[162:165], v[58:61]
	v_mfma_f32_16x16x32_bf16 v[54:57], v[146:149], v[170:173], v[54:57]
	v_mfma_f32_16x16x32_bf16 v[50:53], v[154:157], v[170:173], v[50:53]
	v_mfma_f32_16x16x32_bf16 v[46:49], v[146:149], v[178:181], v[46:49]
	v_mfma_f32_16x16x32_bf16 v[42:45], v[154:157], v[178:181], v[42:45]
	v_mfma_f32_16x16x32_bf16 v[38:41], v[146:149], v[186:189], v[38:41]
	v_mfma_f32_16x16x32_bf16 v[34:37], v[154:157], v[186:189], v[34:37]
	v_mfma_f32_16x16x32_bf16 v[62:65], v[150:153], v[166:169], v[62:65]
	v_mfma_f32_16x16x32_bf16 v[58:61], v[158:161], v[166:169], v[58:61]
	v_mfma_f32_16x16x32_bf16 v[54:57], v[150:153], v[174:177], v[54:57]
	v_mfma_f32_16x16x32_bf16 v[50:53], v[158:161], v[174:177], v[50:53]
	v_mfma_f32_16x16x32_bf16 v[46:49], v[150:153], v[182:185], v[46:49]
	v_mfma_f32_16x16x32_bf16 v[42:45], v[158:161], v[182:185], v[42:45]
	v_mfma_f32_16x16x32_bf16 v[38:41], v[150:153], v[192:195], v[38:41]
	v_mfma_f32_16x16x32_bf16 v[34:37], v[158:161], v[192:195], v[34:37]
	s_setprio 0
	s_barrier
	s_add_u32 s0, s40, 0x84080
	s_addc_u32 s1, s41, 0
	s_add_i32 s10, s11, s31
	v_lshl_add_u64 v[146:147], s[0:1], 0, v[132:133]
	s_mov_b32 m0, s10
	s_nop 0
	global_load_lds_dwordx4 v[146:147], off
	v_lshl_add_u64 v[146:147], s[0:1], 0, v[136:137]
	s_add_i32 m0, s10, 0x2000
	s_nop 0
	global_load_lds_dwordx4 v[146:147], off
	s_waitcnt vmcnt(6)
	s_barrier
	s_setprio 1
	v_mfma_f32_16x16x32_bf16 v[30:33], v[196:199], v[162:165], v[30:33]
	s_add_i32 s60, s60, 2
	s_add_u32 s15, s15, 0x100
	s_addc_u32 s59, s59, 0
	s_cmp_gt_u32 s60, 13
	s_mov_b64 s[20:21], s[34:35]
	v_mfma_f32_16x16x32_bf16 v[26:29], v[204:207], v[162:165], v[26:29]
	v_mfma_f32_16x16x32_bf16 v[22:25], v[196:199], v[170:173], v[22:25]
	v_mfma_f32_16x16x32_bf16 v[18:21], v[204:207], v[170:173], v[18:21]
	v_mfma_f32_16x16x32_bf16 v[14:17], v[196:199], v[178:181], v[14:17]
	v_mfma_f32_16x16x32_bf16 v[10:13], v[204:207], v[178:181], v[10:13]
	v_mfma_f32_16x16x32_bf16 v[6:9], v[196:199], v[186:189], v[6:9]
	v_mfma_f32_16x16x32_bf16 v[2:5], v[204:207], v[186:189], v[2:5]
	v_mfma_f32_16x16x32_bf16 v[30:33], v[200:203], v[166:169], v[30:33]
	v_mfma_f32_16x16x32_bf16 v[26:29], v[208:211], v[166:169], v[26:29]
	v_mfma_f32_16x16x32_bf16 v[22:25], v[200:203], v[174:177], v[22:25]
	v_mfma_f32_16x16x32_bf16 v[18:21], v[208:211], v[174:177], v[18:21]
	v_mfma_f32_16x16x32_bf16 v[14:17], v[200:203], v[182:185], v[14:17]
	v_mfma_f32_16x16x32_bf16 v[10:13], v[208:211], v[182:185], v[10:13]
	v_mfma_f32_16x16x32_bf16 v[6:9], v[200:203], v[192:195], v[6:9]
	v_mfma_f32_16x16x32_bf16 v[2:5], v[208:211], v[192:195], v[2:5]
	s_setprio 0
	s_cbranch_scc1 .Lkdone_sc
	s_barrier
	s_branch .LBB0_987

; #define G_STAGE(bufoff, gbase, voff) do { _Pragma("unroll") for (int _i = 0; _i < 2; ++_i) \
;         __builtin_amdgcn_global_load_lds((const unsigned*)((const char*)(gbase) + (voff)[_i]), (LAS unsigned*)(lds + (bufoff) + ldsw + _i * 8192), 16, 0, 0); } while (0)
; #define G_WAIT_L(n) asm volatile("s_waitcnt lgkmcnt(" #n ")" ::: "memory")
; #define G_BAR __builtin_amdgcn_s_barrier()
; #define G_SCHED __builtin_amdgcn_sched_barrier(0)
; template <int MODE  , class Epi, class Sched>
; __device__ __forceinline__ void gemm_phase(LAS unsigned char* lds, const GemmDesc g, const Sched& S, const Epi& E) {
;     ...
;             G_LDB(B0, 0, 0); G_SCHED; G_LDA(At, 0, 0); G_STAGE(G_SA(1, 1), a1 + hstepA, voffA);
;             G_WAIT_L(8); G_BAR; G_WAIT_L(0); G_MMA(0, 0, At, B0); G_BAR; G_SCHED;
;             G_LDB(B1, 0, 1); G_STAGE(G_SB(0, 0), b2, voffB);
;             G_BAR; G_WAIT_L(0); G_MMA(0, 1, At, B1); G_BAR;
;             G_LDA(At, 0, 1); G_STAGE(G_SA(0, 0), a2, voffA);
;             G_BAR; G_WAIT_L(0); G_MMA(1, 0, At, B0); G_BAR; G_SCHED;
.Lnodb_s1a:
.LBB0_1017:
	ds_read_b128 v[130:133], v163
	ds_read_b128 v[134:137], v163 offset:1024
	ds_read_b128 v[154:157], v163 offset:2048
	ds_read_b128 v[170:173], v163 offset:3072
	s_add_u32 s4, s2, 0x100
	s_addc_u32 s5, s3, 0
	s_cmp_eq_u32 s87, 28
	s_cselect_b32 s53, s47, s5
	s_cselect_b32 s52, s46, s4
	s_cselect_b32 s51, s49, s86
	s_cselect_b32 s50, s48, s85
	v_lshl_add_u64 v[158:159], s[2:3], 0, v[150:151]
	s_add_i32 m0, s58, 0xc000
	ds_read_b128 v[174:177], v164
	ds_read_b128 v[178:181], v164 offset:1024
	ds_read_b128 v[182:185], v164 offset:2048
	ds_read_b128 v[186:189], v164 offset:3072
	ds_read_b128 v[192:195], v164 offset:4096
	ds_read_b128 v[196:199], v164 offset:5120
	ds_read_b128 v[200:203], v164 offset:6144
	ds_read_b128 v[204:207], v164 offset:7168
	global_load_lds_dwordx4 v[158:159], off
	v_lshl_add_u64 v[158:159], s[2:3], 0, v[152:153]
	s_add_i32 m0, s58, 0xe000
	s_nop 0
	global_load_lds_dwordx4 v[158:159], off
	s_waitcnt lgkmcnt(8)
	s_barrier
	s_waitcnt lgkmcnt(0)
	s_setprio 1
	s_waitcnt lgkmcnt(0)
	v_mfma_f32_16x16x32_bf16 v[126:129], v[130:133], v[174:177], v[126:129]
	v_mfma_f32_16x16x32_bf16 v[122:125], v[154:157], v[174:177], v[122:125]
	v_mfma_f32_16x16x32_bf16 v[110:113], v[130:133], v[182:185], v[110:113]
	v_mfma_f32_16x16x32_bf16 v[106:109], v[154:157], v[182:185], v[106:109]
	v_mfma_f32_16x16x32_bf16 v[94:97], v[130:133], v[192:195], v[94:97]
	v_mfma_f32_16x16x32_bf16 v[90:93], v[154:157], v[192:195], v[90:93]
	v_mfma_f32_16x16x32_bf16 v[78:81], v[130:133], v[200:203], v[78:81]
	v_mfma_f32_16x16x32_bf16 v[74:77], v[154:157], v[200:203], v[74:77]
	v_mfma_f32_16x16x32_bf16 v[126:129], v[134:137], v[178:181], v[126:129]
	v_mfma_f32_16x16x32_bf16 v[122:125], v[170:173], v[178:181], v[122:125]
	v_mfma_f32_16x16x32_bf16 v[110:113], v[134:137], v[186:189], v[110:113]
	v_mfma_f32_16x16x32_bf16 v[106:109], v[170:173], v[186:189], v[106:109]
	v_mfma_f32_16x16x32_bf16 v[94:97], v[134:137], v[196:199], v[94:97]
	v_mfma_f32_16x16x32_bf16 v[90:93], v[170:173], v[196:199], v[90:93]
	v_mfma_f32_16x16x32_bf16 v[78:81], v[134:137], v[204:207], v[78:81]
	v_mfma_f32_16x16x32_bf16 v[74:77], v[170:173], v[204:207], v[74:77]
	s_setprio 0
	s_barrier
	s_add_i32 s0, s66, s57
	v_lshl_add_u64 v[158:159], s[50:51], 0, v[140:141]
	s_mov_b32 m0, s0
	ds_read_b128 v[208:211], v165
	ds_read_b128 v[212:215], v165 offset:1024
	ds_read_b128 v[216:219], v165 offset:2048
	ds_read_b128 v[220:223], v165 offset:3072
	global_load_lds_dwordx4 v[158:159], off
	v_lshl_add_u64 v[224:225], s[50:51], 0, v[144:145]
	s_add_i32 m0, s0, 0x2000
	s_nop 0
	global_load_lds_dwordx4 v[224:225], off
	s_barrier
	s_waitcnt lgkmcnt(0)
	s_setprio 1
	s_waitcnt lgkmcnt(0)
	v_mfma_f32_16x16x32_bf16 v[118:121], v[208:211], v[174:177], v[118:121]
	v_mfma_f32_16x16x32_bf16 v[114:117], v[216:219], v[174:177], v[114:117]
	v_mfma_f32_16x16x32_bf16 v[102:105], v[208:211], v[182:185], v[102:105]
	v_mfma_f32_16x16x32_bf16 v[98:101], v[216:219], v[182:185], v[98:101]
	v_mfma_f32_16x16x32_bf16 v[86:89], v[208:211], v[192:195], v[86:89]
	v_mfma_f32_16x16x32_bf16 v[82:85], v[216:219], v[192:195], v[82:85]
	v_mfma_f32_16x16x32_bf16 v[70:73], v[208:211], v[200:203], v[70:73]
	v_mfma_f32_16x16x32_bf16 v[66:69], v[216:219], v[200:203], v[66:69]
	v_mfma_f32_16x16x32_bf16 v[118:121], v[212:215], v[178:181], v[118:121]
	v_mfma_f32_16x16x32_bf16 v[114:117], v[220:223], v[178:181], v[114:117]
	v_mfma_f32_16x16x32_bf16 v[102:105], v[212:215], v[186:189], v[102:105]
	v_mfma_f32_16x16x32_bf16 v[98:101], v[220:223], v[186:189], v[98:101]
	v_mfma_f32_16x16x32_bf16 v[86:89], v[212:215], v[196:199], v[86:89]
	v_mfma_f32_16x16x32_bf16 v[82:85], v[220:223], v[196:199], v[82:85]
	v_mfma_f32_16x16x32_bf16 v[70:73], v[212:215], v[204:207], v[70:73]
	v_mfma_f32_16x16x32_bf16 v[66:69], v[220:223], v[204:207], v[66:69]
	s_setprio 0
	s_mov_b32 m0, s58
	v_lshl_add_u64 v[226:227], s[52:53], 0, v[138:139]
	s_barrier
	ds_read_b128 v[174:177], v164 offset:16384
	ds_read_b128 v[178:181], v164 offset:17408
	ds_read_b128 v[182:185], v164 offset:18432
	ds_read_b128 v[186:189], v164 offset:19456
	ds_read_b128 v[192:195], v164 offset:20480
	ds_read_b128 v[196:199], v164 offset:21504
	ds_read_b128 v[200:203], v164 offset:22528
	ds_read_b128 v[204:207], v164 offset:23552
	global_load_lds_dwordx4 v[226:227], off
	v_lshl_add_u64 v[228:229], s[52:53], 0, v[142:143]
	s_mov_b32 m0, s59
	s_nop 0
	global_load_lds_dwordx4 v[228:229], off
	s_barrier
	s_waitcnt lgkmcnt(0)
	s_setprio 1
	s_waitcnt lgkmcnt(0)
	v_mfma_f32_16x16x32_bf16 v[62:65], v[130:133], v[174:177], v[62:65]
	v_mfma_f32_16x16x32_bf16 v[58:61], v[154:157], v[174:177], v[58:61]
	v_mfma_f32_16x16x32_bf16 v[46:49], v[130:133], v[182:185], v[46:49]
	v_mfma_f32_16x16x32_bf16 v[42:45], v[154:157], v[182:185], v[42:45]
	v_mfma_f32_16x16x32_bf16 v[30:33], v[130:133], v[192:195], v[30:33]
	v_mfma_f32_16x16x32_bf16 v[26:29], v[154:157], v[192:195], v[26:29]
	v_mfma_f32_16x16x32_bf16 v[14:17], v[130:133], v[200:203], v[14:17]
	v_mfma_f32_16x16x32_bf16 v[10:13], v[154:157], v[200:203], v[10:13]
	v_mfma_f32_16x16x32_bf16 v[62:65], v[134:137], v[178:181], v[62:65]
	v_mfma_f32_16x16x32_bf16 v[58:61], v[170:173], v[178:181], v[58:61]
	v_mfma_f32_16x16x32_bf16 v[46:49], v[134:137], v[186:189], v[46:49]
	v_mfma_f32_16x16x32_bf16 v[42:45], v[170:173], v[186:189], v[42:45]
	v_mfma_f32_16x16x32_bf16 v[30:33], v[134:137], v[196:199], v[30:33]
	v_mfma_f32_16x16x32_bf16 v[26:29], v[170:173], v[196:199], v[26:29]
	v_mfma_f32_16x16x32_bf16 v[14:17], v[134:137], v[204:207], v[14:17]
	v_mfma_f32_16x16x32_bf16 v[10:13], v[170:173], v[204:207], v[10:13]
	s_setprio 0
	s_barrier
; #define G_STAGE(bufoff, gbase, voff) do { _Pragma("unroll") for (int _i = 0; _i < 2; ++_i) \
;         __builtin_amdgcn_global_load_lds((const unsigned*)((const char*)(gbase) + (voff)[_i]), (LAS unsigned*)(lds + (bufoff) + ldsw + _i * 8192), 16, 0, 0); } while (0)
; #define G_WAIT_V(n) asm volatile("s_waitcnt vmcnt(" #n ")" ::: "memory")
; #define G_WAIT_L(n) asm volatile("s_waitcnt lgkmcnt(" #n ")" ::: "memory")
; #define G_BAR __builtin_amdgcn_s_barrier()
; #define G_SCHED __builtin_amdgcn_sched_barrier(0)
; template <int MODE  , class Epi, class Sched>
; __device__ __forceinline__ void gemm_phase(LAS unsigned char* lds, const GemmDesc g, const Sched& S, const Epi& E) {
;     ...
;             G_STAGE(G_SB(0, 1), b2 + hstepB, voffB);
;             G_WAIT_V(6); G_BAR; G_MMA(1, 1, At, B1); G_BAR;
;             G_LDB(B0, 1, 0); G_SCHED; G_LDA(At, 1, 0); G_STAGE(G_SA(0, 1), a2 + hstepA, voffA);
;             G_WAIT_L(8); G_BAR; G_WAIT_L(0); G_MMA(0, 0, At, B0); G_BAR; G_SCHED;
;             G_LDB(B1, 1, 1); G_STAGE(G_SB(1, 0), b3, voffB);
	s_add_u32 s0, s50, 0x84000
	s_addc_u32 s1, s51, 0
	s_add_i32 s2, s67, s57
	v_lshl_add_u64 v[130:131], s[0:1], 0, v[140:141]
	s_mov_b32 m0, s2
	s_nop 0
	global_load_lds_dwordx4 v[130:131], off
	v_lshl_add_u64 v[130:131], s[0:1], 0, v[144:145]
	s_add_i32 m0, s2, 0x2000
	s_nop 0
	global_load_lds_dwordx4 v[130:131], off
	s_waitcnt vmcnt(6)
	s_barrier
	s_setprio 1
	v_mfma_f32_16x16x32_bf16 v[54:57], v[208:211], v[174:177], v[54:57]
	v_mfma_f32_16x16x32_bf16 v[50:53], v[216:219], v[174:177], v[50:53]
	v_mfma_f32_16x16x32_bf16 v[38:41], v[208:211], v[182:185], v[38:41]
	v_mfma_f32_16x16x32_bf16 v[34:37], v[216:219], v[182:185], v[34:37]
	v_mfma_f32_16x16x32_bf16 v[22:25], v[208:211], v[192:195], v[22:25]
	v_mfma_f32_16x16x32_bf16 v[18:21], v[216:219], v[192:195], v[18:21]
	v_mfma_f32_16x16x32_bf16 v[6:9], v[208:211], v[200:203], v[6:9]
	v_mfma_f32_16x16x32_bf16 v[2:5], v[216:219], v[200:203], v[2:5]
	v_mfma_f32_16x16x32_bf16 v[54:57], v[212:215], v[178:181], v[54:57]
	v_mfma_f32_16x16x32_bf16 v[50:53], v[220:223], v[178:181], v[50:53]
	v_mfma_f32_16x16x32_bf16 v[38:41], v[212:215], v[186:189], v[38:41]
	v_mfma_f32_16x16x32_bf16 v[34:37], v[220:223], v[186:189], v[34:37]
	v_mfma_f32_16x16x32_bf16 v[22:25], v[212:215], v[196:199], v[22:25]
	v_mfma_f32_16x16x32_bf16 v[18:21], v[220:223], v[196:199], v[18:21]
	v_mfma_f32_16x16x32_bf16 v[6:9], v[212:215], v[204:207], v[6:9]
	v_mfma_f32_16x16x32_bf16 v[2:5], v[220:223], v[204:207], v[2:5]
	s_setprio 0
	s_add_i32 s2, 0, 0x18000
	v_add_u32_e32 v146, s2, v160
	s_barrier
	ds_read_b128 v[130:133], v146
	ds_read_b128 v[134:137], v146 offset:1024
	ds_read_b128 v[154:157], v146 offset:2048
	ds_read_b128 v[170:173], v146 offset:3072
	s_add_u32 s0, s52, 0x84000
	s_addc_u32 s1, s53, 0
	s_mov_b32 m0, s60
	v_lshl_add_u64 v[208:209], s[0:1], 0, v[138:139]
	ds_read_b128 v[174:177], v164 offset:32768
	ds_read_b128 v[178:181], v164 offset:33792
	ds_read_b128 v[182:185], v164 offset:34816
	ds_read_b128 v[186:189], v164 offset:35840
	ds_read_b128 v[192:195], v164 offset:36864
	ds_read_b128 v[196:199], v164 offset:37888
	ds_read_b128 v[200:203], v164 offset:38912
	ds_read_b128 v[204:207], v164 offset:39936
	global_load_lds_dwordx4 v[208:209], off
	v_lshl_add_u64 v[208:209], s[0:1], 0, v[142:143]
	s_mov_b32 m0, s61
	s_nop 0
	global_load_lds_dwordx4 v[208:209], off
	s_waitcnt lgkmcnt(8)
	s_barrier
	s_waitcnt lgkmcnt(0)
	s_setprio 1
	s_waitcnt lgkmcnt(0)
	v_mfma_f32_16x16x32_bf16 v[126:129], v[130:133], v[174:177], v[126:129]
	v_mfma_f32_16x16x32_bf16 v[122:125], v[154:157], v[174:177], v[122:125]
	v_mfma_f32_16x16x32_bf16 v[110:113], v[130:133], v[182:185], v[110:113]
	v_mfma_f32_16x16x32_bf16 v[106:109], v[154:157], v[182:185], v[106:109]
	v_mfma_f32_16x16x32_bf16 v[94:97], v[130:133], v[192:195], v[94:97]
	v_mfma_f32_16x16x32_bf16 v[90:93], v[154:157], v[192:195], v[90:93]
	v_mfma_f32_16x16x32_bf16 v[78:81], v[130:133], v[200:203], v[78:81]
	v_mfma_f32_16x16x32_bf16 v[74:77], v[154:157], v[200:203], v[74:77]
	v_mfma_f32_16x16x32_bf16 v[126:129], v[134:137], v[178:181], v[126:129]
	v_mfma_f32_16x16x32_bf16 v[122:125], v[170:173], v[178:181], v[122:125]
	v_mfma_f32_16x16x32_bf16 v[110:113], v[134:137], v[186:189], v[110:113]
	v_mfma_f32_16x16x32_bf16 v[106:109], v[170:173], v[186:189], v[106:109]
	v_mfma_f32_16x16x32_bf16 v[94:97], v[134:137], v[196:199], v[94:97]
	v_mfma_f32_16x16x32_bf16 v[90:93], v[170:173], v[196:199], v[90:93]
	v_mfma_f32_16x16x32_bf16 v[78:81], v[134:137], v[204:207], v[78:81]
	v_mfma_f32_16x16x32_bf16 v[74:77], v[170:173], v[204:207], v[74:77]
	s_setprio 0
	s_barrier
	s_add_i32 s3, 0, 0x1c000
	s_add_i32 s0, s2, s57
	v_add_u32_e32 v146, s3, v160
	v_lshl_add_u64 v[158:159], v[158:159], 0, s[14:15]
	s_mov_b32 m0, s0
	ds_read_b128 v[208:211], v146
	ds_read_b128 v[212:215], v146 offset:1024
	ds_read_b128 v[216:219], v146 offset:2048
	ds_read_b128 v[220:223], v146 offset:3072
	global_load_lds_dwordx4 v[158:159], off
	v_lshl_add_u64 v[158:159], v[224:225], 0, s[14:15]
	s_add_i32 m0, s0, 0x2000
	s_nop 0
	global_load_lds_dwordx4 v[158:159], off
	s_barrier
; #define G_STAGE(bufoff, gbase, voff) do { _Pragma("unroll") for (int _i = 0; _i < 2; ++_i) \
;         __builtin_amdgcn_global_load_lds((const unsigned*)((const char*)(gbase) + (voff)[_i]), (LAS unsigned*)(lds + (bufoff) + ldsw + _i * 8192), 16, 0, 0); } while (0)
; #define G_WAIT_V(n) asm volatile("s_waitcnt vmcnt(" #n ")" ::: "memory")
; #define G_WAIT_L(n) asm volatile("s_waitcnt lgkmcnt(" #n ")" ::: "memory")
; #define G_BAR __builtin_amdgcn_s_barrier()
; #define G_SCHED __builtin_amdgcn_sched_barrier(0)
; template <int MODE  , class Epi, class Sched>
; __device__ __forceinline__ void gemm_phase(LAS unsigned char* lds, const GemmDesc g, const Sched& S, const Epi& E) {
;     ...
;             G_LDB(B1, 1, 1); G_STAGE(G_SB(1, 0), b3, voffB);
;             G_BAR; G_WAIT_L(0); G_MMA(0, 1, At, B1); G_BAR;
;             G_LDA(At, 1, 1); G_STAGE(G_SA(1, 0), a3, voffA);
;             G_BAR; G_WAIT_L(0); G_MMA(1, 0, At, B0); G_BAR; G_SCHED;
;             G_STAGE(G_SB(1, 1), b3 + hstepB, voffB);
;             G_WAIT_V(6); G_BAR; G_MMA(1, 1, At, B1); G_BAR;
	s_waitcnt lgkmcnt(0)
	s_setprio 1
	s_waitcnt lgkmcnt(0)
	v_mfma_f32_16x16x32_bf16 v[118:121], v[208:211], v[174:177], v[118:121]
	v_mfma_f32_16x16x32_bf16 v[114:117], v[216:219], v[174:177], v[114:117]
	v_mfma_f32_16x16x32_bf16 v[102:105], v[208:211], v[182:185], v[102:105]
	v_mfma_f32_16x16x32_bf16 v[98:101], v[216:219], v[182:185], v[98:101]
	v_mfma_f32_16x16x32_bf16 v[86:89], v[208:211], v[192:195], v[86:89]
	v_mfma_f32_16x16x32_bf16 v[82:85], v[216:219], v[192:195], v[82:85]
	v_mfma_f32_16x16x32_bf16 v[70:73], v[208:211], v[200:203], v[70:73]
	v_mfma_f32_16x16x32_bf16 v[66:69], v[216:219], v[200:203], v[66:69]
	v_mfma_f32_16x16x32_bf16 v[118:121], v[212:215], v[178:181], v[118:121]
	v_mfma_f32_16x16x32_bf16 v[114:117], v[220:223], v[178:181], v[114:117]
	v_mfma_f32_16x16x32_bf16 v[102:105], v[212:215], v[186:189], v[102:105]
	v_mfma_f32_16x16x32_bf16 v[98:101], v[220:223], v[186:189], v[98:101]
	v_mfma_f32_16x16x32_bf16 v[86:89], v[212:215], v[196:199], v[86:89]
	v_mfma_f32_16x16x32_bf16 v[82:85], v[220:223], v[196:199], v[82:85]
	v_mfma_f32_16x16x32_bf16 v[70:73], v[212:215], v[204:207], v[70:73]
	v_mfma_f32_16x16x32_bf16 v[66:69], v[220:223], v[204:207], v[66:69]
	s_setprio 0
	s_mov_b32 m0, s64
	v_lshl_add_u64 v[158:159], v[226:227], 0, s[14:15]
	s_barrier
	ds_read_b128 v[174:177], v164 offset:49152
	ds_read_b128 v[178:181], v164 offset:50176
	ds_read_b128 v[182:185], v164 offset:51200
	ds_read_b128 v[186:189], v164 offset:52224
	ds_read_b128 v[192:195], v164 offset:53248
	ds_read_b128 v[196:199], v164 offset:54272
	ds_read_b128 v[200:203], v164 offset:55296
	ds_read_b128 v[204:207], v164 offset:56320
	global_load_lds_dwordx4 v[158:159], off
	v_lshl_add_u64 v[158:159], v[228:229], 0, s[14:15]
	s_mov_b32 m0, s65
	s_nop 0
	global_load_lds_dwordx4 v[158:159], off
	s_barrier
	s_waitcnt lgkmcnt(0)
	s_setprio 1
	s_waitcnt lgkmcnt(0)
	v_mfma_f32_16x16x32_bf16 v[62:65], v[130:133], v[174:177], v[62:65]
	v_mfma_f32_16x16x32_bf16 v[58:61], v[154:157], v[174:177], v[58:61]
	v_mfma_f32_16x16x32_bf16 v[46:49], v[130:133], v[182:185], v[46:49]
	v_mfma_f32_16x16x32_bf16 v[42:45], v[154:157], v[182:185], v[42:45]
	v_mfma_f32_16x16x32_bf16 v[30:33], v[130:133], v[192:195], v[30:33]
	v_mfma_f32_16x16x32_bf16 v[26:29], v[154:157], v[192:195], v[26:29]
	v_mfma_f32_16x16x32_bf16 v[14:17], v[130:133], v[200:203], v[14:17]
	v_mfma_f32_16x16x32_bf16 v[10:13], v[154:157], v[200:203], v[10:13]
	v_mfma_f32_16x16x32_bf16 v[62:65], v[134:137], v[178:181], v[62:65]
	v_mfma_f32_16x16x32_bf16 v[58:61], v[170:173], v[178:181], v[58:61]
	v_mfma_f32_16x16x32_bf16 v[46:49], v[134:137], v[186:189], v[46:49]
	v_mfma_f32_16x16x32_bf16 v[42:45], v[170:173], v[186:189], v[42:45]
	v_mfma_f32_16x16x32_bf16 v[30:33], v[134:137], v[196:199], v[30:33]
	v_mfma_f32_16x16x32_bf16 v[26:29], v[170:173], v[196:199], v[26:29]
	v_mfma_f32_16x16x32_bf16 v[14:17], v[134:137], v[204:207], v[14:17]
	v_mfma_f32_16x16x32_bf16 v[10:13], v[170:173], v[204:207], v[10:13]
	s_setprio 0
	s_barrier
	s_add_u32 s0, s50, 0x84080
	s_addc_u32 s1, s51, 0
	s_add_i32 s2, s3, s57
	v_lshl_add_u64 v[130:131], s[0:1], 0, v[140:141]
	s_mov_b32 m0, s2
	s_nop 0
	global_load_lds_dwordx4 v[130:131], off
	v_lshl_add_u64 v[130:131], s[0:1], 0, v[144:145]
	s_add_i32 m0, s2, 0x2000
	s_nop 0
	global_load_lds_dwordx4 v[130:131], off
	s_waitcnt vmcnt(6)
	s_barrier
	s_setprio 1
	v_mfma_f32_16x16x32_bf16 v[54:57], v[208:211], v[174:177], v[54:57]
	s_add_i32 s87, s87, 2
	s_add_u32 s85, s85, 0x100
	s_addc_u32 s86, s86, 0
	s_cmp_gt_u32 s87, 29
	s_mov_b64 s[2:3], s[4:5]
	v_mfma_f32_16x16x32_bf16 v[50:53], v[216:219], v[174:177], v[50:53]
	v_mfma_f32_16x16x32_bf16 v[38:41], v[208:211], v[182:185], v[38:41]
	v_mfma_f32_16x16x32_bf16 v[34:37], v[216:219], v[182:185], v[34:37]
	v_mfma_f32_16x16x32_bf16 v[22:25], v[208:211], v[192:195], v[22:25]
	v_mfma_f32_16x16x32_bf16 v[18:21], v[216:219], v[192:195], v[18:21]
	v_mfma_f32_16x16x32_bf16 v[6:9], v[208:211], v[200:203], v[6:9]
	v_mfma_f32_16x16x32_bf16 v[2:5], v[216:219], v[200:203], v[2:5]
	v_mfma_f32_16x16x32_bf16 v[54:57], v[212:215], v[178:181], v[54:57]
	v_mfma_f32_16x16x32_bf16 v[50:53], v[220:223], v[178:181], v[50:53]
	v_mfma_f32_16x16x32_bf16 v[38:41], v[212:215], v[186:189], v[38:41]
	v_mfma_f32_16x16x32_bf16 v[34:37], v[220:223], v[186:189], v[34:37]
	v_mfma_f32_16x16x32_bf16 v[22:25], v[212:215], v[196:199], v[22:25]
	v_mfma_f32_16x16x32_bf16 v[18:21], v[220:223], v[196:199], v[18:21]
	v_mfma_f32_16x16x32_bf16 v[6:9], v[212:215], v[204:207], v[6:9]
	v_mfma_f32_16x16x32_bf16 v[2:5], v[220:223], v[204:207], v[2:5]
	s_setprio 0
	s_cbranch_scc1 .Lkdone_s1a
	s_barrier
	s_branch .LBB0_1017
